# refine bitwise search exits as soon as exactly need candidates lie above the trial value; classify pass 1 unrolled with one-chunk-ahead LDS reads and add-with-carry mask building
# speedup vs baseline: 1.0745x; 1.0065x over previous
.LBB0_729:
	s_ashr_i32 s90, s60, 7
	s_lshl_b32 s6, s90, 5
	s_add_i32 s61, s6, 0
	s_add_i32 s91, s61, 0x25800
	v_mov_b32_e32 v1, s91
	s_waitcnt lgkmcnt(0)
	s_barrier
	ds_read_b32 v8, v1
	s_lshl_b32 s57, s13, 3
	s_add_i32 s57, s57, 8
	v_and_or_b32 v3, s60, 64, v145
	s_lshl_b32 s89, s90, 15
	v_cmp_gt_i32_e64 s[12:13], s57, v3
	v_mov_b32_e32 v4, 0
	s_waitcnt lgkmcnt(0)
	v_lshlrev_b32_e32 v176, 21, v8
	v_or_b32_e32 v177, 0x1fffff, v176
	v_mov_b32_e32 v178, 0
	v_mov_b32_e32 v179, 0
	v_mov_b32_e32 v180, 0
	v_mov_b32_e32 v181, 0
	v_mov_b32_e32 v182, 0
	v_mov_b32_e32 v183, 0
	s_and_saveexec_b64 s[6:7], s[12:13]
	s_cbranch_execz .LBB0_733
	s_lshl_b32 s10, s60, 4
	s_and_b32 s10, s10, 0x400
	s_add_i32 s10, s89, s10
	s_add_i32 s10, s10, 0
	v_lshl_add_u32 v1, v145, 4, s10
	v_mov_b32_e32 v5, v3
	s_mov_b64 s[10:11], exec
	ds_read_b128 v[10:13], v1
	ds_read_b128 v[216:219], v1 offset:2048
	s_waitcnt lgkmcnt(1)
	v_cmp_ge_u32_e64 s[16:17], v10, v176
	v_cmp_ge_u32_e64 s[18:19], v11, v176
	v_cmp_ge_u32_e64 s[22:23], v12, v176
	v_cmp_ge_u32_e64 s[24:25], v13, v176
	v_addc_co_u32_e64 v178, s[16:17], v178, v178, s[16:17]
	v_addc_co_u32_e64 v178, s[18:19], v178, v178, s[18:19]
	v_addc_co_u32_e64 v178, s[22:23], v178, v178, s[22:23]
	v_addc_co_u32_e64 v178, s[24:25], v178, v178, s[24:25]
	v_cmp_gt_u32_e64 s[16:17], v10, v177
	v_cmp_gt_u32_e64 s[18:19], v11, v177
	v_cmp_gt_u32_e64 s[22:23], v12, v177
	v_cmp_gt_u32_e64 s[24:25], v13, v177
	v_addc_co_u32_e64 v180, s[16:17], v180, v180, s[16:17]
	v_addc_co_u32_e64 v180, s[18:19], v180, v180, s[18:19]
	v_addc_co_u32_e64 v180, s[22:23], v180, v180, s[22:23]
	v_addc_co_u32_e64 v180, s[24:25], v180, v180, s[24:25]
	v_add_u32_e32 v5, 0x80, v5
	v_cmp_gt_i32_e32 vcc, s57, v5
	s_and_b64 exec, exec, vcc
	s_cbranch_execz .Lcls_p1_done
	ds_read_b128 v[10:13], v1 offset:4096
	s_waitcnt lgkmcnt(1)
	v_cmp_ge_u32_e64 s[16:17], v216, v176
	v_cmp_ge_u32_e64 s[18:19], v217, v176
	v_cmp_ge_u32_e64 s[22:23], v218, v176
	v_cmp_ge_u32_e64 s[24:25], v219, v176
	v_addc_co_u32_e64 v178, s[16:17], v178, v178, s[16:17]
	v_addc_co_u32_e64 v178, s[18:19], v178, v178, s[18:19]
	v_addc_co_u32_e64 v178, s[22:23], v178, v178, s[22:23]
	v_addc_co_u32_e64 v178, s[24:25], v178, v178, s[24:25]
	v_cmp_gt_u32_e64 s[16:17], v216, v177
	v_cmp_gt_u32_e64 s[18:19], v217, v177
	v_cmp_gt_u32_e64 s[22:23], v218, v177
	v_cmp_gt_u32_e64 s[24:25], v219, v177
	v_addc_co_u32_e64 v180, s[16:17], v180, v180, s[16:17]
	v_addc_co_u32_e64 v180, s[18:19], v180, v180, s[18:19]
	v_addc_co_u32_e64 v180, s[22:23], v180, v180, s[22:23]
	v_addc_co_u32_e64 v180, s[24:25], v180, v180, s[24:25]
	v_add_u32_e32 v5, 0x80, v5
	v_cmp_gt_i32_e32 vcc, s57, v5
	s_and_b64 exec, exec, vcc
	s_cbranch_execz .Lcls_p1_done
	ds_read_b128 v[216:219], v1 offset:6144
	s_waitcnt lgkmcnt(1)
	v_cmp_ge_u32_e64 s[16:17], v10, v176
	v_cmp_ge_u32_e64 s[18:19], v11, v176
	v_cmp_ge_u32_e64 s[22:23], v12, v176
	v_cmp_ge_u32_e64 s[24:25], v13, v176
	v_addc_co_u32_e64 v178, s[16:17], v178, v178, s[16:17]
	v_addc_co_u32_e64 v178, s[18:19], v178, v178, s[18:19]
	v_addc_co_u32_e64 v178, s[22:23], v178, v178, s[22:23]
	v_addc_co_u32_e64 v178, s[24:25], v178, v178, s[24:25]
	v_cmp_gt_u32_e64 s[16:17], v10, v177
	v_cmp_gt_u32_e64 s[18:19], v11, v177
	v_cmp_gt_u32_e64 s[22:23], v12, v177
	v_cmp_gt_u32_e64 s[24:25], v13, v177
	v_addc_co_u32_e64 v180, s[16:17], v180, v180, s[16:17]
	v_addc_co_u32_e64 v180, s[18:19], v180, v180, s[18:19]
	v_addc_co_u32_e64 v180, s[22:23], v180, v180, s[22:23]
	v_addc_co_u32_e64 v180, s[24:25], v180, v180, s[24:25]
	v_add_u32_e32 v5, 0x80, v5
	v_cmp_gt_i32_e32 vcc, s57, v5
	s_and_b64 exec, exec, vcc
	s_cbranch_execz .Lcls_p1_done
	ds_read_b128 v[10:13], v1 offset:8192
	s_waitcnt lgkmcnt(1)
	v_cmp_ge_u32_e64 s[16:17], v216, v176
	v_cmp_ge_u32_e64 s[18:19], v217, v176
	v_cmp_ge_u32_e64 s[22:23], v218, v176
	v_cmp_ge_u32_e64 s[24:25], v219, v176
	v_addc_co_u32_e64 v178, s[16:17], v178, v178, s[16:17]
	v_addc_co_u32_e64 v178, s[18:19], v178, v178, s[18:19]
	v_addc_co_u32_e64 v178, s[22:23], v178, v178, s[22:23]
	v_addc_co_u32_e64 v178, s[24:25], v178, v178, s[24:25]
	v_cmp_gt_u32_e64 s[16:17], v216, v177
	v_cmp_gt_u32_e64 s[18:19], v217, v177
	v_cmp_gt_u32_e64 s[22:23], v218, v177
	v_cmp_gt_u32_e64 s[24:25], v219, v177
	v_addc_co_u32_e64 v180, s[16:17], v180, v180, s[16:17]
	v_addc_co_u32_e64 v180, s[18:19], v180, v180, s[18:19]
	v_addc_co_u32_e64 v180, s[22:23], v180, v180, s[22:23]
	v_addc_co_u32_e64 v180, s[24:25], v180, v180, s[24:25]
	v_add_u32_e32 v5, 0x80, v5
	v_cmp_gt_i32_e32 vcc, s57, v5
	s_and_b64 exec, exec, vcc
	s_cbranch_execz .Lcls_p1_done
	ds_read_b128 v[216:219], v1 offset:10240
	s_waitcnt lgkmcnt(1)
	v_cmp_ge_u32_e64 s[16:17], v10, v176
	v_cmp_ge_u32_e64 s[18:19], v11, v176
	v_cmp_ge_u32_e64 s[22:23], v12, v176
	v_cmp_ge_u32_e64 s[24:25], v13, v176
	v_addc_co_u32_e64 v178, s[16:17], v178, v178, s[16:17]
	v_addc_co_u32_e64 v178, s[18:19], v178, v178, s[18:19]
	v_addc_co_u32_e64 v178, s[22:23], v178, v178, s[22:23]
	v_addc_co_u32_e64 v178, s[24:25], v178, v178, s[24:25]
	v_cmp_gt_u32_e64 s[16:17], v10, v177
	v_cmp_gt_u32_e64 s[18:19], v11, v177
	v_cmp_gt_u32_e64 s[22:23], v12, v177
	v_cmp_gt_u32_e64 s[24:25], v13, v177
	v_addc_co_u32_e64 v180, s[16:17], v180, v180, s[16:17]
	v_addc_co_u32_e64 v180, s[18:19], v180, v180, s[18:19]
	v_addc_co_u32_e64 v180, s[22:23], v180, v180, s[22:23]
	v_addc_co_u32_e64 v180, s[24:25], v180, v180, s[24:25]
	v_add_u32_e32 v5, 0x80, v5
	v_cmp_gt_i32_e32 vcc, s57, v5
	s_and_b64 exec, exec, vcc
	s_cbranch_execz .Lcls_p1_done
	ds_read_b128 v[10:13], v1 offset:12288
	s_waitcnt lgkmcnt(1)
	v_cmp_ge_u32_e64 s[16:17], v216, v176
	v_cmp_ge_u32_e64 s[18:19], v217, v176
	v_cmp_ge_u32_e64 s[22:23], v218, v176
	v_cmp_ge_u32_e64 s[24:25], v219, v176
	v_addc_co_u32_e64 v178, s[16:17], v178, v178, s[16:17]
	v_addc_co_u32_e64 v178, s[18:19], v178, v178, s[18:19]
	v_addc_co_u32_e64 v178, s[22:23], v178, v178, s[22:23]
	v_addc_co_u32_e64 v178, s[24:25], v178, v178, s[24:25]
	v_cmp_gt_u32_e64 s[16:17], v216, v177
	v_cmp_gt_u32_e64 s[18:19], v217, v177
	v_cmp_gt_u32_e64 s[22:23], v218, v177
	v_cmp_gt_u32_e64 s[24:25], v219, v177
	v_addc_co_u32_e64 v180, s[16:17], v180, v180, s[16:17]
	v_addc_co_u32_e64 v180, s[18:19], v180, v180, s[18:19]
	v_addc_co_u32_e64 v180, s[22:23], v180, v180, s[22:23]
	v_addc_co_u32_e64 v180, s[24:25], v180, v180, s[24:25]
	v_add_u32_e32 v5, 0x80, v5
	v_cmp_gt_i32_e32 vcc, s57, v5
	s_and_b64 exec, exec, vcc
	s_cbranch_execz .Lcls_p1_done
	ds_read_b128 v[216:219], v1 offset:14336
	s_waitcnt lgkmcnt(1)
	v_cmp_ge_u32_e64 s[16:17], v10, v176
	v_cmp_ge_u32_e64 s[18:19], v11, v176
	v_cmp_ge_u32_e64 s[22:23], v12, v176
	v_cmp_ge_u32_e64 s[24:25], v13, v176
	v_addc_co_u32_e64 v178, s[16:17], v178, v178, s[16:17]
	v_addc_co_u32_e64 v178, s[18:19], v178, v178, s[18:19]
	v_addc_co_u32_e64 v178, s[22:23], v178, v178, s[22:23]
	v_addc_co_u32_e64 v178, s[24:25], v178, v178, s[24:25]
	v_cmp_gt_u32_e64 s[16:17], v10, v177
	v_cmp_gt_u32_e64 s[18:19], v11, v177
	v_cmp_gt_u32_e64 s[22:23], v12, v177
	v_cmp_gt_u32_e64 s[24:25], v13, v177
	v_addc_co_u32_e64 v180, s[16:17], v180, v180, s[16:17]
	v_addc_co_u32_e64 v180, s[18:19], v180, v180, s[18:19]
	v_addc_co_u32_e64 v180, s[22:23], v180, v180, s[22:23]
	v_addc_co_u32_e64 v180, s[24:25], v180, v180, s[24:25]
	v_add_u32_e32 v5, 0x80, v5
	v_cmp_gt_i32_e32 vcc, s57, v5
	s_and_b64 exec, exec, vcc
	s_cbranch_execz .Lcls_p1_done
	ds_read_b128 v[10:13], v1 offset:16384
	s_waitcnt lgkmcnt(1)
	v_cmp_ge_u32_e64 s[16:17], v216, v176
	v_cmp_ge_u32_e64 s[18:19], v217, v176
	v_cmp_ge_u32_e64 s[22:23], v218, v176
	v_cmp_ge_u32_e64 s[24:25], v219, v176
	v_addc_co_u32_e64 v178, s[16:17], v178, v178, s[16:17]
	v_addc_co_u32_e64 v178, s[18:19], v178, v178, s[18:19]
	v_addc_co_u32_e64 v178, s[22:23], v178, v178, s[22:23]
	v_addc_co_u32_e64 v178, s[24:25], v178, v178, s[24:25]
	v_cmp_gt_u32_e64 s[16:17], v216, v177
	v_cmp_gt_u32_e64 s[18:19], v217, v177
	v_cmp_gt_u32_e64 s[22:23], v218, v177
	v_cmp_gt_u32_e64 s[24:25], v219, v177
	v_addc_co_u32_e64 v180, s[16:17], v180, v180, s[16:17]
	v_addc_co_u32_e64 v180, s[18:19], v180, v180, s[18:19]
	v_addc_co_u32_e64 v180, s[22:23], v180, v180, s[22:23]
	v_addc_co_u32_e64 v180, s[24:25], v180, v180, s[24:25]
	v_add_u32_e32 v5, 0x80, v5
	v_cmp_gt_i32_e32 vcc, s57, v5
	s_and_b64 exec, exec, vcc
	s_cbranch_execz .Lcls_p1_done
	ds_read_b128 v[216:219], v1 offset:18432
	s_waitcnt lgkmcnt(1)
	v_cmp_ge_u32_e64 s[16:17], v10, v176
	v_cmp_ge_u32_e64 s[18:19], v11, v176
	v_cmp_ge_u32_e64 s[22:23], v12, v176
	v_cmp_ge_u32_e64 s[24:25], v13, v176
	v_addc_co_u32_e64 v179, s[16:17], v179, v179, s[16:17]
	v_addc_co_u32_e64 v179, s[18:19], v179, v179, s[18:19]
	v_addc_co_u32_e64 v179, s[22:23], v179, v179, s[22:23]
	v_addc_co_u32_e64 v179, s[24:25], v179, v179, s[24:25]
	v_cmp_gt_u32_e64 s[16:17], v10, v177
	v_cmp_gt_u32_e64 s[18:19], v11, v177
	v_cmp_gt_u32_e64 s[22:23], v12, v177
	v_cmp_gt_u32_e64 s[24:25], v13, v177
	v_addc_co_u32_e64 v181, s[16:17], v181, v181, s[16:17]
	v_addc_co_u32_e64 v181, s[18:19], v181, v181, s[18:19]
	v_addc_co_u32_e64 v181, s[22:23], v181, v181, s[22:23]
	v_addc_co_u32_e64 v181, s[24:25], v181, v181, s[24:25]
	v_add_u32_e32 v5, 0x80, v5
	v_cmp_gt_i32_e32 vcc, s57, v5
	s_and_b64 exec, exec, vcc
	s_cbranch_execz .Lcls_p1_done
	ds_read_b128 v[10:13], v1 offset:20480
	s_waitcnt lgkmcnt(1)
	v_cmp_ge_u32_e64 s[16:17], v216, v176
	v_cmp_ge_u32_e64 s[18:19], v217, v176
	v_cmp_ge_u32_e64 s[22:23], v218, v176
	v_cmp_ge_u32_e64 s[24:25], v219, v176
	v_addc_co_u32_e64 v179, s[16:17], v179, v179, s[16:17]
	v_addc_co_u32_e64 v179, s[18:19], v179, v179, s[18:19]
	v_addc_co_u32_e64 v179, s[22:23], v179, v179, s[22:23]
	v_addc_co_u32_e64 v179, s[24:25], v179, v179, s[24:25]
	v_cmp_gt_u32_e64 s[16:17], v216, v177
	v_cmp_gt_u32_e64 s[18:19], v217, v177
	v_cmp_gt_u32_e64 s[22:23], v218, v177
	v_cmp_gt_u32_e64 s[24:25], v219, v177
	v_addc_co_u32_e64 v181, s[16:17], v181, v181, s[16:17]
	v_addc_co_u32_e64 v181, s[18:19], v181, v181, s[18:19]
	v_addc_co_u32_e64 v181, s[22:23], v181, v181, s[22:23]
	v_addc_co_u32_e64 v181, s[24:25], v181, v181, s[24:25]
	v_add_u32_e32 v5, 0x80, v5
	v_cmp_gt_i32_e32 vcc, s57, v5
	s_and_b64 exec, exec, vcc
	s_cbranch_execz .Lcls_p1_done
	ds_read_b128 v[216:219], v1 offset:22528
	s_waitcnt lgkmcnt(1)
	v_cmp_ge_u32_e64 s[16:17], v10, v176
	v_cmp_ge_u32_e64 s[18:19], v11, v176
	v_cmp_ge_u32_e64 s[22:23], v12, v176
	v_cmp_ge_u32_e64 s[24:25], v13, v176
	v_addc_co_u32_e64 v179, s[16:17], v179, v179, s[16:17]
	v_addc_co_u32_e64 v179, s[18:19], v179, v179, s[18:19]
	v_addc_co_u32_e64 v179, s[22:23], v179, v179, s[22:23]
	v_addc_co_u32_e64 v179, s[24:25], v179, v179, s[24:25]
	v_cmp_gt_u32_e64 s[16:17], v10, v177
	v_cmp_gt_u32_e64 s[18:19], v11, v177
	v_cmp_gt_u32_e64 s[22:23], v12, v177
	v_cmp_gt_u32_e64 s[24:25], v13, v177
	v_addc_co_u32_e64 v181, s[16:17], v181, v181, s[16:17]
	v_addc_co_u32_e64 v181, s[18:19], v181, v181, s[18:19]
	v_addc_co_u32_e64 v181, s[22:23], v181, v181, s[22:23]
	v_addc_co_u32_e64 v181, s[24:25], v181, v181, s[24:25]
	v_add_u32_e32 v5, 0x80, v5
	v_cmp_gt_i32_e32 vcc, s57, v5
	s_and_b64 exec, exec, vcc
	s_cbranch_execz .Lcls_p1_done
	ds_read_b128 v[10:13], v1 offset:24576
	s_waitcnt lgkmcnt(1)
	v_cmp_ge_u32_e64 s[16:17], v216, v176
	v_cmp_ge_u32_e64 s[18:19], v217, v176
	v_cmp_ge_u32_e64 s[22:23], v218, v176
	v_cmp_ge_u32_e64 s[24:25], v219, v176
	v_addc_co_u32_e64 v179, s[16:17], v179, v179, s[16:17]
	v_addc_co_u32_e64 v179, s[18:19], v179, v179, s[18:19]
	v_addc_co_u32_e64 v179, s[22:23], v179, v179, s[22:23]
	v_addc_co_u32_e64 v179, s[24:25], v179, v179, s[24:25]
	v_cmp_gt_u32_e64 s[16:17], v216, v177
	v_cmp_gt_u32_e64 s[18:19], v217, v177
	v_cmp_gt_u32_e64 s[22:23], v218, v177
	v_cmp_gt_u32_e64 s[24:25], v219, v177
	v_addc_co_u32_e64 v181, s[16:17], v181, v181, s[16:17]
	v_addc_co_u32_e64 v181, s[18:19], v181, v181, s[18:19]
	v_addc_co_u32_e64 v181, s[22:23], v181, v181, s[22:23]
	v_addc_co_u32_e64 v181, s[24:25], v181, v181, s[24:25]
	v_add_u32_e32 v5, 0x80, v5
	v_cmp_gt_i32_e32 vcc, s57, v5
	s_and_b64 exec, exec, vcc
	s_cbranch_execz .Lcls_p1_done
	ds_read_b128 v[216:219], v1 offset:26624
	s_waitcnt lgkmcnt(1)
	v_cmp_ge_u32_e64 s[16:17], v10, v176
	v_cmp_ge_u32_e64 s[18:19], v11, v176
	v_cmp_ge_u32_e64 s[22:23], v12, v176
	v_cmp_ge_u32_e64 s[24:25], v13, v176
	v_addc_co_u32_e64 v179, s[16:17], v179, v179, s[16:17]
	v_addc_co_u32_e64 v179, s[18:19], v179, v179, s[18:19]
	v_addc_co_u32_e64 v179, s[22:23], v179, v179, s[22:23]
	v_addc_co_u32_e64 v179, s[24:25], v179, v179, s[24:25]
	v_cmp_gt_u32_e64 s[16:17], v10, v177
	v_cmp_gt_u32_e64 s[18:19], v11, v177
	v_cmp_gt_u32_e64 s[22:23], v12, v177
	v_cmp_gt_u32_e64 s[24:25], v13, v177
	v_addc_co_u32_e64 v181, s[16:17], v181, v181, s[16:17]
	v_addc_co_u32_e64 v181, s[18:19], v181, v181, s[18:19]
	v_addc_co_u32_e64 v181, s[22:23], v181, v181, s[22:23]
	v_addc_co_u32_e64 v181, s[24:25], v181, v181, s[24:25]
	v_add_u32_e32 v5, 0x80, v5
	v_cmp_gt_i32_e32 vcc, s57, v5
	s_and_b64 exec, exec, vcc
	s_cbranch_execz .Lcls_p1_done
	ds_read_b128 v[10:13], v1 offset:28672
	s_waitcnt lgkmcnt(1)
	v_cmp_ge_u32_e64 s[16:17], v216, v176
	v_cmp_ge_u32_e64 s[18:19], v217, v176
	v_cmp_ge_u32_e64 s[22:23], v218, v176
	v_cmp_ge_u32_e64 s[24:25], v219, v176
	v_addc_co_u32_e64 v179, s[16:17], v179, v179, s[16:17]
	v_addc_co_u32_e64 v179, s[18:19], v179, v179, s[18:19]
	v_addc_co_u32_e64 v179, s[22:23], v179, v179, s[22:23]
	v_addc_co_u32_e64 v179, s[24:25], v179, v179, s[24:25]
	v_cmp_gt_u32_e64 s[16:17], v216, v177
	v_cmp_gt_u32_e64 s[18:19], v217, v177
	v_cmp_gt_u32_e64 s[22:23], v218, v177
	v_cmp_gt_u32_e64 s[24:25], v219, v177
	v_addc_co_u32_e64 v181, s[16:17], v181, v181, s[16:17]
	v_addc_co_u32_e64 v181, s[18:19], v181, v181, s[18:19]
	v_addc_co_u32_e64 v181, s[22:23], v181, v181, s[22:23]
	v_addc_co_u32_e64 v181, s[24:25], v181, v181, s[24:25]
	v_add_u32_e32 v5, 0x80, v5
	v_cmp_gt_i32_e32 vcc, s57, v5
	s_and_b64 exec, exec, vcc
	s_cbranch_execz .Lcls_p1_done
	ds_read_b128 v[216:219], v1 offset:30720
	s_waitcnt lgkmcnt(1)
	v_cmp_ge_u32_e64 s[16:17], v10, v176
	v_cmp_ge_u32_e64 s[18:19], v11, v176
	v_cmp_ge_u32_e64 s[22:23], v12, v176
	v_cmp_ge_u32_e64 s[24:25], v13, v176
	v_addc_co_u32_e64 v179, s[16:17], v179, v179, s[16:17]
	v_addc_co_u32_e64 v179, s[18:19], v179, v179, s[18:19]
	v_addc_co_u32_e64 v179, s[22:23], v179, v179, s[22:23]
	v_addc_co_u32_e64 v179, s[24:25], v179, v179, s[24:25]
	v_cmp_gt_u32_e64 s[16:17], v10, v177
	v_cmp_gt_u32_e64 s[18:19], v11, v177
	v_cmp_gt_u32_e64 s[22:23], v12, v177
	v_cmp_gt_u32_e64 s[24:25], v13, v177
	v_addc_co_u32_e64 v181, s[16:17], v181, v181, s[16:17]
	v_addc_co_u32_e64 v181, s[18:19], v181, v181, s[18:19]
	v_addc_co_u32_e64 v181, s[22:23], v181, v181, s[22:23]
	v_addc_co_u32_e64 v181, s[24:25], v181, v181, s[24:25]
	v_add_u32_e32 v5, 0x80, v5
	v_cmp_gt_i32_e32 vcc, s57, v5
	s_and_b64 exec, exec, vcc
	s_cbranch_execz .Lcls_p1_done
	s_waitcnt lgkmcnt(0)
	v_cmp_ge_u32_e64 s[16:17], v216, v176
	v_cmp_ge_u32_e64 s[18:19], v217, v176
	v_cmp_ge_u32_e64 s[22:23], v218, v176
	v_cmp_ge_u32_e64 s[24:25], v219, v176
	v_addc_co_u32_e64 v179, s[16:17], v179, v179, s[16:17]
	v_addc_co_u32_e64 v179, s[18:19], v179, v179, s[18:19]
	v_addc_co_u32_e64 v179, s[22:23], v179, v179, s[22:23]
	v_addc_co_u32_e64 v179, s[24:25], v179, v179, s[24:25]
	v_cmp_gt_u32_e64 s[16:17], v216, v177
	v_cmp_gt_u32_e64 s[18:19], v217, v177
	v_cmp_gt_u32_e64 s[22:23], v218, v177
	v_cmp_gt_u32_e64 s[24:25], v219, v177
	v_addc_co_u32_e64 v181, s[16:17], v181, v181, s[16:17]
	v_addc_co_u32_e64 v181, s[18:19], v181, v181, s[18:19]
	v_addc_co_u32_e64 v181, s[22:23], v181, v181, s[22:23]
	v_addc_co_u32_e64 v181, s[24:25], v181, v181, s[24:25]
.Lcls_p1_done:
	s_waitcnt lgkmcnt(0)
	s_mov_b64 exec, s[10:11]
	v_bcnt_u32_b32 v182, v178, 0
	v_bcnt_u32_b32 v183, v180, 0
	v_bcnt_u32_b32 v182, v179, v182
	v_bcnt_u32_b32 v183, v181, v183
	s_add_i32 s10, s57, 0x7f
	v_sub_u32_e32 v184, s10, v3
	v_lshrrev_b32_e32 v184, 7, v184
	v_min_u32_e32 v185, 8, v184
	v_sub_u32_e32 v186, v184, v185
	v_lshlrev_b32_e32 v185, 2, v185
	v_lshlrev_b32_e32 v186, 2, v186
	v_sub_u32_e32 v185, 32, v185
	v_sub_u32_e32 v186, 32, v186
	v_lshlrev_b32_e32 v178, v185, v178
	v_lshlrev_b32_e32 v180, v185, v180
	v_lshlrev_b32_e32 v179, v186, v179
	v_lshlrev_b32_e32 v181, v186, v181
	v_sub_u32_e32 v184, v182, v183
	v_lshl_or_b32 v4, v184, 16, v183
.LBB0_733:
	s_or_b64 exec, exec, s[6:7]
	v_and_b32_e32 v1, 64, v147
	v_cmp_eq_u32_e64 s[6:7], 0, v145
	v_cmp_gt_u32_e64 s[10:11], 32, v145
	v_lshlrev_b32_e32 v10, 2, v147
	v_mov_b32_e32 v5, v4
	s_nop 1
	v_add_u32_dpp v5, v5, v5 row_shr:1 row_mask:0xf bank_mask:0xf
	s_nop 1
	v_add_u32_dpp v5, v5, v5 row_shr:2 row_mask:0xf bank_mask:0xf
	s_nop 1
	v_add_u32_dpp v5, v5, v5 row_shr:4 row_mask:0xf bank_mask:0xf
	s_nop 1
	v_add_u32_dpp v5, v5, v5 row_shr:8 row_mask:0xf bank_mask:0xf
	s_nop 1
	v_add_u32_dpp v5, v5, v5 row_bcast:15 row_mask:0xa bank_mask:0xf
	s_nop 1
	v_add_u32_dpp v5, v5, v5 row_bcast:31 row_mask:0xc bank_mask:0xf
	s_nop 1
	v_readlane_b32 s18, v5, 63
	s_add_i32 s23, s61, 0x25808
	v_mov_b32_e32 v184, s23
	s_and_b32 s19, s18, 0xffff
	s_lshr_b32 s22, s18, 16
	v_mov_b32_e32 v6, s19
	v_mov_b32_e32 v7, s22
	s_mov_b64 exec, 1
	ds_add_rtn_u32 v185, v184, v6
	ds_add_rtn_u32 v186, v184, v7 offset:12
	s_mov_b64 exec, -1
	v_sub_u32_e32 v4, v5, v4
	s_lshl_b32 s92, s90, 9
	s_add_i32 s93, s92, 0x24000
	s_waitcnt lgkmcnt(0)
	v_readfirstlane_b32 s19, v185
	v_readfirstlane_b32 s22, v186
	v_lshrrev_b32_e32 v9, 16, v4
	v_add_u32_e32 v11, s19, v4
	v_add_u32_e32 v9, s22, v9
	s_and_saveexec_b64 s[16:17], s[12:13]
	s_cbranch_execz .LBB0_778
	v_mov_b32_e32 v199, 0x1000
	v_mov_b32_e32 v189, 0x80000000
	v_lshlrev_b32_e32 v190, 2, v3
	v_xor_b32_e32 v178, v178, v180
	v_xor_b32_e32 v179, v179, v181
.Lcls_A_lo:
	v_cmp_ne_u32_e32 vcc, 0, v180
	s_cbranch_vccz .Lcls_A_lo_done
	s_and_saveexec_b64 s[18:19], vcc
	v_ffbh_u32_e32 v191, v180
	v_lshrrev_b32_e32 v193, v191, v189
	v_xor_b32_e32 v180, v180, v193
	v_and_b32_e32 v193, 60, v191
	v_lshl_add_u32 v192, v193, 7, v190
	v_and_b32_e32 v193, 3, v191
	v_add_u32_e32 v192, v192, v193
	v_and_b32_e32 v193, 0xff, v11
	v_lshl_add_u32 v193, v193, 1, s93
	v_add_u32_e32 v11, 1, v11
	ds_write_b16 v193, v192
	s_mov_b64 exec, s[18:19]
	s_branch .Lcls_A_lo
.Lcls_A_lo_done:
.Lcls_A_hi:
	v_cmp_ne_u32_e32 vcc, 0, v181
	s_cbranch_vccz .Lcls_A_hi_done
	s_and_saveexec_b64 s[18:19], vcc
	v_ffbh_u32_e32 v191, v181
	v_lshrrev_b32_e32 v193, v191, v189
	v_xor_b32_e32 v181, v181, v193
	v_and_b32_e32 v193, 60, v191
	v_lshl_add_u32 v192, v193, 7, v190
	v_and_b32_e32 v193, 3, v191
	v_add3_u32 v192, v192, v193, v199
	v_and_b32_e32 v193, 0xff, v11
	v_lshl_add_u32 v193, v193, 1, s93
	v_add_u32_e32 v11, 1, v11
	ds_write_b16 v193, v192
	s_mov_b64 exec, s[18:19]
	s_branch .Lcls_A_hi
.Lcls_A_hi_done:
.Lcls_C_lo:
	v_cmp_ne_u32_e32 vcc, 0, v178
	s_cbranch_vccz .Lcls_C_lo_done
	s_and_saveexec_b64 s[18:19], vcc
	v_ffbh_u32_e32 v191, v178
	v_lshrrev_b32_e32 v193, v191, v189
	v_xor_b32_e32 v178, v178, v193
	v_and_b32_e32 v193, 60, v191
	v_lshl_add_u32 v192, v193, 7, v190
	v_and_b32_e32 v193, 3, v191
	v_add_u32_e32 v192, v192, v193
	v_lshl_add_u32 v195, v192, 2, s89
	ds_read_b32 v194, v195
	v_cmp_gt_u32_e32 vcc, s69, v9
	v_or_b32_e32 v196, s92, v9
	v_lshl_add_u32 v197, v196, 2, s68
	v_lshl_add_u32 v198, v196, 1, s68
	v_add_u32_e32 v9, 1, v9
	s_and_b64 exec, exec, vcc
	s_waitcnt lgkmcnt(0)
	ds_write_b32 v197, v194
	ds_write_b16 v198, v192 offset:8192
	s_mov_b64 exec, s[18:19]
	s_branch .Lcls_C_lo
.Lcls_C_lo_done:
.Lcls_C_hi:
	v_cmp_ne_u32_e32 vcc, 0, v179
	s_cbranch_vccz .Lcls_C_hi_done
	s_and_saveexec_b64 s[18:19], vcc
	v_ffbh_u32_e32 v191, v179
	v_lshrrev_b32_e32 v193, v191, v189
	v_xor_b32_e32 v179, v179, v193
	v_and_b32_e32 v193, 60, v191
	v_lshl_add_u32 v192, v193, 7, v190
	v_and_b32_e32 v193, 3, v191
	v_add3_u32 v192, v192, v193, v199
	v_lshl_add_u32 v195, v192, 2, s89
	ds_read_b32 v194, v195
	v_cmp_gt_u32_e32 vcc, s69, v9
	v_or_b32_e32 v196, s92, v9
	v_lshl_add_u32 v197, v196, 2, s68
	v_lshl_add_u32 v198, v196, 1, s68
	v_add_u32_e32 v9, 1, v9
	s_and_b64 exec, exec, vcc
	s_waitcnt lgkmcnt(0)
	ds_write_b32 v197, v194
	ds_write_b16 v198, v192 offset:8192
	s_mov_b64 exec, s[18:19]
	s_branch .Lcls_C_hi

.Lref_v8:
	ds_read_b32 v216, v238
	ds_read_u16 v224, v245
	ds_read_b32 v217, v238 offset:256
	ds_read_u16 v225, v245 offset:128
	ds_read_b32 v218, v238 offset:512
	ds_read_u16 v226, v245 offset:256
	ds_read_b32 v219, v238 offset:768
	ds_read_u16 v227, v245 offset:384
	ds_read_b32 v220, v238 offset:1024
	ds_read_u16 v228, v245 offset:512
	ds_read_b32 v221, v238 offset:1280
	ds_read_u16 v229, v245 offset:640
	ds_read_b32 v222, v238 offset:1536
	ds_read_u16 v230, v245 offset:768
	ds_read_b32 v223, v238 offset:1792
	ds_read_u16 v231, v245 offset:896
	v_cmp_gt_u32_e64 s[8:9], s93, v145
	v_add_u32_e32 v241, 64, v145
	v_cmp_gt_u32_e64 s[12:13], s93, v241
	v_add_u32_e32 v241, 128, v145
	v_cmp_gt_u32_e64 s[14:15], s93, v241
	v_add_u32_e32 v241, 192, v145
	v_cmp_gt_u32_e64 s[16:17], s93, v241
	v_add_u32_e32 v241, 256, v145
	v_cmp_gt_u32_e64 s[18:19], s93, v241
	v_add_u32_e32 v241, 320, v145
	v_cmp_gt_u32_e64 s[22:23], s93, v241
	v_add_u32_e32 v241, 384, v145
	v_cmp_gt_u32_e64 s[24:25], s93, v241
	v_add_u32_e32 v241, 448, v145
	v_cmp_gt_u32_e64 s[58:59], s93, v241
	s_waitcnt lgkmcnt(0)
	v_cndmask_b32_e64 v216, 0, v216, s[8:9]
	v_cndmask_b32_e64 v217, 0, v217, s[12:13]
	v_cndmask_b32_e64 v218, 0, v218, s[14:15]
	v_cndmask_b32_e64 v219, 0, v219, s[16:17]
	v_cndmask_b32_e64 v220, 0, v220, s[18:19]
	v_cndmask_b32_e64 v221, 0, v221, s[22:23]
	v_cndmask_b32_e64 v222, 0, v222, s[24:25]
	v_cndmask_b32_e64 v223, 0, v223, s[58:59]
	s_or_b32 s57, s33, 0x100000
	v_cmp_ge_u32_e64 s[8:9], v216, s57
	v_cmp_ge_u32_e64 s[12:13], v217, s57
	v_cmp_ge_u32_e64 s[14:15], v218, s57
	v_cmp_ge_u32_e64 s[16:17], v219, s57
	v_cmp_ge_u32_e64 s[18:19], v220, s57
	v_cmp_ge_u32_e64 s[22:23], v221, s57
	v_cmp_ge_u32_e64 s[24:25], v222, s57
	v_cmp_ge_u32_e64 s[58:59], v223, s57
	s_bcnt1_i32_b64 s89, s[8:9]
	s_bcnt1_i32_b64 s61, s[12:13]
	s_add_u32 s89, s89, s61
	s_bcnt1_i32_b64 s61, s[14:15]
	s_add_u32 s89, s89, s61
	s_bcnt1_i32_b64 s61, s[16:17]
	s_add_u32 s89, s89, s61
	s_bcnt1_i32_b64 s61, s[18:19]
	s_add_u32 s89, s89, s61
	s_bcnt1_i32_b64 s61, s[22:23]
	s_add_u32 s89, s89, s61
	s_bcnt1_i32_b64 s61, s[24:25]
	s_add_u32 s89, s89, s61
	s_bcnt1_i32_b64 s61, s[58:59]
	s_add_u32 s89, s89, s61
	s_cmp_ge_u32 s89, s91
	s_cselect_b32 s33, s57, s33
	s_cmp_eq_u32 s89, s91
	s_cbranch_scc1 .Lref_e8
	s_or_b32 s57, s33, 0x80000
	v_cmp_ge_u32_e64 s[8:9], v216, s57
	v_cmp_ge_u32_e64 s[12:13], v217, s57
	v_cmp_ge_u32_e64 s[14:15], v218, s57
	v_cmp_ge_u32_e64 s[16:17], v219, s57
	v_cmp_ge_u32_e64 s[18:19], v220, s57
	v_cmp_ge_u32_e64 s[22:23], v221, s57
	v_cmp_ge_u32_e64 s[24:25], v222, s57
	v_cmp_ge_u32_e64 s[58:59], v223, s57
	s_bcnt1_i32_b64 s89, s[8:9]
	s_bcnt1_i32_b64 s61, s[12:13]
	s_add_u32 s89, s89, s61
	s_bcnt1_i32_b64 s61, s[14:15]
	s_add_u32 s89, s89, s61
	s_bcnt1_i32_b64 s61, s[16:17]
	s_add_u32 s89, s89, s61
	s_bcnt1_i32_b64 s61, s[18:19]
	s_add_u32 s89, s89, s61
	s_bcnt1_i32_b64 s61, s[22:23]
	s_add_u32 s89, s89, s61
	s_bcnt1_i32_b64 s61, s[24:25]
	s_add_u32 s89, s89, s61
	s_bcnt1_i32_b64 s61, s[58:59]
	s_add_u32 s89, s89, s61
	s_cmp_ge_u32 s89, s91
	s_cselect_b32 s33, s57, s33
	s_cmp_eq_u32 s89, s91
	s_cbranch_scc1 .Lref_e8
	s_or_b32 s57, s33, 0x40000
	v_cmp_ge_u32_e64 s[8:9], v216, s57
	v_cmp_ge_u32_e64 s[12:13], v217, s57
	v_cmp_ge_u32_e64 s[14:15], v218, s57
	v_cmp_ge_u32_e64 s[16:17], v219, s57
	v_cmp_ge_u32_e64 s[18:19], v220, s57
	v_cmp_ge_u32_e64 s[22:23], v221, s57
	v_cmp_ge_u32_e64 s[24:25], v222, s57
	v_cmp_ge_u32_e64 s[58:59], v223, s57
	s_bcnt1_i32_b64 s89, s[8:9]
	s_bcnt1_i32_b64 s61, s[12:13]
	s_add_u32 s89, s89, s61
	s_bcnt1_i32_b64 s61, s[14:15]
	s_add_u32 s89, s89, s61
	s_bcnt1_i32_b64 s61, s[16:17]
	s_add_u32 s89, s89, s61
	s_bcnt1_i32_b64 s61, s[18:19]
	s_add_u32 s89, s89, s61
	s_bcnt1_i32_b64 s61, s[22:23]
	s_add_u32 s89, s89, s61
	s_bcnt1_i32_b64 s61, s[24:25]
	s_add_u32 s89, s89, s61
	s_bcnt1_i32_b64 s61, s[58:59]
	s_add_u32 s89, s89, s61
	s_cmp_ge_u32 s89, s91
	s_cselect_b32 s33, s57, s33
	s_cmp_eq_u32 s89, s91
	s_cbranch_scc1 .Lref_e8
	s_or_b32 s57, s33, 0x20000
	v_cmp_ge_u32_e64 s[8:9], v216, s57
	v_cmp_ge_u32_e64 s[12:13], v217, s57
	v_cmp_ge_u32_e64 s[14:15], v218, s57
	v_cmp_ge_u32_e64 s[16:17], v219, s57
	v_cmp_ge_u32_e64 s[18:19], v220, s57
	v_cmp_ge_u32_e64 s[22:23], v221, s57
	v_cmp_ge_u32_e64 s[24:25], v222, s57
	v_cmp_ge_u32_e64 s[58:59], v223, s57
	s_bcnt1_i32_b64 s89, s[8:9]
	s_bcnt1_i32_b64 s61, s[12:13]
	s_add_u32 s89, s89, s61
	s_bcnt1_i32_b64 s61, s[14:15]
	s_add_u32 s89, s89, s61
	s_bcnt1_i32_b64 s61, s[16:17]
	s_add_u32 s89, s89, s61
	s_bcnt1_i32_b64 s61, s[18:19]
	s_add_u32 s89, s89, s61
	s_bcnt1_i32_b64 s61, s[22:23]
	s_add_u32 s89, s89, s61
	s_bcnt1_i32_b64 s61, s[24:25]
	s_add_u32 s89, s89, s61
	s_bcnt1_i32_b64 s61, s[58:59]
	s_add_u32 s89, s89, s61
	s_cmp_ge_u32 s89, s91
	s_cselect_b32 s33, s57, s33
	s_cmp_eq_u32 s89, s91
	s_cbranch_scc1 .Lref_e8
	s_or_b32 s57, s33, 0x10000
	v_cmp_ge_u32_e64 s[8:9], v216, s57
	v_cmp_ge_u32_e64 s[12:13], v217, s57
	v_cmp_ge_u32_e64 s[14:15], v218, s57
	v_cmp_ge_u32_e64 s[16:17], v219, s57
	v_cmp_ge_u32_e64 s[18:19], v220, s57
	v_cmp_ge_u32_e64 s[22:23], v221, s57
	v_cmp_ge_u32_e64 s[24:25], v222, s57
	v_cmp_ge_u32_e64 s[58:59], v223, s57
	s_bcnt1_i32_b64 s89, s[8:9]
	s_bcnt1_i32_b64 s61, s[12:13]
	s_add_u32 s89, s89, s61
	s_bcnt1_i32_b64 s61, s[14:15]
	s_add_u32 s89, s89, s61
	s_bcnt1_i32_b64 s61, s[16:17]
	s_add_u32 s89, s89, s61
	s_bcnt1_i32_b64 s61, s[18:19]
	s_add_u32 s89, s89, s61
	s_bcnt1_i32_b64 s61, s[22:23]
	s_add_u32 s89, s89, s61
	s_bcnt1_i32_b64 s61, s[24:25]
	s_add_u32 s89, s89, s61
	s_bcnt1_i32_b64 s61, s[58:59]
	s_add_u32 s89, s89, s61
	s_cmp_ge_u32 s89, s91
	s_cselect_b32 s33, s57, s33
	s_cmp_eq_u32 s89, s91
	s_cbranch_scc1 .Lref_e8
	s_or_b32 s57, s33, 0x8000
	v_cmp_ge_u32_e64 s[8:9], v216, s57
	v_cmp_ge_u32_e64 s[12:13], v217, s57
	v_cmp_ge_u32_e64 s[14:15], v218, s57
	v_cmp_ge_u32_e64 s[16:17], v219, s57
	v_cmp_ge_u32_e64 s[18:19], v220, s57
	v_cmp_ge_u32_e64 s[22:23], v221, s57
	v_cmp_ge_u32_e64 s[24:25], v222, s57
	v_cmp_ge_u32_e64 s[58:59], v223, s57
	s_bcnt1_i32_b64 s89, s[8:9]
	s_bcnt1_i32_b64 s61, s[12:13]
	s_add_u32 s89, s89, s61
	s_bcnt1_i32_b64 s61, s[14:15]
	s_add_u32 s89, s89, s61
	s_bcnt1_i32_b64 s61, s[16:17]
	s_add_u32 s89, s89, s61
	s_bcnt1_i32_b64 s61, s[18:19]
	s_add_u32 s89, s89, s61
	s_bcnt1_i32_b64 s61, s[22:23]
	s_add_u32 s89, s89, s61
	s_bcnt1_i32_b64 s61, s[24:25]
	s_add_u32 s89, s89, s61
	s_bcnt1_i32_b64 s61, s[58:59]
	s_add_u32 s89, s89, s61
	s_cmp_ge_u32 s89, s91
	s_cselect_b32 s33, s57, s33
	s_cmp_eq_u32 s89, s91
	s_cbranch_scc1 .Lref_e8
	s_or_b32 s57, s33, 0x4000
	v_cmp_ge_u32_e64 s[8:9], v216, s57
	v_cmp_ge_u32_e64 s[12:13], v217, s57
	v_cmp_ge_u32_e64 s[14:15], v218, s57
	v_cmp_ge_u32_e64 s[16:17], v219, s57
	v_cmp_ge_u32_e64 s[18:19], v220, s57
	v_cmp_ge_u32_e64 s[22:23], v221, s57
	v_cmp_ge_u32_e64 s[24:25], v222, s57
	v_cmp_ge_u32_e64 s[58:59], v223, s57
	s_bcnt1_i32_b64 s89, s[8:9]
	s_bcnt1_i32_b64 s61, s[12:13]
	s_add_u32 s89, s89, s61
	s_bcnt1_i32_b64 s61, s[14:15]
	s_add_u32 s89, s89, s61
	s_bcnt1_i32_b64 s61, s[16:17]
	s_add_u32 s89, s89, s61
	s_bcnt1_i32_b64 s61, s[18:19]
	s_add_u32 s89, s89, s61
	s_bcnt1_i32_b64 s61, s[22:23]
	s_add_u32 s89, s89, s61
	s_bcnt1_i32_b64 s61, s[24:25]
	s_add_u32 s89, s89, s61
	s_bcnt1_i32_b64 s61, s[58:59]
	s_add_u32 s89, s89, s61
	s_cmp_ge_u32 s89, s91
	s_cselect_b32 s33, s57, s33
	s_cmp_eq_u32 s89, s91
	s_cbranch_scc1 .Lref_e8
	s_or_b32 s57, s33, 0x2000
	v_cmp_ge_u32_e64 s[8:9], v216, s57
	v_cmp_ge_u32_e64 s[12:13], v217, s57
	v_cmp_ge_u32_e64 s[14:15], v218, s57
	v_cmp_ge_u32_e64 s[16:17], v219, s57
	v_cmp_ge_u32_e64 s[18:19], v220, s57
	v_cmp_ge_u32_e64 s[22:23], v221, s57
	v_cmp_ge_u32_e64 s[24:25], v222, s57
	v_cmp_ge_u32_e64 s[58:59], v223, s57
	s_bcnt1_i32_b64 s89, s[8:9]
	s_bcnt1_i32_b64 s61, s[12:13]
	s_add_u32 s89, s89, s61
	s_bcnt1_i32_b64 s61, s[14:15]
	s_add_u32 s89, s89, s61
	s_bcnt1_i32_b64 s61, s[16:17]
	s_add_u32 s89, s89, s61
	s_bcnt1_i32_b64 s61, s[18:19]
	s_add_u32 s89, s89, s61
	s_bcnt1_i32_b64 s61, s[22:23]
	s_add_u32 s89, s89, s61
	s_bcnt1_i32_b64 s61, s[24:25]
	s_add_u32 s89, s89, s61
	s_bcnt1_i32_b64 s61, s[58:59]
	s_add_u32 s89, s89, s61
	s_cmp_ge_u32 s89, s91
	s_cselect_b32 s33, s57, s33
	s_cmp_eq_u32 s89, s91
	s_cbranch_scc1 .Lref_e8
	s_or_b32 s57, s33, 0x1000
	v_cmp_ge_u32_e64 s[8:9], v216, s57
	v_cmp_ge_u32_e64 s[12:13], v217, s57
	v_cmp_ge_u32_e64 s[14:15], v218, s57
	v_cmp_ge_u32_e64 s[16:17], v219, s57
	v_cmp_ge_u32_e64 s[18:19], v220, s57
	v_cmp_ge_u32_e64 s[22:23], v221, s57
	v_cmp_ge_u32_e64 s[24:25], v222, s57
	v_cmp_ge_u32_e64 s[58:59], v223, s57
	s_bcnt1_i32_b64 s89, s[8:9]
	s_bcnt1_i32_b64 s61, s[12:13]
	s_add_u32 s89, s89, s61
	s_bcnt1_i32_b64 s61, s[14:15]
	s_add_u32 s89, s89, s61
	s_bcnt1_i32_b64 s61, s[16:17]
	s_add_u32 s89, s89, s61
	s_bcnt1_i32_b64 s61, s[18:19]
	s_add_u32 s89, s89, s61
	s_bcnt1_i32_b64 s61, s[22:23]
	s_add_u32 s89, s89, s61
	s_bcnt1_i32_b64 s61, s[24:25]
	s_add_u32 s89, s89, s61
	s_bcnt1_i32_b64 s61, s[58:59]
	s_add_u32 s89, s89, s61
	s_cmp_ge_u32 s89, s91
	s_cselect_b32 s33, s57, s33
	s_cmp_eq_u32 s89, s91
	s_cbranch_scc1 .Lref_e8
	s_or_b32 s57, s33, 0x800
	v_cmp_ge_u32_e64 s[8:9], v216, s57
	v_cmp_ge_u32_e64 s[12:13], v217, s57
	v_cmp_ge_u32_e64 s[14:15], v218, s57
	v_cmp_ge_u32_e64 s[16:17], v219, s57
	v_cmp_ge_u32_e64 s[18:19], v220, s57
	v_cmp_ge_u32_e64 s[22:23], v221, s57
	v_cmp_ge_u32_e64 s[24:25], v222, s57
	v_cmp_ge_u32_e64 s[58:59], v223, s57
	s_bcnt1_i32_b64 s89, s[8:9]
	s_bcnt1_i32_b64 s61, s[12:13]
	s_add_u32 s89, s89, s61
	s_bcnt1_i32_b64 s61, s[14:15]
	s_add_u32 s89, s89, s61
	s_bcnt1_i32_b64 s61, s[16:17]
	s_add_u32 s89, s89, s61
	s_bcnt1_i32_b64 s61, s[18:19]
	s_add_u32 s89, s89, s61
	s_bcnt1_i32_b64 s61, s[22:23]
	s_add_u32 s89, s89, s61
	s_bcnt1_i32_b64 s61, s[24:25]
	s_add_u32 s89, s89, s61
	s_bcnt1_i32_b64 s61, s[58:59]
	s_add_u32 s89, s89, s61
	s_cmp_ge_u32 s89, s91
	s_cselect_b32 s33, s57, s33
	s_cmp_eq_u32 s89, s91
	s_cbranch_scc1 .Lref_e8
	s_or_b32 s57, s33, 0x400
	v_cmp_ge_u32_e64 s[8:9], v216, s57
	v_cmp_ge_u32_e64 s[12:13], v217, s57
	v_cmp_ge_u32_e64 s[14:15], v218, s57
	v_cmp_ge_u32_e64 s[16:17], v219, s57
	v_cmp_ge_u32_e64 s[18:19], v220, s57
	v_cmp_ge_u32_e64 s[22:23], v221, s57
	v_cmp_ge_u32_e64 s[24:25], v222, s57
	v_cmp_ge_u32_e64 s[58:59], v223, s57
	s_bcnt1_i32_b64 s89, s[8:9]
	s_bcnt1_i32_b64 s61, s[12:13]
	s_add_u32 s89, s89, s61
	s_bcnt1_i32_b64 s61, s[14:15]
	s_add_u32 s89, s89, s61
	s_bcnt1_i32_b64 s61, s[16:17]
	s_add_u32 s89, s89, s61
	s_bcnt1_i32_b64 s61, s[18:19]
	s_add_u32 s89, s89, s61
	s_bcnt1_i32_b64 s61, s[22:23]
	s_add_u32 s89, s89, s61
	s_bcnt1_i32_b64 s61, s[24:25]
	s_add_u32 s89, s89, s61
	s_bcnt1_i32_b64 s61, s[58:59]
	s_add_u32 s89, s89, s61
	s_cmp_ge_u32 s89, s91
	s_cselect_b32 s33, s57, s33
	s_cmp_eq_u32 s89, s91
	s_cbranch_scc1 .Lref_e8
	s_or_b32 s57, s33, 0x200
	v_cmp_ge_u32_e64 s[8:9], v216, s57
	v_cmp_ge_u32_e64 s[12:13], v217, s57
	v_cmp_ge_u32_e64 s[14:15], v218, s57
	v_cmp_ge_u32_e64 s[16:17], v219, s57
	v_cmp_ge_u32_e64 s[18:19], v220, s57
	v_cmp_ge_u32_e64 s[22:23], v221, s57
	v_cmp_ge_u32_e64 s[24:25], v222, s57
	v_cmp_ge_u32_e64 s[58:59], v223, s57
	s_bcnt1_i32_b64 s89, s[8:9]
	s_bcnt1_i32_b64 s61, s[12:13]
	s_add_u32 s89, s89, s61
	s_bcnt1_i32_b64 s61, s[14:15]
	s_add_u32 s89, s89, s61
	s_bcnt1_i32_b64 s61, s[16:17]
	s_add_u32 s89, s89, s61
	s_bcnt1_i32_b64 s61, s[18:19]
	s_add_u32 s89, s89, s61
	s_bcnt1_i32_b64 s61, s[22:23]
	s_add_u32 s89, s89, s61
	s_bcnt1_i32_b64 s61, s[24:25]
	s_add_u32 s89, s89, s61
	s_bcnt1_i32_b64 s61, s[58:59]
	s_add_u32 s89, s89, s61
	s_cmp_ge_u32 s89, s91
	s_cselect_b32 s33, s57, s33
	s_cmp_eq_u32 s89, s91
	s_cbranch_scc1 .Lref_e8
	s_or_b32 s57, s33, 0x100
	v_cmp_ge_u32_e64 s[8:9], v216, s57
	v_cmp_ge_u32_e64 s[12:13], v217, s57
	v_cmp_ge_u32_e64 s[14:15], v218, s57
	v_cmp_ge_u32_e64 s[16:17], v219, s57
	v_cmp_ge_u32_e64 s[18:19], v220, s57
	v_cmp_ge_u32_e64 s[22:23], v221, s57
	v_cmp_ge_u32_e64 s[24:25], v222, s57
	v_cmp_ge_u32_e64 s[58:59], v223, s57
	s_bcnt1_i32_b64 s89, s[8:9]
	s_bcnt1_i32_b64 s61, s[12:13]
	s_add_u32 s89, s89, s61
	s_bcnt1_i32_b64 s61, s[14:15]
	s_add_u32 s89, s89, s61
	s_bcnt1_i32_b64 s61, s[16:17]
	s_add_u32 s89, s89, s61
	s_bcnt1_i32_b64 s61, s[18:19]
	s_add_u32 s89, s89, s61
	s_bcnt1_i32_b64 s61, s[22:23]
	s_add_u32 s89, s89, s61
	s_bcnt1_i32_b64 s61, s[24:25]
	s_add_u32 s89, s89, s61
	s_bcnt1_i32_b64 s61, s[58:59]
	s_add_u32 s89, s89, s61
	s_cmp_ge_u32 s89, s91
	s_cselect_b32 s33, s57, s33
	s_cmp_eq_u32 s89, s91
	s_cbranch_scc1 .Lref_e8
	s_or_b32 s57, s33, 0x80
	v_cmp_ge_u32_e64 s[8:9], v216, s57
	v_cmp_ge_u32_e64 s[12:13], v217, s57
	v_cmp_ge_u32_e64 s[14:15], v218, s57
	v_cmp_ge_u32_e64 s[16:17], v219, s57
	v_cmp_ge_u32_e64 s[18:19], v220, s57
	v_cmp_ge_u32_e64 s[22:23], v221, s57
	v_cmp_ge_u32_e64 s[24:25], v222, s57
	v_cmp_ge_u32_e64 s[58:59], v223, s57
	s_bcnt1_i32_b64 s89, s[8:9]
	s_bcnt1_i32_b64 s61, s[12:13]
	s_add_u32 s89, s89, s61
	s_bcnt1_i32_b64 s61, s[14:15]
	s_add_u32 s89, s89, s61
	s_bcnt1_i32_b64 s61, s[16:17]
	s_add_u32 s89, s89, s61
	s_bcnt1_i32_b64 s61, s[18:19]
	s_add_u32 s89, s89, s61
	s_bcnt1_i32_b64 s61, s[22:23]
	s_add_u32 s89, s89, s61
	s_bcnt1_i32_b64 s61, s[24:25]
	s_add_u32 s89, s89, s61
	s_bcnt1_i32_b64 s61, s[58:59]
	s_add_u32 s89, s89, s61
	s_cmp_ge_u32 s89, s91
	s_cselect_b32 s33, s57, s33
	s_cmp_eq_u32 s89, s91
	s_cbranch_scc1 .Lref_e8
	s_or_b32 s57, s33, 0x40
	v_cmp_ge_u32_e64 s[8:9], v216, s57
	v_cmp_ge_u32_e64 s[12:13], v217, s57
	v_cmp_ge_u32_e64 s[14:15], v218, s57
	v_cmp_ge_u32_e64 s[16:17], v219, s57
	v_cmp_ge_u32_e64 s[18:19], v220, s57
	v_cmp_ge_u32_e64 s[22:23], v221, s57
	v_cmp_ge_u32_e64 s[24:25], v222, s57
	v_cmp_ge_u32_e64 s[58:59], v223, s57
	s_bcnt1_i32_b64 s89, s[8:9]
	s_bcnt1_i32_b64 s61, s[12:13]
	s_add_u32 s89, s89, s61
	s_bcnt1_i32_b64 s61, s[14:15]
	s_add_u32 s89, s89, s61
	s_bcnt1_i32_b64 s61, s[16:17]
	s_add_u32 s89, s89, s61
	s_bcnt1_i32_b64 s61, s[18:19]
	s_add_u32 s89, s89, s61
	s_bcnt1_i32_b64 s61, s[22:23]
	s_add_u32 s89, s89, s61
	s_bcnt1_i32_b64 s61, s[24:25]
	s_add_u32 s89, s89, s61
	s_bcnt1_i32_b64 s61, s[58:59]
	s_add_u32 s89, s89, s61
	s_cmp_ge_u32 s89, s91
	s_cselect_b32 s33, s57, s33
	s_cmp_eq_u32 s89, s91
	s_cbranch_scc1 .Lref_e8
	s_or_b32 s57, s33, 0x20
	v_cmp_ge_u32_e64 s[8:9], v216, s57
	v_cmp_ge_u32_e64 s[12:13], v217, s57
	v_cmp_ge_u32_e64 s[14:15], v218, s57
	v_cmp_ge_u32_e64 s[16:17], v219, s57
	v_cmp_ge_u32_e64 s[18:19], v220, s57
	v_cmp_ge_u32_e64 s[22:23], v221, s57
	v_cmp_ge_u32_e64 s[24:25], v222, s57
	v_cmp_ge_u32_e64 s[58:59], v223, s57
	s_bcnt1_i32_b64 s89, s[8:9]
	s_bcnt1_i32_b64 s61, s[12:13]
	s_add_u32 s89, s89, s61
	s_bcnt1_i32_b64 s61, s[14:15]
	s_add_u32 s89, s89, s61
	s_bcnt1_i32_b64 s61, s[16:17]
	s_add_u32 s89, s89, s61
	s_bcnt1_i32_b64 s61, s[18:19]
	s_add_u32 s89, s89, s61
	s_bcnt1_i32_b64 s61, s[22:23]
	s_add_u32 s89, s89, s61
	s_bcnt1_i32_b64 s61, s[24:25]
	s_add_u32 s89, s89, s61
	s_bcnt1_i32_b64 s61, s[58:59]
	s_add_u32 s89, s89, s61
	s_cmp_ge_u32 s89, s91
	s_cselect_b32 s33, s57, s33
	s_cmp_eq_u32 s89, s91
	s_cbranch_scc1 .Lref_e8
	s_or_b32 s57, s33, 0x10
	v_cmp_ge_u32_e64 s[8:9], v216, s57
	v_cmp_ge_u32_e64 s[12:13], v217, s57
	v_cmp_ge_u32_e64 s[14:15], v218, s57
	v_cmp_ge_u32_e64 s[16:17], v219, s57
	v_cmp_ge_u32_e64 s[18:19], v220, s57
	v_cmp_ge_u32_e64 s[22:23], v221, s57
	v_cmp_ge_u32_e64 s[24:25], v222, s57
	v_cmp_ge_u32_e64 s[58:59], v223, s57
	s_bcnt1_i32_b64 s89, s[8:9]
	s_bcnt1_i32_b64 s61, s[12:13]
	s_add_u32 s89, s89, s61
	s_bcnt1_i32_b64 s61, s[14:15]
	s_add_u32 s89, s89, s61
	s_bcnt1_i32_b64 s61, s[16:17]
	s_add_u32 s89, s89, s61
	s_bcnt1_i32_b64 s61, s[18:19]
	s_add_u32 s89, s89, s61
	s_bcnt1_i32_b64 s61, s[22:23]
	s_add_u32 s89, s89, s61
	s_bcnt1_i32_b64 s61, s[24:25]
	s_add_u32 s89, s89, s61
	s_bcnt1_i32_b64 s61, s[58:59]
	s_add_u32 s89, s89, s61
	s_cmp_ge_u32 s89, s91
	s_cselect_b32 s33, s57, s33
	s_cmp_eq_u32 s89, s91
	s_cbranch_scc1 .Lref_e8
	s_or_b32 s57, s33, 0x8
	v_cmp_ge_u32_e64 s[8:9], v216, s57
	v_cmp_ge_u32_e64 s[12:13], v217, s57
	v_cmp_ge_u32_e64 s[14:15], v218, s57
	v_cmp_ge_u32_e64 s[16:17], v219, s57
	v_cmp_ge_u32_e64 s[18:19], v220, s57
	v_cmp_ge_u32_e64 s[22:23], v221, s57
	v_cmp_ge_u32_e64 s[24:25], v222, s57
	v_cmp_ge_u32_e64 s[58:59], v223, s57
	s_bcnt1_i32_b64 s89, s[8:9]
	s_bcnt1_i32_b64 s61, s[12:13]
	s_add_u32 s89, s89, s61
	s_bcnt1_i32_b64 s61, s[14:15]
	s_add_u32 s89, s89, s61
	s_bcnt1_i32_b64 s61, s[16:17]
	s_add_u32 s89, s89, s61
	s_bcnt1_i32_b64 s61, s[18:19]
	s_add_u32 s89, s89, s61
	s_bcnt1_i32_b64 s61, s[22:23]
	s_add_u32 s89, s89, s61
	s_bcnt1_i32_b64 s61, s[24:25]
	s_add_u32 s89, s89, s61
	s_bcnt1_i32_b64 s61, s[58:59]
	s_add_u32 s89, s89, s61
	s_cmp_ge_u32 s89, s91
	s_cselect_b32 s33, s57, s33
	s_cmp_eq_u32 s89, s91
	s_cbranch_scc1 .Lref_e8
	s_or_b32 s57, s33, 0x4
	v_cmp_ge_u32_e64 s[8:9], v216, s57
	v_cmp_ge_u32_e64 s[12:13], v217, s57
	v_cmp_ge_u32_e64 s[14:15], v218, s57
	v_cmp_ge_u32_e64 s[16:17], v219, s57
	v_cmp_ge_u32_e64 s[18:19], v220, s57
	v_cmp_ge_u32_e64 s[22:23], v221, s57
	v_cmp_ge_u32_e64 s[24:25], v222, s57
	v_cmp_ge_u32_e64 s[58:59], v223, s57
	s_bcnt1_i32_b64 s89, s[8:9]
	s_bcnt1_i32_b64 s61, s[12:13]
	s_add_u32 s89, s89, s61
	s_bcnt1_i32_b64 s61, s[14:15]
	s_add_u32 s89, s89, s61
	s_bcnt1_i32_b64 s61, s[16:17]
	s_add_u32 s89, s89, s61
	s_bcnt1_i32_b64 s61, s[18:19]
	s_add_u32 s89, s89, s61
	s_bcnt1_i32_b64 s61, s[22:23]
	s_add_u32 s89, s89, s61
	s_bcnt1_i32_b64 s61, s[24:25]
	s_add_u32 s89, s89, s61
	s_bcnt1_i32_b64 s61, s[58:59]
	s_add_u32 s89, s89, s61
	s_cmp_ge_u32 s89, s91
	s_cselect_b32 s33, s57, s33
	s_cmp_eq_u32 s89, s91
	s_cbranch_scc1 .Lref_e8
	s_or_b32 s57, s33, 0x2
	v_cmp_ge_u32_e64 s[8:9], v216, s57
	v_cmp_ge_u32_e64 s[12:13], v217, s57
	v_cmp_ge_u32_e64 s[14:15], v218, s57
	v_cmp_ge_u32_e64 s[16:17], v219, s57
	v_cmp_ge_u32_e64 s[18:19], v220, s57
	v_cmp_ge_u32_e64 s[22:23], v221, s57
	v_cmp_ge_u32_e64 s[24:25], v222, s57
	v_cmp_ge_u32_e64 s[58:59], v223, s57
	s_bcnt1_i32_b64 s89, s[8:9]
	s_bcnt1_i32_b64 s61, s[12:13]
	s_add_u32 s89, s89, s61
	s_bcnt1_i32_b64 s61, s[14:15]
	s_add_u32 s89, s89, s61
	s_bcnt1_i32_b64 s61, s[16:17]
	s_add_u32 s89, s89, s61
	s_bcnt1_i32_b64 s61, s[18:19]
	s_add_u32 s89, s89, s61
	s_bcnt1_i32_b64 s61, s[22:23]
	s_add_u32 s89, s89, s61
	s_bcnt1_i32_b64 s61, s[24:25]
	s_add_u32 s89, s89, s61
	s_bcnt1_i32_b64 s61, s[58:59]
	s_add_u32 s89, s89, s61
	s_cmp_ge_u32 s89, s91
	s_cselect_b32 s33, s57, s33
	s_cmp_eq_u32 s89, s91
	s_cbranch_scc1 .Lref_e8
	s_or_b32 s57, s33, 0x1
	v_cmp_ge_u32_e64 s[8:9], v216, s57
	v_cmp_ge_u32_e64 s[12:13], v217, s57
	v_cmp_ge_u32_e64 s[14:15], v218, s57
	v_cmp_ge_u32_e64 s[16:17], v219, s57
	v_cmp_ge_u32_e64 s[18:19], v220, s57
	v_cmp_ge_u32_e64 s[22:23], v221, s57
	v_cmp_ge_u32_e64 s[24:25], v222, s57
	v_cmp_ge_u32_e64 s[58:59], v223, s57
	s_bcnt1_i32_b64 s89, s[8:9]
	s_bcnt1_i32_b64 s61, s[12:13]
	s_add_u32 s89, s89, s61
	s_bcnt1_i32_b64 s61, s[14:15]
	s_add_u32 s89, s89, s61
	s_bcnt1_i32_b64 s61, s[16:17]
	s_add_u32 s89, s89, s61
	s_bcnt1_i32_b64 s61, s[18:19]
	s_add_u32 s89, s89, s61
	s_bcnt1_i32_b64 s61, s[22:23]
	s_add_u32 s89, s89, s61
	s_bcnt1_i32_b64 s61, s[24:25]
	s_add_u32 s89, s89, s61
	s_bcnt1_i32_b64 s61, s[58:59]
	s_add_u32 s89, s89, s61
	s_cmp_ge_u32 s89, s91
	s_cselect_b32 s33, s57, s33
	s_cmp_eq_u32 s89, s91
	s_cbranch_scc1 .Lref_e8
	v_cmp_gt_u32_e64 s[8:9], v216, s33
	v_cmp_gt_u32_e64 s[12:13], v217, s33
	v_cmp_gt_u32_e64 s[14:15], v218, s33
	v_cmp_gt_u32_e64 s[16:17], v219, s33
	v_cmp_gt_u32_e64 s[18:19], v220, s33
	v_cmp_gt_u32_e64 s[22:23], v221, s33
	v_cmp_gt_u32_e64 s[24:25], v222, s33
	v_cmp_gt_u32_e64 s[58:59], v223, s33
	s_bcnt1_i32_b64 s89, s[8:9]
	s_bcnt1_i32_b64 s61, s[12:13]
	s_add_u32 s89, s89, s61
	s_bcnt1_i32_b64 s61, s[14:15]
	s_add_u32 s89, s89, s61
	s_bcnt1_i32_b64 s61, s[16:17]
	s_add_u32 s89, s89, s61
	s_bcnt1_i32_b64 s61, s[18:19]
	s_add_u32 s89, s89, s61
	s_bcnt1_i32_b64 s61, s[22:23]
	s_add_u32 s89, s89, s61
	s_bcnt1_i32_b64 s61, s[24:25]
	s_add_u32 s89, s89, s61
	s_bcnt1_i32_b64 s61, s[58:59]
	s_add_u32 s89, s89, s61
	s_sub_u32 s91, s91, s89
	v_cmp_eq_u32_e64 s[8:9], v216, s33
	v_cmp_eq_u32_e64 s[12:13], v217, s33
	v_cmp_eq_u32_e64 s[14:15], v218, s33
	v_cmp_eq_u32_e64 s[16:17], v219, s33
	v_cmp_eq_u32_e64 s[18:19], v220, s33
	v_cmp_eq_u32_e64 s[22:23], v221, s33
	v_cmp_eq_u32_e64 s[24:25], v222, s33
	v_cmp_eq_u32_e64 s[58:59], v223, s33
	s_bcnt1_i32_b64 s89, s[8:9]
	s_bcnt1_i32_b64 s61, s[12:13]
	s_add_u32 s89, s89, s61
	s_bcnt1_i32_b64 s61, s[14:15]
	s_add_u32 s89, s89, s61
	s_bcnt1_i32_b64 s61, s[16:17]
	s_add_u32 s89, s89, s61
	s_bcnt1_i32_b64 s61, s[18:19]
	s_add_u32 s89, s89, s61
	s_bcnt1_i32_b64 s61, s[22:23]
	s_add_u32 s89, s89, s61
	s_bcnt1_i32_b64 s61, s[24:25]
	s_add_u32 s89, s89, s61
	s_bcnt1_i32_b64 s61, s[58:59]
	s_add_u32 s89, s89, s61
	s_add_u32 s57, s33, 1
	s_cmp_eq_u32 s91, s89
	s_cselect_b32 s57, s33, s57
	s_cselect_b32 s60, 1, 0
	s_branch .Lref_emit8
.Lref_e8:
	s_mov_b32 s60, 1
.Lref_emit8:
	v_cmp_ge_u32_e64 s[8:9], v216, s57
	v_cmp_ge_u32_e64 s[12:13], v217, s57
	v_cmp_ge_u32_e64 s[14:15], v218, s57
	v_cmp_ge_u32_e64 s[16:17], v219, s57
	v_cmp_ge_u32_e64 s[18:19], v220, s57
	v_cmp_ge_u32_e64 s[22:23], v221, s57
	v_cmp_ge_u32_e64 s[24:25], v222, s57
	v_cmp_ge_u32_e64 s[58:59], v223, s57
	s_nop 1
	v_mbcnt_lo_u32_b32 v241, s8, 0
	v_mbcnt_hi_u32_b32 v241, s9, v241
	v_add_u32_e32 v241, s90, v241
	v_and_b32_e32 v241, 0xff, v241
	v_lshl_add_u32 v241, v241, 1, v246
	s_mov_b64 exec, s[8:9]
	ds_write_b16 v241, v224
	s_mov_b64 exec, -1
	s_bcnt1_i32_b64 s61, s[8:9]
	s_add_u32 s90, s90, s61
	v_mbcnt_lo_u32_b32 v241, s12, 0
	v_mbcnt_hi_u32_b32 v241, s13, v241
	v_add_u32_e32 v241, s90, v241
	v_and_b32_e32 v241, 0xff, v241
	v_lshl_add_u32 v241, v241, 1, v246
	s_mov_b64 exec, s[12:13]
	ds_write_b16 v241, v225
	s_mov_b64 exec, -1
	s_bcnt1_i32_b64 s61, s[12:13]
	s_add_u32 s90, s90, s61
	v_mbcnt_lo_u32_b32 v241, s14, 0
	v_mbcnt_hi_u32_b32 v241, s15, v241
	v_add_u32_e32 v241, s90, v241
	v_and_b32_e32 v241, 0xff, v241
	v_lshl_add_u32 v241, v241, 1, v246
	s_mov_b64 exec, s[14:15]
	ds_write_b16 v241, v226
	s_mov_b64 exec, -1
	s_bcnt1_i32_b64 s61, s[14:15]
	s_add_u32 s90, s90, s61
	v_mbcnt_lo_u32_b32 v241, s16, 0
	v_mbcnt_hi_u32_b32 v241, s17, v241
	v_add_u32_e32 v241, s90, v241
	v_and_b32_e32 v241, 0xff, v241
	v_lshl_add_u32 v241, v241, 1, v246
	s_mov_b64 exec, s[16:17]
	ds_write_b16 v241, v227
	s_mov_b64 exec, -1
	s_bcnt1_i32_b64 s61, s[16:17]
	s_add_u32 s90, s90, s61
	v_mbcnt_lo_u32_b32 v241, s18, 0
	v_mbcnt_hi_u32_b32 v241, s19, v241
	v_add_u32_e32 v241, s90, v241
	v_and_b32_e32 v241, 0xff, v241
	v_lshl_add_u32 v241, v241, 1, v246
	s_mov_b64 exec, s[18:19]
	ds_write_b16 v241, v228
	s_mov_b64 exec, -1
	s_bcnt1_i32_b64 s61, s[18:19]
	s_add_u32 s90, s90, s61
	v_mbcnt_lo_u32_b32 v241, s22, 0
	v_mbcnt_hi_u32_b32 v241, s23, v241
	v_add_u32_e32 v241, s90, v241
	v_and_b32_e32 v241, 0xff, v241
	v_lshl_add_u32 v241, v241, 1, v246
	s_mov_b64 exec, s[22:23]
	ds_write_b16 v241, v229
	s_mov_b64 exec, -1
	s_bcnt1_i32_b64 s61, s[22:23]
	s_add_u32 s90, s90, s61
	v_mbcnt_lo_u32_b32 v241, s24, 0
	v_mbcnt_hi_u32_b32 v241, s25, v241
	v_add_u32_e32 v241, s90, v241
	v_and_b32_e32 v241, 0xff, v241
	v_lshl_add_u32 v241, v241, 1, v246
	s_mov_b64 exec, s[24:25]
	ds_write_b16 v241, v230
	s_mov_b64 exec, -1
	s_bcnt1_i32_b64 s61, s[24:25]
	s_add_u32 s90, s90, s61
	v_mbcnt_lo_u32_b32 v241, s58, 0
	v_mbcnt_hi_u32_b32 v241, s59, v241
	v_add_u32_e32 v241, s90, v241
	v_and_b32_e32 v241, 0xff, v241
	v_lshl_add_u32 v241, v241, 1, v246
	s_mov_b64 exec, s[58:59]
	ds_write_b16 v241, v231
	s_mov_b64 exec, -1
	s_bcnt1_i32_b64 s61, s[58:59]
	s_add_u32 s90, s90, s61
	s_mov_b32 s92, 0
	s_cmp_lg_u32 s60, 0
	s_cbranch_scc1 .Lref_fin
	v_cmp_eq_u32_e64 s[8:9], v216, s33
	v_cmp_eq_u32_e64 s[12:13], v217, s33
	v_cmp_eq_u32_e64 s[14:15], v218, s33
	v_cmp_eq_u32_e64 s[16:17], v219, s33
	v_cmp_eq_u32_e64 s[18:19], v220, s33
	v_cmp_eq_u32_e64 s[22:23], v221, s33
	v_cmp_eq_u32_e64 s[24:25], v222, s33
	v_cmp_eq_u32_e64 s[58:59], v223, s33
	s_nop 1
	v_mbcnt_lo_u32_b32 v241, s8, 0
	v_mbcnt_hi_u32_b32 v241, s9, v241
	v_add_u32_e32 v241, s92, v241
	v_lshl_add_u32 v241, v241, 1, v244
	s_mov_b64 exec, s[8:9]
	ds_write_b16 v241, v224
	s_mov_b64 exec, -1
	s_bcnt1_i32_b64 s61, s[8:9]
	s_add_u32 s92, s92, s61
	v_mbcnt_lo_u32_b32 v241, s12, 0
	v_mbcnt_hi_u32_b32 v241, s13, v241
	v_add_u32_e32 v241, s92, v241
	v_lshl_add_u32 v241, v241, 1, v244
	s_mov_b64 exec, s[12:13]
	ds_write_b16 v241, v225
	s_mov_b64 exec, -1
	s_bcnt1_i32_b64 s61, s[12:13]
	s_add_u32 s92, s92, s61
	v_mbcnt_lo_u32_b32 v241, s14, 0
	v_mbcnt_hi_u32_b32 v241, s15, v241
	v_add_u32_e32 v241, s92, v241
	v_lshl_add_u32 v241, v241, 1, v244
	s_mov_b64 exec, s[14:15]
	ds_write_b16 v241, v226
	s_mov_b64 exec, -1
	s_bcnt1_i32_b64 s61, s[14:15]
	s_add_u32 s92, s92, s61
	v_mbcnt_lo_u32_b32 v241, s16, 0
	v_mbcnt_hi_u32_b32 v241, s17, v241
	v_add_u32_e32 v241, s92, v241
	v_lshl_add_u32 v241, v241, 1, v244
	s_mov_b64 exec, s[16:17]
	ds_write_b16 v241, v227
	s_mov_b64 exec, -1
	s_bcnt1_i32_b64 s61, s[16:17]
	s_add_u32 s92, s92, s61
	v_mbcnt_lo_u32_b32 v241, s18, 0
	v_mbcnt_hi_u32_b32 v241, s19, v241
	v_add_u32_e32 v241, s92, v241
	v_lshl_add_u32 v241, v241, 1, v244
	s_mov_b64 exec, s[18:19]
	ds_write_b16 v241, v228
	s_mov_b64 exec, -1
	s_bcnt1_i32_b64 s61, s[18:19]
	s_add_u32 s92, s92, s61
	v_mbcnt_lo_u32_b32 v241, s22, 0
	v_mbcnt_hi_u32_b32 v241, s23, v241
	v_add_u32_e32 v241, s92, v241
	v_lshl_add_u32 v241, v241, 1, v244
	s_mov_b64 exec, s[22:23]
	ds_write_b16 v241, v229
	s_mov_b64 exec, -1
	s_bcnt1_i32_b64 s61, s[22:23]
	s_add_u32 s92, s92, s61
	v_mbcnt_lo_u32_b32 v241, s24, 0
	v_mbcnt_hi_u32_b32 v241, s25, v241
	v_add_u32_e32 v241, s92, v241
	v_lshl_add_u32 v241, v241, 1, v244
	s_mov_b64 exec, s[24:25]
	ds_write_b16 v241, v230
	s_mov_b64 exec, -1
	s_bcnt1_i32_b64 s61, s[24:25]
	s_add_u32 s92, s92, s61
	v_mbcnt_lo_u32_b32 v241, s58, 0
	v_mbcnt_hi_u32_b32 v241, s59, v241
	v_add_u32_e32 v241, s92, v241
	v_lshl_add_u32 v241, v241, 1, v244
	s_mov_b64 exec, s[58:59]
	ds_write_b16 v241, v231
	s_mov_b64 exec, -1
	s_bcnt1_i32_b64 s61, s[58:59]
	s_add_u32 s92, s92, s61
	s_branch .Lref_fin
.Lref_v7:
	ds_read_b32 v216, v238
	ds_read_u16 v224, v245
	ds_read_b32 v217, v238 offset:256
	ds_read_u16 v225, v245 offset:128
	ds_read_b32 v218, v238 offset:512
	ds_read_u16 v226, v245 offset:256
	ds_read_b32 v219, v238 offset:768
	ds_read_u16 v227, v245 offset:384
	ds_read_b32 v220, v238 offset:1024
	ds_read_u16 v228, v245 offset:512
	ds_read_b32 v221, v238 offset:1280
	ds_read_u16 v229, v245 offset:640
	ds_read_b32 v222, v238 offset:1536
	ds_read_u16 v230, v245 offset:768
	v_cmp_gt_u32_e64 s[8:9], s93, v145
	v_add_u32_e32 v241, 64, v145
	v_cmp_gt_u32_e64 s[12:13], s93, v241
	v_add_u32_e32 v241, 128, v145
	v_cmp_gt_u32_e64 s[14:15], s93, v241
	v_add_u32_e32 v241, 192, v145
	v_cmp_gt_u32_e64 s[16:17], s93, v241
	v_add_u32_e32 v241, 256, v145
	v_cmp_gt_u32_e64 s[18:19], s93, v241
	v_add_u32_e32 v241, 320, v145
	v_cmp_gt_u32_e64 s[22:23], s93, v241
	v_add_u32_e32 v241, 384, v145
	v_cmp_gt_u32_e64 s[24:25], s93, v241
	s_waitcnt lgkmcnt(0)
	v_cndmask_b32_e64 v216, 0, v216, s[8:9]
	v_cndmask_b32_e64 v217, 0, v217, s[12:13]
	v_cndmask_b32_e64 v218, 0, v218, s[14:15]
	v_cndmask_b32_e64 v219, 0, v219, s[16:17]
	v_cndmask_b32_e64 v220, 0, v220, s[18:19]
	v_cndmask_b32_e64 v221, 0, v221, s[22:23]
	v_cndmask_b32_e64 v222, 0, v222, s[24:25]
	s_or_b32 s57, s33, 0x100000
	v_cmp_ge_u32_e64 s[8:9], v216, s57
	v_cmp_ge_u32_e64 s[12:13], v217, s57
	v_cmp_ge_u32_e64 s[14:15], v218, s57
	v_cmp_ge_u32_e64 s[16:17], v219, s57
	v_cmp_ge_u32_e64 s[18:19], v220, s57
	v_cmp_ge_u32_e64 s[22:23], v221, s57
	v_cmp_ge_u32_e64 s[24:25], v222, s57
	s_bcnt1_i32_b64 s89, s[8:9]
	s_bcnt1_i32_b64 s61, s[12:13]
	s_add_u32 s89, s89, s61
	s_bcnt1_i32_b64 s61, s[14:15]
	s_add_u32 s89, s89, s61
	s_bcnt1_i32_b64 s61, s[16:17]
	s_add_u32 s89, s89, s61
	s_bcnt1_i32_b64 s61, s[18:19]
	s_add_u32 s89, s89, s61
	s_bcnt1_i32_b64 s61, s[22:23]
	s_add_u32 s89, s89, s61
	s_bcnt1_i32_b64 s61, s[24:25]
	s_add_u32 s89, s89, s61
	s_cmp_ge_u32 s89, s91
	s_cselect_b32 s33, s57, s33
	s_cmp_eq_u32 s89, s91
	s_cbranch_scc1 .Lref_e7
	s_or_b32 s57, s33, 0x80000
	v_cmp_ge_u32_e64 s[8:9], v216, s57
	v_cmp_ge_u32_e64 s[12:13], v217, s57
	v_cmp_ge_u32_e64 s[14:15], v218, s57
	v_cmp_ge_u32_e64 s[16:17], v219, s57
	v_cmp_ge_u32_e64 s[18:19], v220, s57
	v_cmp_ge_u32_e64 s[22:23], v221, s57
	v_cmp_ge_u32_e64 s[24:25], v222, s57
	s_bcnt1_i32_b64 s89, s[8:9]
	s_bcnt1_i32_b64 s61, s[12:13]
	s_add_u32 s89, s89, s61
	s_bcnt1_i32_b64 s61, s[14:15]
	s_add_u32 s89, s89, s61
	s_bcnt1_i32_b64 s61, s[16:17]
	s_add_u32 s89, s89, s61
	s_bcnt1_i32_b64 s61, s[18:19]
	s_add_u32 s89, s89, s61
	s_bcnt1_i32_b64 s61, s[22:23]
	s_add_u32 s89, s89, s61
	s_bcnt1_i32_b64 s61, s[24:25]
	s_add_u32 s89, s89, s61
	s_cmp_ge_u32 s89, s91
	s_cselect_b32 s33, s57, s33
	s_cmp_eq_u32 s89, s91
	s_cbranch_scc1 .Lref_e7
	s_or_b32 s57, s33, 0x40000
	v_cmp_ge_u32_e64 s[8:9], v216, s57
	v_cmp_ge_u32_e64 s[12:13], v217, s57
	v_cmp_ge_u32_e64 s[14:15], v218, s57
	v_cmp_ge_u32_e64 s[16:17], v219, s57
	v_cmp_ge_u32_e64 s[18:19], v220, s57
	v_cmp_ge_u32_e64 s[22:23], v221, s57
	v_cmp_ge_u32_e64 s[24:25], v222, s57
	s_bcnt1_i32_b64 s89, s[8:9]
	s_bcnt1_i32_b64 s61, s[12:13]
	s_add_u32 s89, s89, s61
	s_bcnt1_i32_b64 s61, s[14:15]
	s_add_u32 s89, s89, s61
	s_bcnt1_i32_b64 s61, s[16:17]
	s_add_u32 s89, s89, s61
	s_bcnt1_i32_b64 s61, s[18:19]
	s_add_u32 s89, s89, s61
	s_bcnt1_i32_b64 s61, s[22:23]
	s_add_u32 s89, s89, s61
	s_bcnt1_i32_b64 s61, s[24:25]
	s_add_u32 s89, s89, s61
	s_cmp_ge_u32 s89, s91
	s_cselect_b32 s33, s57, s33
	s_cmp_eq_u32 s89, s91
	s_cbranch_scc1 .Lref_e7
	s_or_b32 s57, s33, 0x20000
	v_cmp_ge_u32_e64 s[8:9], v216, s57
	v_cmp_ge_u32_e64 s[12:13], v217, s57
	v_cmp_ge_u32_e64 s[14:15], v218, s57
	v_cmp_ge_u32_e64 s[16:17], v219, s57
	v_cmp_ge_u32_e64 s[18:19], v220, s57
	v_cmp_ge_u32_e64 s[22:23], v221, s57
	v_cmp_ge_u32_e64 s[24:25], v222, s57
	s_bcnt1_i32_b64 s89, s[8:9]
	s_bcnt1_i32_b64 s61, s[12:13]
	s_add_u32 s89, s89, s61
	s_bcnt1_i32_b64 s61, s[14:15]
	s_add_u32 s89, s89, s61
	s_bcnt1_i32_b64 s61, s[16:17]
	s_add_u32 s89, s89, s61
	s_bcnt1_i32_b64 s61, s[18:19]
	s_add_u32 s89, s89, s61
	s_bcnt1_i32_b64 s61, s[22:23]
	s_add_u32 s89, s89, s61
	s_bcnt1_i32_b64 s61, s[24:25]
	s_add_u32 s89, s89, s61
	s_cmp_ge_u32 s89, s91
	s_cselect_b32 s33, s57, s33
	s_cmp_eq_u32 s89, s91
	s_cbranch_scc1 .Lref_e7
	s_or_b32 s57, s33, 0x10000
	v_cmp_ge_u32_e64 s[8:9], v216, s57
	v_cmp_ge_u32_e64 s[12:13], v217, s57
	v_cmp_ge_u32_e64 s[14:15], v218, s57
	v_cmp_ge_u32_e64 s[16:17], v219, s57
	v_cmp_ge_u32_e64 s[18:19], v220, s57
	v_cmp_ge_u32_e64 s[22:23], v221, s57
	v_cmp_ge_u32_e64 s[24:25], v222, s57
	s_bcnt1_i32_b64 s89, s[8:9]
	s_bcnt1_i32_b64 s61, s[12:13]
	s_add_u32 s89, s89, s61
	s_bcnt1_i32_b64 s61, s[14:15]
	s_add_u32 s89, s89, s61
	s_bcnt1_i32_b64 s61, s[16:17]
	s_add_u32 s89, s89, s61
	s_bcnt1_i32_b64 s61, s[18:19]
	s_add_u32 s89, s89, s61
	s_bcnt1_i32_b64 s61, s[22:23]
	s_add_u32 s89, s89, s61
	s_bcnt1_i32_b64 s61, s[24:25]
	s_add_u32 s89, s89, s61
	s_cmp_ge_u32 s89, s91
	s_cselect_b32 s33, s57, s33
	s_cmp_eq_u32 s89, s91
	s_cbranch_scc1 .Lref_e7
	s_or_b32 s57, s33, 0x8000
	v_cmp_ge_u32_e64 s[8:9], v216, s57
	v_cmp_ge_u32_e64 s[12:13], v217, s57
	v_cmp_ge_u32_e64 s[14:15], v218, s57
	v_cmp_ge_u32_e64 s[16:17], v219, s57
	v_cmp_ge_u32_e64 s[18:19], v220, s57
	v_cmp_ge_u32_e64 s[22:23], v221, s57
	v_cmp_ge_u32_e64 s[24:25], v222, s57
	s_bcnt1_i32_b64 s89, s[8:9]
	s_bcnt1_i32_b64 s61, s[12:13]
	s_add_u32 s89, s89, s61
	s_bcnt1_i32_b64 s61, s[14:15]
	s_add_u32 s89, s89, s61
	s_bcnt1_i32_b64 s61, s[16:17]
	s_add_u32 s89, s89, s61
	s_bcnt1_i32_b64 s61, s[18:19]
	s_add_u32 s89, s89, s61
	s_bcnt1_i32_b64 s61, s[22:23]
	s_add_u32 s89, s89, s61
	s_bcnt1_i32_b64 s61, s[24:25]
	s_add_u32 s89, s89, s61
	s_cmp_ge_u32 s89, s91
	s_cselect_b32 s33, s57, s33
	s_cmp_eq_u32 s89, s91
	s_cbranch_scc1 .Lref_e7
	s_or_b32 s57, s33, 0x4000
	v_cmp_ge_u32_e64 s[8:9], v216, s57
	v_cmp_ge_u32_e64 s[12:13], v217, s57
	v_cmp_ge_u32_e64 s[14:15], v218, s57
	v_cmp_ge_u32_e64 s[16:17], v219, s57
	v_cmp_ge_u32_e64 s[18:19], v220, s57
	v_cmp_ge_u32_e64 s[22:23], v221, s57
	v_cmp_ge_u32_e64 s[24:25], v222, s57
	s_bcnt1_i32_b64 s89, s[8:9]
	s_bcnt1_i32_b64 s61, s[12:13]
	s_add_u32 s89, s89, s61
	s_bcnt1_i32_b64 s61, s[14:15]
	s_add_u32 s89, s89, s61
	s_bcnt1_i32_b64 s61, s[16:17]
	s_add_u32 s89, s89, s61
	s_bcnt1_i32_b64 s61, s[18:19]
	s_add_u32 s89, s89, s61
	s_bcnt1_i32_b64 s61, s[22:23]
	s_add_u32 s89, s89, s61
	s_bcnt1_i32_b64 s61, s[24:25]
	s_add_u32 s89, s89, s61
	s_cmp_ge_u32 s89, s91
	s_cselect_b32 s33, s57, s33
	s_cmp_eq_u32 s89, s91
	s_cbranch_scc1 .Lref_e7
	s_or_b32 s57, s33, 0x2000
	v_cmp_ge_u32_e64 s[8:9], v216, s57
	v_cmp_ge_u32_e64 s[12:13], v217, s57
	v_cmp_ge_u32_e64 s[14:15], v218, s57
	v_cmp_ge_u32_e64 s[16:17], v219, s57
	v_cmp_ge_u32_e64 s[18:19], v220, s57
	v_cmp_ge_u32_e64 s[22:23], v221, s57
	v_cmp_ge_u32_e64 s[24:25], v222, s57
	s_bcnt1_i32_b64 s89, s[8:9]
	s_bcnt1_i32_b64 s61, s[12:13]
	s_add_u32 s89, s89, s61
	s_bcnt1_i32_b64 s61, s[14:15]
	s_add_u32 s89, s89, s61
	s_bcnt1_i32_b64 s61, s[16:17]
	s_add_u32 s89, s89, s61
	s_bcnt1_i32_b64 s61, s[18:19]
	s_add_u32 s89, s89, s61
	s_bcnt1_i32_b64 s61, s[22:23]
	s_add_u32 s89, s89, s61
	s_bcnt1_i32_b64 s61, s[24:25]
	s_add_u32 s89, s89, s61
	s_cmp_ge_u32 s89, s91
	s_cselect_b32 s33, s57, s33
	s_cmp_eq_u32 s89, s91
	s_cbranch_scc1 .Lref_e7
	s_or_b32 s57, s33, 0x1000
	v_cmp_ge_u32_e64 s[8:9], v216, s57
	v_cmp_ge_u32_e64 s[12:13], v217, s57
	v_cmp_ge_u32_e64 s[14:15], v218, s57
	v_cmp_ge_u32_e64 s[16:17], v219, s57
	v_cmp_ge_u32_e64 s[18:19], v220, s57
	v_cmp_ge_u32_e64 s[22:23], v221, s57
	v_cmp_ge_u32_e64 s[24:25], v222, s57
	s_bcnt1_i32_b64 s89, s[8:9]
	s_bcnt1_i32_b64 s61, s[12:13]
	s_add_u32 s89, s89, s61
	s_bcnt1_i32_b64 s61, s[14:15]
	s_add_u32 s89, s89, s61
	s_bcnt1_i32_b64 s61, s[16:17]
	s_add_u32 s89, s89, s61
	s_bcnt1_i32_b64 s61, s[18:19]
	s_add_u32 s89, s89, s61
	s_bcnt1_i32_b64 s61, s[22:23]
	s_add_u32 s89, s89, s61
	s_bcnt1_i32_b64 s61, s[24:25]
	s_add_u32 s89, s89, s61
	s_cmp_ge_u32 s89, s91
	s_cselect_b32 s33, s57, s33
	s_cmp_eq_u32 s89, s91
	s_cbranch_scc1 .Lref_e7
	s_or_b32 s57, s33, 0x800
	v_cmp_ge_u32_e64 s[8:9], v216, s57
	v_cmp_ge_u32_e64 s[12:13], v217, s57
	v_cmp_ge_u32_e64 s[14:15], v218, s57
	v_cmp_ge_u32_e64 s[16:17], v219, s57
	v_cmp_ge_u32_e64 s[18:19], v220, s57
	v_cmp_ge_u32_e64 s[22:23], v221, s57
	v_cmp_ge_u32_e64 s[24:25], v222, s57
	s_bcnt1_i32_b64 s89, s[8:9]
	s_bcnt1_i32_b64 s61, s[12:13]
	s_add_u32 s89, s89, s61
	s_bcnt1_i32_b64 s61, s[14:15]
	s_add_u32 s89, s89, s61
	s_bcnt1_i32_b64 s61, s[16:17]
	s_add_u32 s89, s89, s61
	s_bcnt1_i32_b64 s61, s[18:19]
	s_add_u32 s89, s89, s61
	s_bcnt1_i32_b64 s61, s[22:23]
	s_add_u32 s89, s89, s61
	s_bcnt1_i32_b64 s61, s[24:25]
	s_add_u32 s89, s89, s61
	s_cmp_ge_u32 s89, s91
	s_cselect_b32 s33, s57, s33
	s_cmp_eq_u32 s89, s91
	s_cbranch_scc1 .Lref_e7
	s_or_b32 s57, s33, 0x400
	v_cmp_ge_u32_e64 s[8:9], v216, s57
	v_cmp_ge_u32_e64 s[12:13], v217, s57
	v_cmp_ge_u32_e64 s[14:15], v218, s57
	v_cmp_ge_u32_e64 s[16:17], v219, s57
	v_cmp_ge_u32_e64 s[18:19], v220, s57
	v_cmp_ge_u32_e64 s[22:23], v221, s57
	v_cmp_ge_u32_e64 s[24:25], v222, s57
	s_bcnt1_i32_b64 s89, s[8:9]
	s_bcnt1_i32_b64 s61, s[12:13]
	s_add_u32 s89, s89, s61
	s_bcnt1_i32_b64 s61, s[14:15]
	s_add_u32 s89, s89, s61
	s_bcnt1_i32_b64 s61, s[16:17]
	s_add_u32 s89, s89, s61
	s_bcnt1_i32_b64 s61, s[18:19]
	s_add_u32 s89, s89, s61
	s_bcnt1_i32_b64 s61, s[22:23]
	s_add_u32 s89, s89, s61
	s_bcnt1_i32_b64 s61, s[24:25]
	s_add_u32 s89, s89, s61
	s_cmp_ge_u32 s89, s91
	s_cselect_b32 s33, s57, s33
	s_cmp_eq_u32 s89, s91
	s_cbranch_scc1 .Lref_e7
	s_or_b32 s57, s33, 0x200
	v_cmp_ge_u32_e64 s[8:9], v216, s57
	v_cmp_ge_u32_e64 s[12:13], v217, s57
	v_cmp_ge_u32_e64 s[14:15], v218, s57
	v_cmp_ge_u32_e64 s[16:17], v219, s57
	v_cmp_ge_u32_e64 s[18:19], v220, s57
	v_cmp_ge_u32_e64 s[22:23], v221, s57
	v_cmp_ge_u32_e64 s[24:25], v222, s57
	s_bcnt1_i32_b64 s89, s[8:9]
	s_bcnt1_i32_b64 s61, s[12:13]
	s_add_u32 s89, s89, s61
	s_bcnt1_i32_b64 s61, s[14:15]
	s_add_u32 s89, s89, s61
	s_bcnt1_i32_b64 s61, s[16:17]
	s_add_u32 s89, s89, s61
	s_bcnt1_i32_b64 s61, s[18:19]
	s_add_u32 s89, s89, s61
	s_bcnt1_i32_b64 s61, s[22:23]
	s_add_u32 s89, s89, s61
	s_bcnt1_i32_b64 s61, s[24:25]
	s_add_u32 s89, s89, s61
	s_cmp_ge_u32 s89, s91
	s_cselect_b32 s33, s57, s33
	s_cmp_eq_u32 s89, s91
	s_cbranch_scc1 .Lref_e7
	s_or_b32 s57, s33, 0x100
	v_cmp_ge_u32_e64 s[8:9], v216, s57
	v_cmp_ge_u32_e64 s[12:13], v217, s57
	v_cmp_ge_u32_e64 s[14:15], v218, s57
	v_cmp_ge_u32_e64 s[16:17], v219, s57
	v_cmp_ge_u32_e64 s[18:19], v220, s57
	v_cmp_ge_u32_e64 s[22:23], v221, s57
	v_cmp_ge_u32_e64 s[24:25], v222, s57
	s_bcnt1_i32_b64 s89, s[8:9]
	s_bcnt1_i32_b64 s61, s[12:13]
	s_add_u32 s89, s89, s61
	s_bcnt1_i32_b64 s61, s[14:15]
	s_add_u32 s89, s89, s61
	s_bcnt1_i32_b64 s61, s[16:17]
	s_add_u32 s89, s89, s61
	s_bcnt1_i32_b64 s61, s[18:19]
	s_add_u32 s89, s89, s61
	s_bcnt1_i32_b64 s61, s[22:23]
	s_add_u32 s89, s89, s61
	s_bcnt1_i32_b64 s61, s[24:25]
	s_add_u32 s89, s89, s61
	s_cmp_ge_u32 s89, s91
	s_cselect_b32 s33, s57, s33
	s_cmp_eq_u32 s89, s91
	s_cbranch_scc1 .Lref_e7
	s_or_b32 s57, s33, 0x80
	v_cmp_ge_u32_e64 s[8:9], v216, s57
	v_cmp_ge_u32_e64 s[12:13], v217, s57
	v_cmp_ge_u32_e64 s[14:15], v218, s57
	v_cmp_ge_u32_e64 s[16:17], v219, s57
	v_cmp_ge_u32_e64 s[18:19], v220, s57
	v_cmp_ge_u32_e64 s[22:23], v221, s57
	v_cmp_ge_u32_e64 s[24:25], v222, s57
	s_bcnt1_i32_b64 s89, s[8:9]
	s_bcnt1_i32_b64 s61, s[12:13]
	s_add_u32 s89, s89, s61
	s_bcnt1_i32_b64 s61, s[14:15]
	s_add_u32 s89, s89, s61
	s_bcnt1_i32_b64 s61, s[16:17]
	s_add_u32 s89, s89, s61
	s_bcnt1_i32_b64 s61, s[18:19]
	s_add_u32 s89, s89, s61
	s_bcnt1_i32_b64 s61, s[22:23]
	s_add_u32 s89, s89, s61
	s_bcnt1_i32_b64 s61, s[24:25]
	s_add_u32 s89, s89, s61
	s_cmp_ge_u32 s89, s91
	s_cselect_b32 s33, s57, s33
	s_cmp_eq_u32 s89, s91
	s_cbranch_scc1 .Lref_e7
	s_or_b32 s57, s33, 0x40
	v_cmp_ge_u32_e64 s[8:9], v216, s57
	v_cmp_ge_u32_e64 s[12:13], v217, s57
	v_cmp_ge_u32_e64 s[14:15], v218, s57
	v_cmp_ge_u32_e64 s[16:17], v219, s57
	v_cmp_ge_u32_e64 s[18:19], v220, s57
	v_cmp_ge_u32_e64 s[22:23], v221, s57
	v_cmp_ge_u32_e64 s[24:25], v222, s57
	s_bcnt1_i32_b64 s89, s[8:9]
	s_bcnt1_i32_b64 s61, s[12:13]
	s_add_u32 s89, s89, s61
	s_bcnt1_i32_b64 s61, s[14:15]
	s_add_u32 s89, s89, s61
	s_bcnt1_i32_b64 s61, s[16:17]
	s_add_u32 s89, s89, s61
	s_bcnt1_i32_b64 s61, s[18:19]
	s_add_u32 s89, s89, s61
	s_bcnt1_i32_b64 s61, s[22:23]
	s_add_u32 s89, s89, s61
	s_bcnt1_i32_b64 s61, s[24:25]
	s_add_u32 s89, s89, s61
	s_cmp_ge_u32 s89, s91
	s_cselect_b32 s33, s57, s33
	s_cmp_eq_u32 s89, s91
	s_cbranch_scc1 .Lref_e7
	s_or_b32 s57, s33, 0x20
	v_cmp_ge_u32_e64 s[8:9], v216, s57
	v_cmp_ge_u32_e64 s[12:13], v217, s57
	v_cmp_ge_u32_e64 s[14:15], v218, s57
	v_cmp_ge_u32_e64 s[16:17], v219, s57
	v_cmp_ge_u32_e64 s[18:19], v220, s57
	v_cmp_ge_u32_e64 s[22:23], v221, s57
	v_cmp_ge_u32_e64 s[24:25], v222, s57
	s_bcnt1_i32_b64 s89, s[8:9]
	s_bcnt1_i32_b64 s61, s[12:13]
	s_add_u32 s89, s89, s61
	s_bcnt1_i32_b64 s61, s[14:15]
	s_add_u32 s89, s89, s61
	s_bcnt1_i32_b64 s61, s[16:17]
	s_add_u32 s89, s89, s61
	s_bcnt1_i32_b64 s61, s[18:19]
	s_add_u32 s89, s89, s61
	s_bcnt1_i32_b64 s61, s[22:23]
	s_add_u32 s89, s89, s61
	s_bcnt1_i32_b64 s61, s[24:25]
	s_add_u32 s89, s89, s61
	s_cmp_ge_u32 s89, s91
	s_cselect_b32 s33, s57, s33
	s_cmp_eq_u32 s89, s91
	s_cbranch_scc1 .Lref_e7
	s_or_b32 s57, s33, 0x10
	v_cmp_ge_u32_e64 s[8:9], v216, s57
	v_cmp_ge_u32_e64 s[12:13], v217, s57
	v_cmp_ge_u32_e64 s[14:15], v218, s57
	v_cmp_ge_u32_e64 s[16:17], v219, s57
	v_cmp_ge_u32_e64 s[18:19], v220, s57
	v_cmp_ge_u32_e64 s[22:23], v221, s57
	v_cmp_ge_u32_e64 s[24:25], v222, s57
	s_bcnt1_i32_b64 s89, s[8:9]
	s_bcnt1_i32_b64 s61, s[12:13]
	s_add_u32 s89, s89, s61
	s_bcnt1_i32_b64 s61, s[14:15]
	s_add_u32 s89, s89, s61
	s_bcnt1_i32_b64 s61, s[16:17]
	s_add_u32 s89, s89, s61
	s_bcnt1_i32_b64 s61, s[18:19]
	s_add_u32 s89, s89, s61
	s_bcnt1_i32_b64 s61, s[22:23]
	s_add_u32 s89, s89, s61
	s_bcnt1_i32_b64 s61, s[24:25]
	s_add_u32 s89, s89, s61
	s_cmp_ge_u32 s89, s91
	s_cselect_b32 s33, s57, s33
	s_cmp_eq_u32 s89, s91
	s_cbranch_scc1 .Lref_e7
	s_or_b32 s57, s33, 0x8
	v_cmp_ge_u32_e64 s[8:9], v216, s57
	v_cmp_ge_u32_e64 s[12:13], v217, s57
	v_cmp_ge_u32_e64 s[14:15], v218, s57
	v_cmp_ge_u32_e64 s[16:17], v219, s57
	v_cmp_ge_u32_e64 s[18:19], v220, s57
	v_cmp_ge_u32_e64 s[22:23], v221, s57
	v_cmp_ge_u32_e64 s[24:25], v222, s57
	s_bcnt1_i32_b64 s89, s[8:9]
	s_bcnt1_i32_b64 s61, s[12:13]
	s_add_u32 s89, s89, s61
	s_bcnt1_i32_b64 s61, s[14:15]
	s_add_u32 s89, s89, s61
	s_bcnt1_i32_b64 s61, s[16:17]
	s_add_u32 s89, s89, s61
	s_bcnt1_i32_b64 s61, s[18:19]
	s_add_u32 s89, s89, s61
	s_bcnt1_i32_b64 s61, s[22:23]
	s_add_u32 s89, s89, s61
	s_bcnt1_i32_b64 s61, s[24:25]
	s_add_u32 s89, s89, s61
	s_cmp_ge_u32 s89, s91
	s_cselect_b32 s33, s57, s33
	s_cmp_eq_u32 s89, s91
	s_cbranch_scc1 .Lref_e7
	s_or_b32 s57, s33, 0x4
	v_cmp_ge_u32_e64 s[8:9], v216, s57
	v_cmp_ge_u32_e64 s[12:13], v217, s57
	v_cmp_ge_u32_e64 s[14:15], v218, s57
	v_cmp_ge_u32_e64 s[16:17], v219, s57
	v_cmp_ge_u32_e64 s[18:19], v220, s57
	v_cmp_ge_u32_e64 s[22:23], v221, s57
	v_cmp_ge_u32_e64 s[24:25], v222, s57
	s_bcnt1_i32_b64 s89, s[8:9]
	s_bcnt1_i32_b64 s61, s[12:13]
	s_add_u32 s89, s89, s61
	s_bcnt1_i32_b64 s61, s[14:15]
	s_add_u32 s89, s89, s61
	s_bcnt1_i32_b64 s61, s[16:17]
	s_add_u32 s89, s89, s61
	s_bcnt1_i32_b64 s61, s[18:19]
	s_add_u32 s89, s89, s61
	s_bcnt1_i32_b64 s61, s[22:23]
	s_add_u32 s89, s89, s61
	s_bcnt1_i32_b64 s61, s[24:25]
	s_add_u32 s89, s89, s61
	s_cmp_ge_u32 s89, s91
	s_cselect_b32 s33, s57, s33
	s_cmp_eq_u32 s89, s91
	s_cbranch_scc1 .Lref_e7
	s_or_b32 s57, s33, 0x2
	v_cmp_ge_u32_e64 s[8:9], v216, s57
	v_cmp_ge_u32_e64 s[12:13], v217, s57
	v_cmp_ge_u32_e64 s[14:15], v218, s57
	v_cmp_ge_u32_e64 s[16:17], v219, s57
	v_cmp_ge_u32_e64 s[18:19], v220, s57
	v_cmp_ge_u32_e64 s[22:23], v221, s57
	v_cmp_ge_u32_e64 s[24:25], v222, s57
	s_bcnt1_i32_b64 s89, s[8:9]
	s_bcnt1_i32_b64 s61, s[12:13]
	s_add_u32 s89, s89, s61
	s_bcnt1_i32_b64 s61, s[14:15]
	s_add_u32 s89, s89, s61
	s_bcnt1_i32_b64 s61, s[16:17]
	s_add_u32 s89, s89, s61
	s_bcnt1_i32_b64 s61, s[18:19]
	s_add_u32 s89, s89, s61
	s_bcnt1_i32_b64 s61, s[22:23]
	s_add_u32 s89, s89, s61
	s_bcnt1_i32_b64 s61, s[24:25]
	s_add_u32 s89, s89, s61
	s_cmp_ge_u32 s89, s91
	s_cselect_b32 s33, s57, s33
	s_cmp_eq_u32 s89, s91
	s_cbranch_scc1 .Lref_e7
	s_or_b32 s57, s33, 0x1
	v_cmp_ge_u32_e64 s[8:9], v216, s57
	v_cmp_ge_u32_e64 s[12:13], v217, s57
	v_cmp_ge_u32_e64 s[14:15], v218, s57
	v_cmp_ge_u32_e64 s[16:17], v219, s57
	v_cmp_ge_u32_e64 s[18:19], v220, s57
	v_cmp_ge_u32_e64 s[22:23], v221, s57
	v_cmp_ge_u32_e64 s[24:25], v222, s57
	s_bcnt1_i32_b64 s89, s[8:9]
	s_bcnt1_i32_b64 s61, s[12:13]
	s_add_u32 s89, s89, s61
	s_bcnt1_i32_b64 s61, s[14:15]
	s_add_u32 s89, s89, s61
	s_bcnt1_i32_b64 s61, s[16:17]
	s_add_u32 s89, s89, s61
	s_bcnt1_i32_b64 s61, s[18:19]
	s_add_u32 s89, s89, s61
	s_bcnt1_i32_b64 s61, s[22:23]
	s_add_u32 s89, s89, s61
	s_bcnt1_i32_b64 s61, s[24:25]
	s_add_u32 s89, s89, s61
	s_cmp_ge_u32 s89, s91
	s_cselect_b32 s33, s57, s33
	s_cmp_eq_u32 s89, s91
	s_cbranch_scc1 .Lref_e7
	v_cmp_gt_u32_e64 s[8:9], v216, s33
	v_cmp_gt_u32_e64 s[12:13], v217, s33
	v_cmp_gt_u32_e64 s[14:15], v218, s33
	v_cmp_gt_u32_e64 s[16:17], v219, s33
	v_cmp_gt_u32_e64 s[18:19], v220, s33
	v_cmp_gt_u32_e64 s[22:23], v221, s33
	v_cmp_gt_u32_e64 s[24:25], v222, s33
	s_bcnt1_i32_b64 s89, s[8:9]
	s_bcnt1_i32_b64 s61, s[12:13]
	s_add_u32 s89, s89, s61
	s_bcnt1_i32_b64 s61, s[14:15]
	s_add_u32 s89, s89, s61
	s_bcnt1_i32_b64 s61, s[16:17]
	s_add_u32 s89, s89, s61
	s_bcnt1_i32_b64 s61, s[18:19]
	s_add_u32 s89, s89, s61
	s_bcnt1_i32_b64 s61, s[22:23]
	s_add_u32 s89, s89, s61
	s_bcnt1_i32_b64 s61, s[24:25]
	s_add_u32 s89, s89, s61
	s_sub_u32 s91, s91, s89
	v_cmp_eq_u32_e64 s[8:9], v216, s33
	v_cmp_eq_u32_e64 s[12:13], v217, s33
	v_cmp_eq_u32_e64 s[14:15], v218, s33
	v_cmp_eq_u32_e64 s[16:17], v219, s33
	v_cmp_eq_u32_e64 s[18:19], v220, s33
	v_cmp_eq_u32_e64 s[22:23], v221, s33
	v_cmp_eq_u32_e64 s[24:25], v222, s33
	s_bcnt1_i32_b64 s89, s[8:9]
	s_bcnt1_i32_b64 s61, s[12:13]
	s_add_u32 s89, s89, s61
	s_bcnt1_i32_b64 s61, s[14:15]
	s_add_u32 s89, s89, s61
	s_bcnt1_i32_b64 s61, s[16:17]
	s_add_u32 s89, s89, s61
	s_bcnt1_i32_b64 s61, s[18:19]
	s_add_u32 s89, s89, s61
	s_bcnt1_i32_b64 s61, s[22:23]
	s_add_u32 s89, s89, s61
	s_bcnt1_i32_b64 s61, s[24:25]
	s_add_u32 s89, s89, s61
	s_add_u32 s57, s33, 1
	s_cmp_eq_u32 s91, s89
	s_cselect_b32 s57, s33, s57
	s_cselect_b32 s60, 1, 0
	s_branch .Lref_emit7

.Lref_emit7:
	v_cmp_ge_u32_e64 s[8:9], v216, s57
	v_cmp_ge_u32_e64 s[12:13], v217, s57
	v_cmp_ge_u32_e64 s[14:15], v218, s57
	v_cmp_ge_u32_e64 s[16:17], v219, s57
	v_cmp_ge_u32_e64 s[18:19], v220, s57
	v_cmp_ge_u32_e64 s[22:23], v221, s57
	v_cmp_ge_u32_e64 s[24:25], v222, s57
	s_nop 1
	v_mbcnt_lo_u32_b32 v241, s8, 0
	v_mbcnt_hi_u32_b32 v241, s9, v241
	v_add_u32_e32 v241, s90, v241
	v_and_b32_e32 v241, 0xff, v241
	v_lshl_add_u32 v241, v241, 1, v246
	s_mov_b64 exec, s[8:9]
	ds_write_b16 v241, v224
	s_mov_b64 exec, -1
	s_bcnt1_i32_b64 s61, s[8:9]
	s_add_u32 s90, s90, s61
	v_mbcnt_lo_u32_b32 v241, s12, 0
	v_mbcnt_hi_u32_b32 v241, s13, v241
	v_add_u32_e32 v241, s90, v241
	v_and_b32_e32 v241, 0xff, v241
	v_lshl_add_u32 v241, v241, 1, v246
	s_mov_b64 exec, s[12:13]
	ds_write_b16 v241, v225
	s_mov_b64 exec, -1
	s_bcnt1_i32_b64 s61, s[12:13]
	s_add_u32 s90, s90, s61
	v_mbcnt_lo_u32_b32 v241, s14, 0
	v_mbcnt_hi_u32_b32 v241, s15, v241
	v_add_u32_e32 v241, s90, v241
	v_and_b32_e32 v241, 0xff, v241
	v_lshl_add_u32 v241, v241, 1, v246
	s_mov_b64 exec, s[14:15]
	ds_write_b16 v241, v226
	s_mov_b64 exec, -1
	s_bcnt1_i32_b64 s61, s[14:15]
	s_add_u32 s90, s90, s61
	v_mbcnt_lo_u32_b32 v241, s16, 0
	v_mbcnt_hi_u32_b32 v241, s17, v241
	v_add_u32_e32 v241, s90, v241
	v_and_b32_e32 v241, 0xff, v241
	v_lshl_add_u32 v241, v241, 1, v246
	s_mov_b64 exec, s[16:17]
	ds_write_b16 v241, v227
	s_mov_b64 exec, -1
	s_bcnt1_i32_b64 s61, s[16:17]
	s_add_u32 s90, s90, s61
	v_mbcnt_lo_u32_b32 v241, s18, 0
	v_mbcnt_hi_u32_b32 v241, s19, v241
	v_add_u32_e32 v241, s90, v241
	v_and_b32_e32 v241, 0xff, v241
	v_lshl_add_u32 v241, v241, 1, v246
	s_mov_b64 exec, s[18:19]
	ds_write_b16 v241, v228
	s_mov_b64 exec, -1
	s_bcnt1_i32_b64 s61, s[18:19]
	s_add_u32 s90, s90, s61
	v_mbcnt_lo_u32_b32 v241, s22, 0
	v_mbcnt_hi_u32_b32 v241, s23, v241
	v_add_u32_e32 v241, s90, v241
	v_and_b32_e32 v241, 0xff, v241
	v_lshl_add_u32 v241, v241, 1, v246
	s_mov_b64 exec, s[22:23]
	ds_write_b16 v241, v229
	s_mov_b64 exec, -1
	s_bcnt1_i32_b64 s61, s[22:23]
	s_add_u32 s90, s90, s61
	v_mbcnt_lo_u32_b32 v241, s24, 0
	v_mbcnt_hi_u32_b32 v241, s25, v241
	v_add_u32_e32 v241, s90, v241
	v_and_b32_e32 v241, 0xff, v241
	v_lshl_add_u32 v241, v241, 1, v246
	s_mov_b64 exec, s[24:25]
	ds_write_b16 v241, v230
	s_mov_b64 exec, -1
	s_bcnt1_i32_b64 s61, s[24:25]
	s_add_u32 s90, s90, s61
	s_mov_b32 s92, 0
	s_cmp_lg_u32 s60, 0
	s_cbranch_scc1 .Lref_fin
	v_cmp_eq_u32_e64 s[8:9], v216, s33
	v_cmp_eq_u32_e64 s[12:13], v217, s33
	v_cmp_eq_u32_e64 s[14:15], v218, s33
	v_cmp_eq_u32_e64 s[16:17], v219, s33
	v_cmp_eq_u32_e64 s[18:19], v220, s33
	v_cmp_eq_u32_e64 s[22:23], v221, s33
	v_cmp_eq_u32_e64 s[24:25], v222, s33
	s_nop 1
	v_mbcnt_lo_u32_b32 v241, s8, 0
	v_mbcnt_hi_u32_b32 v241, s9, v241
	v_add_u32_e32 v241, s92, v241
	v_lshl_add_u32 v241, v241, 1, v244
	s_mov_b64 exec, s[8:9]
	ds_write_b16 v241, v224
	s_mov_b64 exec, -1
	s_bcnt1_i32_b64 s61, s[8:9]
	s_add_u32 s92, s92, s61
	v_mbcnt_lo_u32_b32 v241, s12, 0
	v_mbcnt_hi_u32_b32 v241, s13, v241
	v_add_u32_e32 v241, s92, v241
	v_lshl_add_u32 v241, v241, 1, v244
	s_mov_b64 exec, s[12:13]
	ds_write_b16 v241, v225
	s_mov_b64 exec, -1
	s_bcnt1_i32_b64 s61, s[12:13]
	s_add_u32 s92, s92, s61
	v_mbcnt_lo_u32_b32 v241, s14, 0
	v_mbcnt_hi_u32_b32 v241, s15, v241
	v_add_u32_e32 v241, s92, v241
	v_lshl_add_u32 v241, v241, 1, v244
	s_mov_b64 exec, s[14:15]
	ds_write_b16 v241, v226
	s_mov_b64 exec, -1
	s_bcnt1_i32_b64 s61, s[14:15]
	s_add_u32 s92, s92, s61
	v_mbcnt_lo_u32_b32 v241, s16, 0
	v_mbcnt_hi_u32_b32 v241, s17, v241
	v_add_u32_e32 v241, s92, v241
	v_lshl_add_u32 v241, v241, 1, v244
	s_mov_b64 exec, s[16:17]
	ds_write_b16 v241, v227
	s_mov_b64 exec, -1
	s_bcnt1_i32_b64 s61, s[16:17]
	s_add_u32 s92, s92, s61
	v_mbcnt_lo_u32_b32 v241, s18, 0
	v_mbcnt_hi_u32_b32 v241, s19, v241
	v_add_u32_e32 v241, s92, v241
	v_lshl_add_u32 v241, v241, 1, v244
	s_mov_b64 exec, s[18:19]
	ds_write_b16 v241, v228
	s_mov_b64 exec, -1
	s_bcnt1_i32_b64 s61, s[18:19]
	s_add_u32 s92, s92, s61
	v_mbcnt_lo_u32_b32 v241, s22, 0
	v_mbcnt_hi_u32_b32 v241, s23, v241
	v_add_u32_e32 v241, s92, v241
	v_lshl_add_u32 v241, v241, 1, v244
	s_mov_b64 exec, s[22:23]
	ds_write_b16 v241, v229
	s_mov_b64 exec, -1
	s_bcnt1_i32_b64 s61, s[22:23]
	s_add_u32 s92, s92, s61
	v_mbcnt_lo_u32_b32 v241, s24, 0
	v_mbcnt_hi_u32_b32 v241, s25, v241
	v_add_u32_e32 v241, s92, v241
	v_lshl_add_u32 v241, v241, 1, v244
	s_mov_b64 exec, s[24:25]
	ds_write_b16 v241, v230
	s_mov_b64 exec, -1
	s_bcnt1_i32_b64 s61, s[24:25]
	s_add_u32 s92, s92, s61
	s_branch .Lref_fin
.Lref_v6:
	ds_read_b32 v216, v238
	ds_read_u16 v224, v245
	ds_read_b32 v217, v238 offset:256
	ds_read_u16 v225, v245 offset:128
	ds_read_b32 v218, v238 offset:512
	ds_read_u16 v226, v245 offset:256
	ds_read_b32 v219, v238 offset:768
	ds_read_u16 v227, v245 offset:384
	ds_read_b32 v220, v238 offset:1024
	ds_read_u16 v228, v245 offset:512
	ds_read_b32 v221, v238 offset:1280
	ds_read_u16 v229, v245 offset:640
	v_cmp_gt_u32_e64 s[8:9], s93, v145
	v_add_u32_e32 v241, 64, v145
	v_cmp_gt_u32_e64 s[12:13], s93, v241
	v_add_u32_e32 v241, 128, v145
	v_cmp_gt_u32_e64 s[14:15], s93, v241
	v_add_u32_e32 v241, 192, v145
	v_cmp_gt_u32_e64 s[16:17], s93, v241
	v_add_u32_e32 v241, 256, v145
	v_cmp_gt_u32_e64 s[18:19], s93, v241
	v_add_u32_e32 v241, 320, v145
	v_cmp_gt_u32_e64 s[22:23], s93, v241
	s_waitcnt lgkmcnt(0)
	v_cndmask_b32_e64 v216, 0, v216, s[8:9]
	v_cndmask_b32_e64 v217, 0, v217, s[12:13]
	v_cndmask_b32_e64 v218, 0, v218, s[14:15]
	v_cndmask_b32_e64 v219, 0, v219, s[16:17]
	v_cndmask_b32_e64 v220, 0, v220, s[18:19]
	v_cndmask_b32_e64 v221, 0, v221, s[22:23]
	s_or_b32 s57, s33, 0x100000
	v_cmp_ge_u32_e64 s[8:9], v216, s57
	v_cmp_ge_u32_e64 s[12:13], v217, s57
	v_cmp_ge_u32_e64 s[14:15], v218, s57
	v_cmp_ge_u32_e64 s[16:17], v219, s57
	v_cmp_ge_u32_e64 s[18:19], v220, s57
	v_cmp_ge_u32_e64 s[22:23], v221, s57
	s_bcnt1_i32_b64 s89, s[8:9]
	s_bcnt1_i32_b64 s61, s[12:13]
	s_add_u32 s89, s89, s61
	s_bcnt1_i32_b64 s61, s[14:15]
	s_add_u32 s89, s89, s61
	s_bcnt1_i32_b64 s61, s[16:17]
	s_add_u32 s89, s89, s61
	s_bcnt1_i32_b64 s61, s[18:19]
	s_add_u32 s89, s89, s61
	s_bcnt1_i32_b64 s61, s[22:23]
	s_add_u32 s89, s89, s61
	s_cmp_ge_u32 s89, s91
	s_cselect_b32 s33, s57, s33
	s_cmp_eq_u32 s89, s91
	s_cbranch_scc1 .Lref_e6
	s_or_b32 s57, s33, 0x80000
	v_cmp_ge_u32_e64 s[8:9], v216, s57
	v_cmp_ge_u32_e64 s[12:13], v217, s57
	v_cmp_ge_u32_e64 s[14:15], v218, s57
	v_cmp_ge_u32_e64 s[16:17], v219, s57
	v_cmp_ge_u32_e64 s[18:19], v220, s57
	v_cmp_ge_u32_e64 s[22:23], v221, s57
	s_bcnt1_i32_b64 s89, s[8:9]
	s_bcnt1_i32_b64 s61, s[12:13]
	s_add_u32 s89, s89, s61
	s_bcnt1_i32_b64 s61, s[14:15]
	s_add_u32 s89, s89, s61
	s_bcnt1_i32_b64 s61, s[16:17]
	s_add_u32 s89, s89, s61
	s_bcnt1_i32_b64 s61, s[18:19]
	s_add_u32 s89, s89, s61
	s_bcnt1_i32_b64 s61, s[22:23]
	s_add_u32 s89, s89, s61
	s_cmp_ge_u32 s89, s91
	s_cselect_b32 s33, s57, s33
	s_cmp_eq_u32 s89, s91
	s_cbranch_scc1 .Lref_e6
	s_or_b32 s57, s33, 0x40000
	v_cmp_ge_u32_e64 s[8:9], v216, s57
	v_cmp_ge_u32_e64 s[12:13], v217, s57
	v_cmp_ge_u32_e64 s[14:15], v218, s57
	v_cmp_ge_u32_e64 s[16:17], v219, s57
	v_cmp_ge_u32_e64 s[18:19], v220, s57
	v_cmp_ge_u32_e64 s[22:23], v221, s57
	s_bcnt1_i32_b64 s89, s[8:9]
	s_bcnt1_i32_b64 s61, s[12:13]
	s_add_u32 s89, s89, s61
	s_bcnt1_i32_b64 s61, s[14:15]
	s_add_u32 s89, s89, s61
	s_bcnt1_i32_b64 s61, s[16:17]
	s_add_u32 s89, s89, s61
	s_bcnt1_i32_b64 s61, s[18:19]
	s_add_u32 s89, s89, s61
	s_bcnt1_i32_b64 s61, s[22:23]
	s_add_u32 s89, s89, s61
	s_cmp_ge_u32 s89, s91
	s_cselect_b32 s33, s57, s33
	s_cmp_eq_u32 s89, s91
	s_cbranch_scc1 .Lref_e6
	s_or_b32 s57, s33, 0x20000
	v_cmp_ge_u32_e64 s[8:9], v216, s57
	v_cmp_ge_u32_e64 s[12:13], v217, s57
	v_cmp_ge_u32_e64 s[14:15], v218, s57
	v_cmp_ge_u32_e64 s[16:17], v219, s57
	v_cmp_ge_u32_e64 s[18:19], v220, s57
	v_cmp_ge_u32_e64 s[22:23], v221, s57
	s_bcnt1_i32_b64 s89, s[8:9]
	s_bcnt1_i32_b64 s61, s[12:13]
	s_add_u32 s89, s89, s61
	s_bcnt1_i32_b64 s61, s[14:15]
	s_add_u32 s89, s89, s61
	s_bcnt1_i32_b64 s61, s[16:17]
	s_add_u32 s89, s89, s61
	s_bcnt1_i32_b64 s61, s[18:19]
	s_add_u32 s89, s89, s61
	s_bcnt1_i32_b64 s61, s[22:23]
	s_add_u32 s89, s89, s61
	s_cmp_ge_u32 s89, s91
	s_cselect_b32 s33, s57, s33
	s_cmp_eq_u32 s89, s91
	s_cbranch_scc1 .Lref_e6
	s_or_b32 s57, s33, 0x10000
	v_cmp_ge_u32_e64 s[8:9], v216, s57
	v_cmp_ge_u32_e64 s[12:13], v217, s57
	v_cmp_ge_u32_e64 s[14:15], v218, s57
	v_cmp_ge_u32_e64 s[16:17], v219, s57
	v_cmp_ge_u32_e64 s[18:19], v220, s57
	v_cmp_ge_u32_e64 s[22:23], v221, s57
	s_bcnt1_i32_b64 s89, s[8:9]
	s_bcnt1_i32_b64 s61, s[12:13]
	s_add_u32 s89, s89, s61
	s_bcnt1_i32_b64 s61, s[14:15]
	s_add_u32 s89, s89, s61
	s_bcnt1_i32_b64 s61, s[16:17]
	s_add_u32 s89, s89, s61
	s_bcnt1_i32_b64 s61, s[18:19]
	s_add_u32 s89, s89, s61
	s_bcnt1_i32_b64 s61, s[22:23]
	s_add_u32 s89, s89, s61
	s_cmp_ge_u32 s89, s91
	s_cselect_b32 s33, s57, s33
	s_cmp_eq_u32 s89, s91
	s_cbranch_scc1 .Lref_e6
	s_or_b32 s57, s33, 0x8000
	v_cmp_ge_u32_e64 s[8:9], v216, s57
	v_cmp_ge_u32_e64 s[12:13], v217, s57
	v_cmp_ge_u32_e64 s[14:15], v218, s57
	v_cmp_ge_u32_e64 s[16:17], v219, s57
	v_cmp_ge_u32_e64 s[18:19], v220, s57
	v_cmp_ge_u32_e64 s[22:23], v221, s57
	s_bcnt1_i32_b64 s89, s[8:9]
	s_bcnt1_i32_b64 s61, s[12:13]
	s_add_u32 s89, s89, s61
	s_bcnt1_i32_b64 s61, s[14:15]
	s_add_u32 s89, s89, s61
	s_bcnt1_i32_b64 s61, s[16:17]
	s_add_u32 s89, s89, s61
	s_bcnt1_i32_b64 s61, s[18:19]
	s_add_u32 s89, s89, s61
	s_bcnt1_i32_b64 s61, s[22:23]
	s_add_u32 s89, s89, s61
	s_cmp_ge_u32 s89, s91
	s_cselect_b32 s33, s57, s33
	s_cmp_eq_u32 s89, s91
	s_cbranch_scc1 .Lref_e6
	s_or_b32 s57, s33, 0x4000
	v_cmp_ge_u32_e64 s[8:9], v216, s57
	v_cmp_ge_u32_e64 s[12:13], v217, s57
	v_cmp_ge_u32_e64 s[14:15], v218, s57
	v_cmp_ge_u32_e64 s[16:17], v219, s57
	v_cmp_ge_u32_e64 s[18:19], v220, s57
	v_cmp_ge_u32_e64 s[22:23], v221, s57
	s_bcnt1_i32_b64 s89, s[8:9]
	s_bcnt1_i32_b64 s61, s[12:13]
	s_add_u32 s89, s89, s61
	s_bcnt1_i32_b64 s61, s[14:15]
	s_add_u32 s89, s89, s61
	s_bcnt1_i32_b64 s61, s[16:17]
	s_add_u32 s89, s89, s61
	s_bcnt1_i32_b64 s61, s[18:19]
	s_add_u32 s89, s89, s61
	s_bcnt1_i32_b64 s61, s[22:23]
	s_add_u32 s89, s89, s61
	s_cmp_ge_u32 s89, s91
	s_cselect_b32 s33, s57, s33
	s_cmp_eq_u32 s89, s91
	s_cbranch_scc1 .Lref_e6
	s_or_b32 s57, s33, 0x2000
	v_cmp_ge_u32_e64 s[8:9], v216, s57
	v_cmp_ge_u32_e64 s[12:13], v217, s57
	v_cmp_ge_u32_e64 s[14:15], v218, s57
	v_cmp_ge_u32_e64 s[16:17], v219, s57
	v_cmp_ge_u32_e64 s[18:19], v220, s57
	v_cmp_ge_u32_e64 s[22:23], v221, s57
	s_bcnt1_i32_b64 s89, s[8:9]
	s_bcnt1_i32_b64 s61, s[12:13]
	s_add_u32 s89, s89, s61
	s_bcnt1_i32_b64 s61, s[14:15]
	s_add_u32 s89, s89, s61
	s_bcnt1_i32_b64 s61, s[16:17]
	s_add_u32 s89, s89, s61
	s_bcnt1_i32_b64 s61, s[18:19]
	s_add_u32 s89, s89, s61
	s_bcnt1_i32_b64 s61, s[22:23]
	s_add_u32 s89, s89, s61
	s_cmp_ge_u32 s89, s91
	s_cselect_b32 s33, s57, s33
	s_cmp_eq_u32 s89, s91
	s_cbranch_scc1 .Lref_e6
	s_or_b32 s57, s33, 0x1000
	v_cmp_ge_u32_e64 s[8:9], v216, s57
	v_cmp_ge_u32_e64 s[12:13], v217, s57
	v_cmp_ge_u32_e64 s[14:15], v218, s57
	v_cmp_ge_u32_e64 s[16:17], v219, s57
	v_cmp_ge_u32_e64 s[18:19], v220, s57
	v_cmp_ge_u32_e64 s[22:23], v221, s57
	s_bcnt1_i32_b64 s89, s[8:9]
	s_bcnt1_i32_b64 s61, s[12:13]
	s_add_u32 s89, s89, s61
	s_bcnt1_i32_b64 s61, s[14:15]
	s_add_u32 s89, s89, s61
	s_bcnt1_i32_b64 s61, s[16:17]
	s_add_u32 s89, s89, s61
	s_bcnt1_i32_b64 s61, s[18:19]
	s_add_u32 s89, s89, s61
	s_bcnt1_i32_b64 s61, s[22:23]
	s_add_u32 s89, s89, s61
	s_cmp_ge_u32 s89, s91
	s_cselect_b32 s33, s57, s33
	s_cmp_eq_u32 s89, s91
	s_cbranch_scc1 .Lref_e6
	s_or_b32 s57, s33, 0x800
	v_cmp_ge_u32_e64 s[8:9], v216, s57
	v_cmp_ge_u32_e64 s[12:13], v217, s57
	v_cmp_ge_u32_e64 s[14:15], v218, s57
	v_cmp_ge_u32_e64 s[16:17], v219, s57
	v_cmp_ge_u32_e64 s[18:19], v220, s57
	v_cmp_ge_u32_e64 s[22:23], v221, s57
	s_bcnt1_i32_b64 s89, s[8:9]
	s_bcnt1_i32_b64 s61, s[12:13]
	s_add_u32 s89, s89, s61
	s_bcnt1_i32_b64 s61, s[14:15]
	s_add_u32 s89, s89, s61
	s_bcnt1_i32_b64 s61, s[16:17]
	s_add_u32 s89, s89, s61
	s_bcnt1_i32_b64 s61, s[18:19]
	s_add_u32 s89, s89, s61
	s_bcnt1_i32_b64 s61, s[22:23]
	s_add_u32 s89, s89, s61
	s_cmp_ge_u32 s89, s91
	s_cselect_b32 s33, s57, s33
	s_cmp_eq_u32 s89, s91
	s_cbranch_scc1 .Lref_e6
	s_or_b32 s57, s33, 0x400
	v_cmp_ge_u32_e64 s[8:9], v216, s57
	v_cmp_ge_u32_e64 s[12:13], v217, s57
	v_cmp_ge_u32_e64 s[14:15], v218, s57
	v_cmp_ge_u32_e64 s[16:17], v219, s57
	v_cmp_ge_u32_e64 s[18:19], v220, s57
	v_cmp_ge_u32_e64 s[22:23], v221, s57
	s_bcnt1_i32_b64 s89, s[8:9]
	s_bcnt1_i32_b64 s61, s[12:13]
	s_add_u32 s89, s89, s61
	s_bcnt1_i32_b64 s61, s[14:15]
	s_add_u32 s89, s89, s61
	s_bcnt1_i32_b64 s61, s[16:17]
	s_add_u32 s89, s89, s61
	s_bcnt1_i32_b64 s61, s[18:19]
	s_add_u32 s89, s89, s61
	s_bcnt1_i32_b64 s61, s[22:23]
	s_add_u32 s89, s89, s61
	s_cmp_ge_u32 s89, s91
	s_cselect_b32 s33, s57, s33
	s_cmp_eq_u32 s89, s91
	s_cbranch_scc1 .Lref_e6
	s_or_b32 s57, s33, 0x200
	v_cmp_ge_u32_e64 s[8:9], v216, s57
	v_cmp_ge_u32_e64 s[12:13], v217, s57
	v_cmp_ge_u32_e64 s[14:15], v218, s57
	v_cmp_ge_u32_e64 s[16:17], v219, s57
	v_cmp_ge_u32_e64 s[18:19], v220, s57
	v_cmp_ge_u32_e64 s[22:23], v221, s57
	s_bcnt1_i32_b64 s89, s[8:9]
	s_bcnt1_i32_b64 s61, s[12:13]
	s_add_u32 s89, s89, s61
	s_bcnt1_i32_b64 s61, s[14:15]
	s_add_u32 s89, s89, s61
	s_bcnt1_i32_b64 s61, s[16:17]
	s_add_u32 s89, s89, s61
	s_bcnt1_i32_b64 s61, s[18:19]
	s_add_u32 s89, s89, s61
	s_bcnt1_i32_b64 s61, s[22:23]
	s_add_u32 s89, s89, s61
	s_cmp_ge_u32 s89, s91
	s_cselect_b32 s33, s57, s33
	s_cmp_eq_u32 s89, s91
	s_cbranch_scc1 .Lref_e6
	s_or_b32 s57, s33, 0x100
	v_cmp_ge_u32_e64 s[8:9], v216, s57
	v_cmp_ge_u32_e64 s[12:13], v217, s57
	v_cmp_ge_u32_e64 s[14:15], v218, s57
	v_cmp_ge_u32_e64 s[16:17], v219, s57
	v_cmp_ge_u32_e64 s[18:19], v220, s57
	v_cmp_ge_u32_e64 s[22:23], v221, s57
	s_bcnt1_i32_b64 s89, s[8:9]
	s_bcnt1_i32_b64 s61, s[12:13]
	s_add_u32 s89, s89, s61
	s_bcnt1_i32_b64 s61, s[14:15]
	s_add_u32 s89, s89, s61
	s_bcnt1_i32_b64 s61, s[16:17]
	s_add_u32 s89, s89, s61
	s_bcnt1_i32_b64 s61, s[18:19]
	s_add_u32 s89, s89, s61
	s_bcnt1_i32_b64 s61, s[22:23]
	s_add_u32 s89, s89, s61
	s_cmp_ge_u32 s89, s91
	s_cselect_b32 s33, s57, s33
	s_cmp_eq_u32 s89, s91
	s_cbranch_scc1 .Lref_e6
	s_or_b32 s57, s33, 0x80
	v_cmp_ge_u32_e64 s[8:9], v216, s57
	v_cmp_ge_u32_e64 s[12:13], v217, s57
	v_cmp_ge_u32_e64 s[14:15], v218, s57
	v_cmp_ge_u32_e64 s[16:17], v219, s57
	v_cmp_ge_u32_e64 s[18:19], v220, s57
	v_cmp_ge_u32_e64 s[22:23], v221, s57
	s_bcnt1_i32_b64 s89, s[8:9]
	s_bcnt1_i32_b64 s61, s[12:13]
	s_add_u32 s89, s89, s61
	s_bcnt1_i32_b64 s61, s[14:15]
	s_add_u32 s89, s89, s61
	s_bcnt1_i32_b64 s61, s[16:17]
	s_add_u32 s89, s89, s61
	s_bcnt1_i32_b64 s61, s[18:19]
	s_add_u32 s89, s89, s61
	s_bcnt1_i32_b64 s61, s[22:23]
	s_add_u32 s89, s89, s61
	s_cmp_ge_u32 s89, s91
	s_cselect_b32 s33, s57, s33
	s_cmp_eq_u32 s89, s91
	s_cbranch_scc1 .Lref_e6
	s_or_b32 s57, s33, 0x40
	v_cmp_ge_u32_e64 s[8:9], v216, s57
	v_cmp_ge_u32_e64 s[12:13], v217, s57
	v_cmp_ge_u32_e64 s[14:15], v218, s57
	v_cmp_ge_u32_e64 s[16:17], v219, s57
	v_cmp_ge_u32_e64 s[18:19], v220, s57
	v_cmp_ge_u32_e64 s[22:23], v221, s57
	s_bcnt1_i32_b64 s89, s[8:9]
	s_bcnt1_i32_b64 s61, s[12:13]
	s_add_u32 s89, s89, s61
	s_bcnt1_i32_b64 s61, s[14:15]
	s_add_u32 s89, s89, s61
	s_bcnt1_i32_b64 s61, s[16:17]
	s_add_u32 s89, s89, s61
	s_bcnt1_i32_b64 s61, s[18:19]
	s_add_u32 s89, s89, s61
	s_bcnt1_i32_b64 s61, s[22:23]
	s_add_u32 s89, s89, s61
	s_cmp_ge_u32 s89, s91
	s_cselect_b32 s33, s57, s33
	s_cmp_eq_u32 s89, s91
	s_cbranch_scc1 .Lref_e6
	s_or_b32 s57, s33, 0x20
	v_cmp_ge_u32_e64 s[8:9], v216, s57
	v_cmp_ge_u32_e64 s[12:13], v217, s57
	v_cmp_ge_u32_e64 s[14:15], v218, s57
	v_cmp_ge_u32_e64 s[16:17], v219, s57
	v_cmp_ge_u32_e64 s[18:19], v220, s57
	v_cmp_ge_u32_e64 s[22:23], v221, s57
	s_bcnt1_i32_b64 s89, s[8:9]
	s_bcnt1_i32_b64 s61, s[12:13]
	s_add_u32 s89, s89, s61
	s_bcnt1_i32_b64 s61, s[14:15]
	s_add_u32 s89, s89, s61
	s_bcnt1_i32_b64 s61, s[16:17]
	s_add_u32 s89, s89, s61
	s_bcnt1_i32_b64 s61, s[18:19]
	s_add_u32 s89, s89, s61
	s_bcnt1_i32_b64 s61, s[22:23]
	s_add_u32 s89, s89, s61
	s_cmp_ge_u32 s89, s91
	s_cselect_b32 s33, s57, s33
	s_cmp_eq_u32 s89, s91
	s_cbranch_scc1 .Lref_e6
	s_or_b32 s57, s33, 0x10
	v_cmp_ge_u32_e64 s[8:9], v216, s57
	v_cmp_ge_u32_e64 s[12:13], v217, s57
	v_cmp_ge_u32_e64 s[14:15], v218, s57
	v_cmp_ge_u32_e64 s[16:17], v219, s57
	v_cmp_ge_u32_e64 s[18:19], v220, s57
	v_cmp_ge_u32_e64 s[22:23], v221, s57
	s_bcnt1_i32_b64 s89, s[8:9]
	s_bcnt1_i32_b64 s61, s[12:13]
	s_add_u32 s89, s89, s61
	s_bcnt1_i32_b64 s61, s[14:15]
	s_add_u32 s89, s89, s61
	s_bcnt1_i32_b64 s61, s[16:17]
	s_add_u32 s89, s89, s61
	s_bcnt1_i32_b64 s61, s[18:19]
	s_add_u32 s89, s89, s61
	s_bcnt1_i32_b64 s61, s[22:23]
	s_add_u32 s89, s89, s61
	s_cmp_ge_u32 s89, s91
	s_cselect_b32 s33, s57, s33
	s_cmp_eq_u32 s89, s91
	s_cbranch_scc1 .Lref_e6
	s_or_b32 s57, s33, 0x8
	v_cmp_ge_u32_e64 s[8:9], v216, s57
	v_cmp_ge_u32_e64 s[12:13], v217, s57
	v_cmp_ge_u32_e64 s[14:15], v218, s57
	v_cmp_ge_u32_e64 s[16:17], v219, s57
	v_cmp_ge_u32_e64 s[18:19], v220, s57
	v_cmp_ge_u32_e64 s[22:23], v221, s57
	s_bcnt1_i32_b64 s89, s[8:9]
	s_bcnt1_i32_b64 s61, s[12:13]
	s_add_u32 s89, s89, s61
	s_bcnt1_i32_b64 s61, s[14:15]
	s_add_u32 s89, s89, s61
	s_bcnt1_i32_b64 s61, s[16:17]
	s_add_u32 s89, s89, s61
	s_bcnt1_i32_b64 s61, s[18:19]
	s_add_u32 s89, s89, s61
	s_bcnt1_i32_b64 s61, s[22:23]
	s_add_u32 s89, s89, s61
	s_cmp_ge_u32 s89, s91
	s_cselect_b32 s33, s57, s33
	s_cmp_eq_u32 s89, s91
	s_cbranch_scc1 .Lref_e6
	s_or_b32 s57, s33, 0x4
	v_cmp_ge_u32_e64 s[8:9], v216, s57
	v_cmp_ge_u32_e64 s[12:13], v217, s57
	v_cmp_ge_u32_e64 s[14:15], v218, s57
	v_cmp_ge_u32_e64 s[16:17], v219, s57
	v_cmp_ge_u32_e64 s[18:19], v220, s57
	v_cmp_ge_u32_e64 s[22:23], v221, s57
	s_bcnt1_i32_b64 s89, s[8:9]
	s_bcnt1_i32_b64 s61, s[12:13]
	s_add_u32 s89, s89, s61
	s_bcnt1_i32_b64 s61, s[14:15]
	s_add_u32 s89, s89, s61
	s_bcnt1_i32_b64 s61, s[16:17]
	s_add_u32 s89, s89, s61
	s_bcnt1_i32_b64 s61, s[18:19]
	s_add_u32 s89, s89, s61
	s_bcnt1_i32_b64 s61, s[22:23]
	s_add_u32 s89, s89, s61
	s_cmp_ge_u32 s89, s91
	s_cselect_b32 s33, s57, s33
	s_cmp_eq_u32 s89, s91
	s_cbranch_scc1 .Lref_e6
	s_or_b32 s57, s33, 0x2
	v_cmp_ge_u32_e64 s[8:9], v216, s57
	v_cmp_ge_u32_e64 s[12:13], v217, s57
	v_cmp_ge_u32_e64 s[14:15], v218, s57
	v_cmp_ge_u32_e64 s[16:17], v219, s57
	v_cmp_ge_u32_e64 s[18:19], v220, s57
	v_cmp_ge_u32_e64 s[22:23], v221, s57
	s_bcnt1_i32_b64 s89, s[8:9]
	s_bcnt1_i32_b64 s61, s[12:13]
	s_add_u32 s89, s89, s61
	s_bcnt1_i32_b64 s61, s[14:15]
	s_add_u32 s89, s89, s61
	s_bcnt1_i32_b64 s61, s[16:17]
	s_add_u32 s89, s89, s61
	s_bcnt1_i32_b64 s61, s[18:19]
	s_add_u32 s89, s89, s61
	s_bcnt1_i32_b64 s61, s[22:23]
	s_add_u32 s89, s89, s61
	s_cmp_ge_u32 s89, s91
	s_cselect_b32 s33, s57, s33
	s_cmp_eq_u32 s89, s91
	s_cbranch_scc1 .Lref_e6
	s_or_b32 s57, s33, 0x1
	v_cmp_ge_u32_e64 s[8:9], v216, s57
	v_cmp_ge_u32_e64 s[12:13], v217, s57
	v_cmp_ge_u32_e64 s[14:15], v218, s57
	v_cmp_ge_u32_e64 s[16:17], v219, s57
	v_cmp_ge_u32_e64 s[18:19], v220, s57
	v_cmp_ge_u32_e64 s[22:23], v221, s57
	s_bcnt1_i32_b64 s89, s[8:9]
	s_bcnt1_i32_b64 s61, s[12:13]
	s_add_u32 s89, s89, s61
	s_bcnt1_i32_b64 s61, s[14:15]
	s_add_u32 s89, s89, s61
	s_bcnt1_i32_b64 s61, s[16:17]
	s_add_u32 s89, s89, s61
	s_bcnt1_i32_b64 s61, s[18:19]
	s_add_u32 s89, s89, s61
	s_bcnt1_i32_b64 s61, s[22:23]
	s_add_u32 s89, s89, s61
	s_cmp_ge_u32 s89, s91
	s_cselect_b32 s33, s57, s33
	s_cmp_eq_u32 s89, s91
	s_cbranch_scc1 .Lref_e6
	v_cmp_gt_u32_e64 s[8:9], v216, s33
	v_cmp_gt_u32_e64 s[12:13], v217, s33
	v_cmp_gt_u32_e64 s[14:15], v218, s33
	v_cmp_gt_u32_e64 s[16:17], v219, s33
	v_cmp_gt_u32_e64 s[18:19], v220, s33
	v_cmp_gt_u32_e64 s[22:23], v221, s33
	s_bcnt1_i32_b64 s89, s[8:9]
	s_bcnt1_i32_b64 s61, s[12:13]
	s_add_u32 s89, s89, s61
	s_bcnt1_i32_b64 s61, s[14:15]
	s_add_u32 s89, s89, s61
	s_bcnt1_i32_b64 s61, s[16:17]
	s_add_u32 s89, s89, s61
	s_bcnt1_i32_b64 s61, s[18:19]
	s_add_u32 s89, s89, s61
	s_bcnt1_i32_b64 s61, s[22:23]
	s_add_u32 s89, s89, s61
	s_sub_u32 s91, s91, s89
	v_cmp_eq_u32_e64 s[8:9], v216, s33
	v_cmp_eq_u32_e64 s[12:13], v217, s33
	v_cmp_eq_u32_e64 s[14:15], v218, s33
	v_cmp_eq_u32_e64 s[16:17], v219, s33
	v_cmp_eq_u32_e64 s[18:19], v220, s33
	v_cmp_eq_u32_e64 s[22:23], v221, s33
	s_bcnt1_i32_b64 s89, s[8:9]
	s_bcnt1_i32_b64 s61, s[12:13]
	s_add_u32 s89, s89, s61
	s_bcnt1_i32_b64 s61, s[14:15]
	s_add_u32 s89, s89, s61
	s_bcnt1_i32_b64 s61, s[16:17]
	s_add_u32 s89, s89, s61
	s_bcnt1_i32_b64 s61, s[18:19]
	s_add_u32 s89, s89, s61
	s_bcnt1_i32_b64 s61, s[22:23]
	s_add_u32 s89, s89, s61
	s_add_u32 s57, s33, 1
	s_cmp_eq_u32 s91, s89
	s_cselect_b32 s57, s33, s57
	s_cselect_b32 s60, 1, 0
	s_branch .Lref_emit6

.Lref_emit6:
	v_cmp_ge_u32_e64 s[8:9], v216, s57
	v_cmp_ge_u32_e64 s[12:13], v217, s57
	v_cmp_ge_u32_e64 s[14:15], v218, s57
	v_cmp_ge_u32_e64 s[16:17], v219, s57
	v_cmp_ge_u32_e64 s[18:19], v220, s57
	v_cmp_ge_u32_e64 s[22:23], v221, s57
	s_nop 1
	v_mbcnt_lo_u32_b32 v241, s8, 0
	v_mbcnt_hi_u32_b32 v241, s9, v241
	v_add_u32_e32 v241, s90, v241
	v_and_b32_e32 v241, 0xff, v241
	v_lshl_add_u32 v241, v241, 1, v246
	s_mov_b64 exec, s[8:9]
	ds_write_b16 v241, v224
	s_mov_b64 exec, -1
	s_bcnt1_i32_b64 s61, s[8:9]
	s_add_u32 s90, s90, s61
	v_mbcnt_lo_u32_b32 v241, s12, 0
	v_mbcnt_hi_u32_b32 v241, s13, v241
	v_add_u32_e32 v241, s90, v241
	v_and_b32_e32 v241, 0xff, v241
	v_lshl_add_u32 v241, v241, 1, v246
	s_mov_b64 exec, s[12:13]
	ds_write_b16 v241, v225
	s_mov_b64 exec, -1
	s_bcnt1_i32_b64 s61, s[12:13]
	s_add_u32 s90, s90, s61
	v_mbcnt_lo_u32_b32 v241, s14, 0
	v_mbcnt_hi_u32_b32 v241, s15, v241
	v_add_u32_e32 v241, s90, v241
	v_and_b32_e32 v241, 0xff, v241
	v_lshl_add_u32 v241, v241, 1, v246
	s_mov_b64 exec, s[14:15]
	ds_write_b16 v241, v226
	s_mov_b64 exec, -1
	s_bcnt1_i32_b64 s61, s[14:15]
	s_add_u32 s90, s90, s61
	v_mbcnt_lo_u32_b32 v241, s16, 0
	v_mbcnt_hi_u32_b32 v241, s17, v241
	v_add_u32_e32 v241, s90, v241
	v_and_b32_e32 v241, 0xff, v241
	v_lshl_add_u32 v241, v241, 1, v246
	s_mov_b64 exec, s[16:17]
	ds_write_b16 v241, v227
	s_mov_b64 exec, -1
	s_bcnt1_i32_b64 s61, s[16:17]
	s_add_u32 s90, s90, s61
	v_mbcnt_lo_u32_b32 v241, s18, 0
	v_mbcnt_hi_u32_b32 v241, s19, v241
	v_add_u32_e32 v241, s90, v241
	v_and_b32_e32 v241, 0xff, v241
	v_lshl_add_u32 v241, v241, 1, v246
	s_mov_b64 exec, s[18:19]
	ds_write_b16 v241, v228
	s_mov_b64 exec, -1
	s_bcnt1_i32_b64 s61, s[18:19]
	s_add_u32 s90, s90, s61
	v_mbcnt_lo_u32_b32 v241, s22, 0
	v_mbcnt_hi_u32_b32 v241, s23, v241
	v_add_u32_e32 v241, s90, v241
	v_and_b32_e32 v241, 0xff, v241
	v_lshl_add_u32 v241, v241, 1, v246
	s_mov_b64 exec, s[22:23]
	ds_write_b16 v241, v229
	s_mov_b64 exec, -1
	s_bcnt1_i32_b64 s61, s[22:23]
	s_add_u32 s90, s90, s61
	s_mov_b32 s92, 0
	s_cmp_lg_u32 s60, 0
	s_cbranch_scc1 .Lref_fin
	v_cmp_eq_u32_e64 s[8:9], v216, s33
	v_cmp_eq_u32_e64 s[12:13], v217, s33
	v_cmp_eq_u32_e64 s[14:15], v218, s33
	v_cmp_eq_u32_e64 s[16:17], v219, s33
	v_cmp_eq_u32_e64 s[18:19], v220, s33
	v_cmp_eq_u32_e64 s[22:23], v221, s33
	s_nop 1
	v_mbcnt_lo_u32_b32 v241, s8, 0
	v_mbcnt_hi_u32_b32 v241, s9, v241
	v_add_u32_e32 v241, s92, v241
	v_lshl_add_u32 v241, v241, 1, v244
	s_mov_b64 exec, s[8:9]
	ds_write_b16 v241, v224
	s_mov_b64 exec, -1
	s_bcnt1_i32_b64 s61, s[8:9]
	s_add_u32 s92, s92, s61
	v_mbcnt_lo_u32_b32 v241, s12, 0
	v_mbcnt_hi_u32_b32 v241, s13, v241
	v_add_u32_e32 v241, s92, v241
	v_lshl_add_u32 v241, v241, 1, v244
	s_mov_b64 exec, s[12:13]
	ds_write_b16 v241, v225
	s_mov_b64 exec, -1
	s_bcnt1_i32_b64 s61, s[12:13]
	s_add_u32 s92, s92, s61
	v_mbcnt_lo_u32_b32 v241, s14, 0
	v_mbcnt_hi_u32_b32 v241, s15, v241
	v_add_u32_e32 v241, s92, v241
	v_lshl_add_u32 v241, v241, 1, v244
	s_mov_b64 exec, s[14:15]
	ds_write_b16 v241, v226
	s_mov_b64 exec, -1
	s_bcnt1_i32_b64 s61, s[14:15]
	s_add_u32 s92, s92, s61
	v_mbcnt_lo_u32_b32 v241, s16, 0
	v_mbcnt_hi_u32_b32 v241, s17, v241
	v_add_u32_e32 v241, s92, v241
	v_lshl_add_u32 v241, v241, 1, v244
	s_mov_b64 exec, s[16:17]
	ds_write_b16 v241, v227
	s_mov_b64 exec, -1
	s_bcnt1_i32_b64 s61, s[16:17]
	s_add_u32 s92, s92, s61
	v_mbcnt_lo_u32_b32 v241, s18, 0
	v_mbcnt_hi_u32_b32 v241, s19, v241
	v_add_u32_e32 v241, s92, v241
	v_lshl_add_u32 v241, v241, 1, v244
	s_mov_b64 exec, s[18:19]
	ds_write_b16 v241, v228
	s_mov_b64 exec, -1
	s_bcnt1_i32_b64 s61, s[18:19]
	s_add_u32 s92, s92, s61
	v_mbcnt_lo_u32_b32 v241, s22, 0
	v_mbcnt_hi_u32_b32 v241, s23, v241
	v_add_u32_e32 v241, s92, v241
	v_lshl_add_u32 v241, v241, 1, v244
	s_mov_b64 exec, s[22:23]
	ds_write_b16 v241, v229
	s_mov_b64 exec, -1
	s_bcnt1_i32_b64 s61, s[22:23]
	s_add_u32 s92, s92, s61
	s_branch .Lref_fin
.Lref_v5:
	ds_read_b32 v216, v238
	ds_read_u16 v224, v245
	ds_read_b32 v217, v238 offset:256
	ds_read_u16 v225, v245 offset:128
	ds_read_b32 v218, v238 offset:512
	ds_read_u16 v226, v245 offset:256
	ds_read_b32 v219, v238 offset:768
	ds_read_u16 v227, v245 offset:384
	ds_read_b32 v220, v238 offset:1024
	ds_read_u16 v228, v245 offset:512
	v_cmp_gt_u32_e64 s[8:9], s93, v145
	v_add_u32_e32 v241, 64, v145
	v_cmp_gt_u32_e64 s[12:13], s93, v241
	v_add_u32_e32 v241, 128, v145
	v_cmp_gt_u32_e64 s[14:15], s93, v241
	v_add_u32_e32 v241, 192, v145
	v_cmp_gt_u32_e64 s[16:17], s93, v241
	v_add_u32_e32 v241, 256, v145
	v_cmp_gt_u32_e64 s[18:19], s93, v241
	s_waitcnt lgkmcnt(0)
	v_cndmask_b32_e64 v216, 0, v216, s[8:9]
	v_cndmask_b32_e64 v217, 0, v217, s[12:13]
	v_cndmask_b32_e64 v218, 0, v218, s[14:15]
	v_cndmask_b32_e64 v219, 0, v219, s[16:17]
	v_cndmask_b32_e64 v220, 0, v220, s[18:19]
	s_or_b32 s57, s33, 0x100000
	v_cmp_ge_u32_e64 s[8:9], v216, s57
	v_cmp_ge_u32_e64 s[12:13], v217, s57
	v_cmp_ge_u32_e64 s[14:15], v218, s57
	v_cmp_ge_u32_e64 s[16:17], v219, s57
	v_cmp_ge_u32_e64 s[18:19], v220, s57
	s_bcnt1_i32_b64 s89, s[8:9]
	s_bcnt1_i32_b64 s61, s[12:13]
	s_add_u32 s89, s89, s61
	s_bcnt1_i32_b64 s61, s[14:15]
	s_add_u32 s89, s89, s61
	s_bcnt1_i32_b64 s61, s[16:17]
	s_add_u32 s89, s89, s61
	s_bcnt1_i32_b64 s61, s[18:19]
	s_add_u32 s89, s89, s61
	s_cmp_ge_u32 s89, s91
	s_cselect_b32 s33, s57, s33
	s_cmp_eq_u32 s89, s91
	s_cbranch_scc1 .Lref_e5
	s_or_b32 s57, s33, 0x80000
	v_cmp_ge_u32_e64 s[8:9], v216, s57
	v_cmp_ge_u32_e64 s[12:13], v217, s57
	v_cmp_ge_u32_e64 s[14:15], v218, s57
	v_cmp_ge_u32_e64 s[16:17], v219, s57
	v_cmp_ge_u32_e64 s[18:19], v220, s57
	s_bcnt1_i32_b64 s89, s[8:9]
	s_bcnt1_i32_b64 s61, s[12:13]
	s_add_u32 s89, s89, s61
	s_bcnt1_i32_b64 s61, s[14:15]
	s_add_u32 s89, s89, s61
	s_bcnt1_i32_b64 s61, s[16:17]
	s_add_u32 s89, s89, s61
	s_bcnt1_i32_b64 s61, s[18:19]
	s_add_u32 s89, s89, s61
	s_cmp_ge_u32 s89, s91
	s_cselect_b32 s33, s57, s33
	s_cmp_eq_u32 s89, s91
	s_cbranch_scc1 .Lref_e5
	s_or_b32 s57, s33, 0x40000
	v_cmp_ge_u32_e64 s[8:9], v216, s57
	v_cmp_ge_u32_e64 s[12:13], v217, s57
	v_cmp_ge_u32_e64 s[14:15], v218, s57
	v_cmp_ge_u32_e64 s[16:17], v219, s57
	v_cmp_ge_u32_e64 s[18:19], v220, s57
	s_bcnt1_i32_b64 s89, s[8:9]
	s_bcnt1_i32_b64 s61, s[12:13]
	s_add_u32 s89, s89, s61
	s_bcnt1_i32_b64 s61, s[14:15]
	s_add_u32 s89, s89, s61
	s_bcnt1_i32_b64 s61, s[16:17]
	s_add_u32 s89, s89, s61
	s_bcnt1_i32_b64 s61, s[18:19]
	s_add_u32 s89, s89, s61
	s_cmp_ge_u32 s89, s91
	s_cselect_b32 s33, s57, s33
	s_cmp_eq_u32 s89, s91
	s_cbranch_scc1 .Lref_e5
	s_or_b32 s57, s33, 0x20000
	v_cmp_ge_u32_e64 s[8:9], v216, s57
	v_cmp_ge_u32_e64 s[12:13], v217, s57
	v_cmp_ge_u32_e64 s[14:15], v218, s57
	v_cmp_ge_u32_e64 s[16:17], v219, s57
	v_cmp_ge_u32_e64 s[18:19], v220, s57
	s_bcnt1_i32_b64 s89, s[8:9]
	s_bcnt1_i32_b64 s61, s[12:13]
	s_add_u32 s89, s89, s61
	s_bcnt1_i32_b64 s61, s[14:15]
	s_add_u32 s89, s89, s61
	s_bcnt1_i32_b64 s61, s[16:17]
	s_add_u32 s89, s89, s61
	s_bcnt1_i32_b64 s61, s[18:19]
	s_add_u32 s89, s89, s61
	s_cmp_ge_u32 s89, s91
	s_cselect_b32 s33, s57, s33
	s_cmp_eq_u32 s89, s91
	s_cbranch_scc1 .Lref_e5
	s_or_b32 s57, s33, 0x10000
	v_cmp_ge_u32_e64 s[8:9], v216, s57
	v_cmp_ge_u32_e64 s[12:13], v217, s57
	v_cmp_ge_u32_e64 s[14:15], v218, s57
	v_cmp_ge_u32_e64 s[16:17], v219, s57
	v_cmp_ge_u32_e64 s[18:19], v220, s57
	s_bcnt1_i32_b64 s89, s[8:9]
	s_bcnt1_i32_b64 s61, s[12:13]
	s_add_u32 s89, s89, s61
	s_bcnt1_i32_b64 s61, s[14:15]
	s_add_u32 s89, s89, s61
	s_bcnt1_i32_b64 s61, s[16:17]
	s_add_u32 s89, s89, s61
	s_bcnt1_i32_b64 s61, s[18:19]
	s_add_u32 s89, s89, s61
	s_cmp_ge_u32 s89, s91
	s_cselect_b32 s33, s57, s33
	s_cmp_eq_u32 s89, s91
	s_cbranch_scc1 .Lref_e5
	s_or_b32 s57, s33, 0x8000
	v_cmp_ge_u32_e64 s[8:9], v216, s57
	v_cmp_ge_u32_e64 s[12:13], v217, s57
	v_cmp_ge_u32_e64 s[14:15], v218, s57
	v_cmp_ge_u32_e64 s[16:17], v219, s57
	v_cmp_ge_u32_e64 s[18:19], v220, s57
	s_bcnt1_i32_b64 s89, s[8:9]
	s_bcnt1_i32_b64 s61, s[12:13]
	s_add_u32 s89, s89, s61
	s_bcnt1_i32_b64 s61, s[14:15]
	s_add_u32 s89, s89, s61
	s_bcnt1_i32_b64 s61, s[16:17]
	s_add_u32 s89, s89, s61
	s_bcnt1_i32_b64 s61, s[18:19]
	s_add_u32 s89, s89, s61
	s_cmp_ge_u32 s89, s91
	s_cselect_b32 s33, s57, s33
	s_cmp_eq_u32 s89, s91
	s_cbranch_scc1 .Lref_e5
	s_or_b32 s57, s33, 0x4000
	v_cmp_ge_u32_e64 s[8:9], v216, s57
	v_cmp_ge_u32_e64 s[12:13], v217, s57
	v_cmp_ge_u32_e64 s[14:15], v218, s57
	v_cmp_ge_u32_e64 s[16:17], v219, s57
	v_cmp_ge_u32_e64 s[18:19], v220, s57
	s_bcnt1_i32_b64 s89, s[8:9]
	s_bcnt1_i32_b64 s61, s[12:13]
	s_add_u32 s89, s89, s61
	s_bcnt1_i32_b64 s61, s[14:15]
	s_add_u32 s89, s89, s61
	s_bcnt1_i32_b64 s61, s[16:17]
	s_add_u32 s89, s89, s61
	s_bcnt1_i32_b64 s61, s[18:19]
	s_add_u32 s89, s89, s61
	s_cmp_ge_u32 s89, s91
	s_cselect_b32 s33, s57, s33
	s_cmp_eq_u32 s89, s91
	s_cbranch_scc1 .Lref_e5
	s_or_b32 s57, s33, 0x2000
	v_cmp_ge_u32_e64 s[8:9], v216, s57
	v_cmp_ge_u32_e64 s[12:13], v217, s57
	v_cmp_ge_u32_e64 s[14:15], v218, s57
	v_cmp_ge_u32_e64 s[16:17], v219, s57
	v_cmp_ge_u32_e64 s[18:19], v220, s57
	s_bcnt1_i32_b64 s89, s[8:9]
	s_bcnt1_i32_b64 s61, s[12:13]
	s_add_u32 s89, s89, s61
	s_bcnt1_i32_b64 s61, s[14:15]
	s_add_u32 s89, s89, s61
	s_bcnt1_i32_b64 s61, s[16:17]
	s_add_u32 s89, s89, s61
	s_bcnt1_i32_b64 s61, s[18:19]
	s_add_u32 s89, s89, s61
	s_cmp_ge_u32 s89, s91
	s_cselect_b32 s33, s57, s33
	s_cmp_eq_u32 s89, s91
	s_cbranch_scc1 .Lref_e5
	s_or_b32 s57, s33, 0x1000
	v_cmp_ge_u32_e64 s[8:9], v216, s57
	v_cmp_ge_u32_e64 s[12:13], v217, s57
	v_cmp_ge_u32_e64 s[14:15], v218, s57
	v_cmp_ge_u32_e64 s[16:17], v219, s57
	v_cmp_ge_u32_e64 s[18:19], v220, s57
	s_bcnt1_i32_b64 s89, s[8:9]
	s_bcnt1_i32_b64 s61, s[12:13]
	s_add_u32 s89, s89, s61
	s_bcnt1_i32_b64 s61, s[14:15]
	s_add_u32 s89, s89, s61
	s_bcnt1_i32_b64 s61, s[16:17]
	s_add_u32 s89, s89, s61
	s_bcnt1_i32_b64 s61, s[18:19]
	s_add_u32 s89, s89, s61
	s_cmp_ge_u32 s89, s91
	s_cselect_b32 s33, s57, s33
	s_cmp_eq_u32 s89, s91
	s_cbranch_scc1 .Lref_e5
	s_or_b32 s57, s33, 0x800
	v_cmp_ge_u32_e64 s[8:9], v216, s57
	v_cmp_ge_u32_e64 s[12:13], v217, s57
	v_cmp_ge_u32_e64 s[14:15], v218, s57
	v_cmp_ge_u32_e64 s[16:17], v219, s57
	v_cmp_ge_u32_e64 s[18:19], v220, s57
	s_bcnt1_i32_b64 s89, s[8:9]
	s_bcnt1_i32_b64 s61, s[12:13]
	s_add_u32 s89, s89, s61
	s_bcnt1_i32_b64 s61, s[14:15]
	s_add_u32 s89, s89, s61
	s_bcnt1_i32_b64 s61, s[16:17]
	s_add_u32 s89, s89, s61
	s_bcnt1_i32_b64 s61, s[18:19]
	s_add_u32 s89, s89, s61
	s_cmp_ge_u32 s89, s91
	s_cselect_b32 s33, s57, s33
	s_cmp_eq_u32 s89, s91
	s_cbranch_scc1 .Lref_e5
	s_or_b32 s57, s33, 0x400
	v_cmp_ge_u32_e64 s[8:9], v216, s57
	v_cmp_ge_u32_e64 s[12:13], v217, s57
	v_cmp_ge_u32_e64 s[14:15], v218, s57
	v_cmp_ge_u32_e64 s[16:17], v219, s57
	v_cmp_ge_u32_e64 s[18:19], v220, s57
	s_bcnt1_i32_b64 s89, s[8:9]
	s_bcnt1_i32_b64 s61, s[12:13]
	s_add_u32 s89, s89, s61
	s_bcnt1_i32_b64 s61, s[14:15]
	s_add_u32 s89, s89, s61
	s_bcnt1_i32_b64 s61, s[16:17]
	s_add_u32 s89, s89, s61
	s_bcnt1_i32_b64 s61, s[18:19]
	s_add_u32 s89, s89, s61
	s_cmp_ge_u32 s89, s91
	s_cselect_b32 s33, s57, s33
	s_cmp_eq_u32 s89, s91
	s_cbranch_scc1 .Lref_e5
	s_or_b32 s57, s33, 0x200
	v_cmp_ge_u32_e64 s[8:9], v216, s57
	v_cmp_ge_u32_e64 s[12:13], v217, s57
	v_cmp_ge_u32_e64 s[14:15], v218, s57
	v_cmp_ge_u32_e64 s[16:17], v219, s57
	v_cmp_ge_u32_e64 s[18:19], v220, s57
	s_bcnt1_i32_b64 s89, s[8:9]
	s_bcnt1_i32_b64 s61, s[12:13]
	s_add_u32 s89, s89, s61
	s_bcnt1_i32_b64 s61, s[14:15]
	s_add_u32 s89, s89, s61
	s_bcnt1_i32_b64 s61, s[16:17]
	s_add_u32 s89, s89, s61
	s_bcnt1_i32_b64 s61, s[18:19]
	s_add_u32 s89, s89, s61
	s_cmp_ge_u32 s89, s91
	s_cselect_b32 s33, s57, s33
	s_cmp_eq_u32 s89, s91
	s_cbranch_scc1 .Lref_e5
	s_or_b32 s57, s33, 0x100
	v_cmp_ge_u32_e64 s[8:9], v216, s57
	v_cmp_ge_u32_e64 s[12:13], v217, s57
	v_cmp_ge_u32_e64 s[14:15], v218, s57
	v_cmp_ge_u32_e64 s[16:17], v219, s57
	v_cmp_ge_u32_e64 s[18:19], v220, s57
	s_bcnt1_i32_b64 s89, s[8:9]
	s_bcnt1_i32_b64 s61, s[12:13]
	s_add_u32 s89, s89, s61
	s_bcnt1_i32_b64 s61, s[14:15]
	s_add_u32 s89, s89, s61
	s_bcnt1_i32_b64 s61, s[16:17]
	s_add_u32 s89, s89, s61
	s_bcnt1_i32_b64 s61, s[18:19]
	s_add_u32 s89, s89, s61
	s_cmp_ge_u32 s89, s91
	s_cselect_b32 s33, s57, s33
	s_cmp_eq_u32 s89, s91
	s_cbranch_scc1 .Lref_e5
	s_or_b32 s57, s33, 0x80
	v_cmp_ge_u32_e64 s[8:9], v216, s57
	v_cmp_ge_u32_e64 s[12:13], v217, s57
	v_cmp_ge_u32_e64 s[14:15], v218, s57
	v_cmp_ge_u32_e64 s[16:17], v219, s57
	v_cmp_ge_u32_e64 s[18:19], v220, s57
	s_bcnt1_i32_b64 s89, s[8:9]
	s_bcnt1_i32_b64 s61, s[12:13]
	s_add_u32 s89, s89, s61
	s_bcnt1_i32_b64 s61, s[14:15]
	s_add_u32 s89, s89, s61
	s_bcnt1_i32_b64 s61, s[16:17]
	s_add_u32 s89, s89, s61
	s_bcnt1_i32_b64 s61, s[18:19]
	s_add_u32 s89, s89, s61
	s_cmp_ge_u32 s89, s91
	s_cselect_b32 s33, s57, s33
	s_cmp_eq_u32 s89, s91
	s_cbranch_scc1 .Lref_e5
	s_or_b32 s57, s33, 0x40
	v_cmp_ge_u32_e64 s[8:9], v216, s57
	v_cmp_ge_u32_e64 s[12:13], v217, s57
	v_cmp_ge_u32_e64 s[14:15], v218, s57
	v_cmp_ge_u32_e64 s[16:17], v219, s57
	v_cmp_ge_u32_e64 s[18:19], v220, s57
	s_bcnt1_i32_b64 s89, s[8:9]
	s_bcnt1_i32_b64 s61, s[12:13]
	s_add_u32 s89, s89, s61
	s_bcnt1_i32_b64 s61, s[14:15]
	s_add_u32 s89, s89, s61
	s_bcnt1_i32_b64 s61, s[16:17]
	s_add_u32 s89, s89, s61
	s_bcnt1_i32_b64 s61, s[18:19]
	s_add_u32 s89, s89, s61
	s_cmp_ge_u32 s89, s91
	s_cselect_b32 s33, s57, s33
	s_cmp_eq_u32 s89, s91
	s_cbranch_scc1 .Lref_e5
	s_or_b32 s57, s33, 0x20
	v_cmp_ge_u32_e64 s[8:9], v216, s57
	v_cmp_ge_u32_e64 s[12:13], v217, s57
	v_cmp_ge_u32_e64 s[14:15], v218, s57
	v_cmp_ge_u32_e64 s[16:17], v219, s57
	v_cmp_ge_u32_e64 s[18:19], v220, s57
	s_bcnt1_i32_b64 s89, s[8:9]
	s_bcnt1_i32_b64 s61, s[12:13]
	s_add_u32 s89, s89, s61
	s_bcnt1_i32_b64 s61, s[14:15]
	s_add_u32 s89, s89, s61
	s_bcnt1_i32_b64 s61, s[16:17]
	s_add_u32 s89, s89, s61
	s_bcnt1_i32_b64 s61, s[18:19]
	s_add_u32 s89, s89, s61
	s_cmp_ge_u32 s89, s91
	s_cselect_b32 s33, s57, s33
	s_cmp_eq_u32 s89, s91
	s_cbranch_scc1 .Lref_e5
	s_or_b32 s57, s33, 0x10
	v_cmp_ge_u32_e64 s[8:9], v216, s57
	v_cmp_ge_u32_e64 s[12:13], v217, s57
	v_cmp_ge_u32_e64 s[14:15], v218, s57
	v_cmp_ge_u32_e64 s[16:17], v219, s57
	v_cmp_ge_u32_e64 s[18:19], v220, s57
	s_bcnt1_i32_b64 s89, s[8:9]
	s_bcnt1_i32_b64 s61, s[12:13]
	s_add_u32 s89, s89, s61
	s_bcnt1_i32_b64 s61, s[14:15]
	s_add_u32 s89, s89, s61
	s_bcnt1_i32_b64 s61, s[16:17]
	s_add_u32 s89, s89, s61
	s_bcnt1_i32_b64 s61, s[18:19]
	s_add_u32 s89, s89, s61
	s_cmp_ge_u32 s89, s91
	s_cselect_b32 s33, s57, s33
	s_cmp_eq_u32 s89, s91
	s_cbranch_scc1 .Lref_e5
	s_or_b32 s57, s33, 0x8
	v_cmp_ge_u32_e64 s[8:9], v216, s57
	v_cmp_ge_u32_e64 s[12:13], v217, s57
	v_cmp_ge_u32_e64 s[14:15], v218, s57
	v_cmp_ge_u32_e64 s[16:17], v219, s57
	v_cmp_ge_u32_e64 s[18:19], v220, s57
	s_bcnt1_i32_b64 s89, s[8:9]
	s_bcnt1_i32_b64 s61, s[12:13]
	s_add_u32 s89, s89, s61
	s_bcnt1_i32_b64 s61, s[14:15]
	s_add_u32 s89, s89, s61
	s_bcnt1_i32_b64 s61, s[16:17]
	s_add_u32 s89, s89, s61
	s_bcnt1_i32_b64 s61, s[18:19]
	s_add_u32 s89, s89, s61
	s_cmp_ge_u32 s89, s91
	s_cselect_b32 s33, s57, s33
	s_cmp_eq_u32 s89, s91
	s_cbranch_scc1 .Lref_e5
	s_or_b32 s57, s33, 0x4
	v_cmp_ge_u32_e64 s[8:9], v216, s57
	v_cmp_ge_u32_e64 s[12:13], v217, s57
	v_cmp_ge_u32_e64 s[14:15], v218, s57
	v_cmp_ge_u32_e64 s[16:17], v219, s57
	v_cmp_ge_u32_e64 s[18:19], v220, s57
	s_bcnt1_i32_b64 s89, s[8:9]
	s_bcnt1_i32_b64 s61, s[12:13]
	s_add_u32 s89, s89, s61
	s_bcnt1_i32_b64 s61, s[14:15]
	s_add_u32 s89, s89, s61
	s_bcnt1_i32_b64 s61, s[16:17]
	s_add_u32 s89, s89, s61
	s_bcnt1_i32_b64 s61, s[18:19]
	s_add_u32 s89, s89, s61
	s_cmp_ge_u32 s89, s91
	s_cselect_b32 s33, s57, s33
	s_cmp_eq_u32 s89, s91
	s_cbranch_scc1 .Lref_e5
	s_or_b32 s57, s33, 0x2
	v_cmp_ge_u32_e64 s[8:9], v216, s57
	v_cmp_ge_u32_e64 s[12:13], v217, s57
	v_cmp_ge_u32_e64 s[14:15], v218, s57
	v_cmp_ge_u32_e64 s[16:17], v219, s57
	v_cmp_ge_u32_e64 s[18:19], v220, s57
	s_bcnt1_i32_b64 s89, s[8:9]
	s_bcnt1_i32_b64 s61, s[12:13]
	s_add_u32 s89, s89, s61
	s_bcnt1_i32_b64 s61, s[14:15]
	s_add_u32 s89, s89, s61
	s_bcnt1_i32_b64 s61, s[16:17]
	s_add_u32 s89, s89, s61
	s_bcnt1_i32_b64 s61, s[18:19]
	s_add_u32 s89, s89, s61
	s_cmp_ge_u32 s89, s91
	s_cselect_b32 s33, s57, s33
	s_cmp_eq_u32 s89, s91
	s_cbranch_scc1 .Lref_e5
	s_or_b32 s57, s33, 0x1
	v_cmp_ge_u32_e64 s[8:9], v216, s57
	v_cmp_ge_u32_e64 s[12:13], v217, s57
	v_cmp_ge_u32_e64 s[14:15], v218, s57
	v_cmp_ge_u32_e64 s[16:17], v219, s57
	v_cmp_ge_u32_e64 s[18:19], v220, s57
	s_bcnt1_i32_b64 s89, s[8:9]
	s_bcnt1_i32_b64 s61, s[12:13]
	s_add_u32 s89, s89, s61
	s_bcnt1_i32_b64 s61, s[14:15]
	s_add_u32 s89, s89, s61
	s_bcnt1_i32_b64 s61, s[16:17]
	s_add_u32 s89, s89, s61
	s_bcnt1_i32_b64 s61, s[18:19]
	s_add_u32 s89, s89, s61
	s_cmp_ge_u32 s89, s91
	s_cselect_b32 s33, s57, s33
	s_cmp_eq_u32 s89, s91
	s_cbranch_scc1 .Lref_e5
	v_cmp_gt_u32_e64 s[8:9], v216, s33
	v_cmp_gt_u32_e64 s[12:13], v217, s33
	v_cmp_gt_u32_e64 s[14:15], v218, s33
	v_cmp_gt_u32_e64 s[16:17], v219, s33
	v_cmp_gt_u32_e64 s[18:19], v220, s33
	s_bcnt1_i32_b64 s89, s[8:9]
	s_bcnt1_i32_b64 s61, s[12:13]
	s_add_u32 s89, s89, s61
	s_bcnt1_i32_b64 s61, s[14:15]
	s_add_u32 s89, s89, s61
	s_bcnt1_i32_b64 s61, s[16:17]
	s_add_u32 s89, s89, s61
	s_bcnt1_i32_b64 s61, s[18:19]
	s_add_u32 s89, s89, s61
	s_sub_u32 s91, s91, s89
	v_cmp_eq_u32_e64 s[8:9], v216, s33
	v_cmp_eq_u32_e64 s[12:13], v217, s33
	v_cmp_eq_u32_e64 s[14:15], v218, s33
	v_cmp_eq_u32_e64 s[16:17], v219, s33
	v_cmp_eq_u32_e64 s[18:19], v220, s33
	s_bcnt1_i32_b64 s89, s[8:9]
	s_bcnt1_i32_b64 s61, s[12:13]
	s_add_u32 s89, s89, s61
	s_bcnt1_i32_b64 s61, s[14:15]
	s_add_u32 s89, s89, s61
	s_bcnt1_i32_b64 s61, s[16:17]
	s_add_u32 s89, s89, s61
	s_bcnt1_i32_b64 s61, s[18:19]
	s_add_u32 s89, s89, s61
	s_add_u32 s57, s33, 1
	s_cmp_eq_u32 s91, s89
	s_cselect_b32 s57, s33, s57
	s_cselect_b32 s60, 1, 0
	s_branch .Lref_emit5

.Lref_emit5:
	v_cmp_ge_u32_e64 s[8:9], v216, s57
	v_cmp_ge_u32_e64 s[12:13], v217, s57
	v_cmp_ge_u32_e64 s[14:15], v218, s57
	v_cmp_ge_u32_e64 s[16:17], v219, s57
	v_cmp_ge_u32_e64 s[18:19], v220, s57
	s_nop 1
	v_mbcnt_lo_u32_b32 v241, s8, 0
	v_mbcnt_hi_u32_b32 v241, s9, v241
	v_add_u32_e32 v241, s90, v241
	v_and_b32_e32 v241, 0xff, v241
	v_lshl_add_u32 v241, v241, 1, v246
	s_mov_b64 exec, s[8:9]
	ds_write_b16 v241, v224
	s_mov_b64 exec, -1
	s_bcnt1_i32_b64 s61, s[8:9]
	s_add_u32 s90, s90, s61
	v_mbcnt_lo_u32_b32 v241, s12, 0
	v_mbcnt_hi_u32_b32 v241, s13, v241
	v_add_u32_e32 v241, s90, v241
	v_and_b32_e32 v241, 0xff, v241
	v_lshl_add_u32 v241, v241, 1, v246
	s_mov_b64 exec, s[12:13]
	ds_write_b16 v241, v225
	s_mov_b64 exec, -1
	s_bcnt1_i32_b64 s61, s[12:13]
	s_add_u32 s90, s90, s61
	v_mbcnt_lo_u32_b32 v241, s14, 0
	v_mbcnt_hi_u32_b32 v241, s15, v241
	v_add_u32_e32 v241, s90, v241
	v_and_b32_e32 v241, 0xff, v241
	v_lshl_add_u32 v241, v241, 1, v246
	s_mov_b64 exec, s[14:15]
	ds_write_b16 v241, v226
	s_mov_b64 exec, -1
	s_bcnt1_i32_b64 s61, s[14:15]
	s_add_u32 s90, s90, s61
	v_mbcnt_lo_u32_b32 v241, s16, 0
	v_mbcnt_hi_u32_b32 v241, s17, v241
	v_add_u32_e32 v241, s90, v241
	v_and_b32_e32 v241, 0xff, v241
	v_lshl_add_u32 v241, v241, 1, v246
	s_mov_b64 exec, s[16:17]
	ds_write_b16 v241, v227
	s_mov_b64 exec, -1
	s_bcnt1_i32_b64 s61, s[16:17]
	s_add_u32 s90, s90, s61
	v_mbcnt_lo_u32_b32 v241, s18, 0
	v_mbcnt_hi_u32_b32 v241, s19, v241
	v_add_u32_e32 v241, s90, v241
	v_and_b32_e32 v241, 0xff, v241
	v_lshl_add_u32 v241, v241, 1, v246
	s_mov_b64 exec, s[18:19]
	ds_write_b16 v241, v228
	s_mov_b64 exec, -1
	s_bcnt1_i32_b64 s61, s[18:19]
	s_add_u32 s90, s90, s61
	s_mov_b32 s92, 0
	s_cmp_lg_u32 s60, 0
	s_cbranch_scc1 .Lref_fin
	v_cmp_eq_u32_e64 s[8:9], v216, s33
	v_cmp_eq_u32_e64 s[12:13], v217, s33
	v_cmp_eq_u32_e64 s[14:15], v218, s33
	v_cmp_eq_u32_e64 s[16:17], v219, s33
	v_cmp_eq_u32_e64 s[18:19], v220, s33
	s_nop 1
	v_mbcnt_lo_u32_b32 v241, s8, 0
	v_mbcnt_hi_u32_b32 v241, s9, v241
	v_add_u32_e32 v241, s92, v241
	v_lshl_add_u32 v241, v241, 1, v244
	s_mov_b64 exec, s[8:9]
	ds_write_b16 v241, v224
	s_mov_b64 exec, -1
	s_bcnt1_i32_b64 s61, s[8:9]
	s_add_u32 s92, s92, s61
	v_mbcnt_lo_u32_b32 v241, s12, 0
	v_mbcnt_hi_u32_b32 v241, s13, v241
	v_add_u32_e32 v241, s92, v241
	v_lshl_add_u32 v241, v241, 1, v244
	s_mov_b64 exec, s[12:13]
	ds_write_b16 v241, v225
	s_mov_b64 exec, -1
	s_bcnt1_i32_b64 s61, s[12:13]
	s_add_u32 s92, s92, s61
	v_mbcnt_lo_u32_b32 v241, s14, 0
	v_mbcnt_hi_u32_b32 v241, s15, v241
	v_add_u32_e32 v241, s92, v241
	v_lshl_add_u32 v241, v241, 1, v244
	s_mov_b64 exec, s[14:15]
	ds_write_b16 v241, v226
	s_mov_b64 exec, -1
	s_bcnt1_i32_b64 s61, s[14:15]
	s_add_u32 s92, s92, s61
	v_mbcnt_lo_u32_b32 v241, s16, 0
	v_mbcnt_hi_u32_b32 v241, s17, v241
	v_add_u32_e32 v241, s92, v241
	v_lshl_add_u32 v241, v241, 1, v244
	s_mov_b64 exec, s[16:17]
	ds_write_b16 v241, v227
	s_mov_b64 exec, -1
	s_bcnt1_i32_b64 s61, s[16:17]
	s_add_u32 s92, s92, s61
	v_mbcnt_lo_u32_b32 v241, s18, 0
	v_mbcnt_hi_u32_b32 v241, s19, v241
	v_add_u32_e32 v241, s92, v241
	v_lshl_add_u32 v241, v241, 1, v244
	s_mov_b64 exec, s[18:19]
	ds_write_b16 v241, v228
	s_mov_b64 exec, -1
	s_bcnt1_i32_b64 s61, s[18:19]
	s_add_u32 s92, s92, s61
	s_branch .Lref_fin
.Lref_v4:
	ds_read_b32 v216, v238
	ds_read_u16 v224, v245
	ds_read_b32 v217, v238 offset:256
	ds_read_u16 v225, v245 offset:128
	ds_read_b32 v218, v238 offset:512
	ds_read_u16 v226, v245 offset:256
	ds_read_b32 v219, v238 offset:768
	ds_read_u16 v227, v245 offset:384
	v_cmp_gt_u32_e64 s[8:9], s93, v145
	v_add_u32_e32 v241, 64, v145
	v_cmp_gt_u32_e64 s[12:13], s93, v241
	v_add_u32_e32 v241, 128, v145
	v_cmp_gt_u32_e64 s[14:15], s93, v241
	v_add_u32_e32 v241, 192, v145
	v_cmp_gt_u32_e64 s[16:17], s93, v241
	s_waitcnt lgkmcnt(0)
	v_cndmask_b32_e64 v216, 0, v216, s[8:9]
	v_cndmask_b32_e64 v217, 0, v217, s[12:13]
	v_cndmask_b32_e64 v218, 0, v218, s[14:15]
	v_cndmask_b32_e64 v219, 0, v219, s[16:17]
	s_or_b32 s57, s33, 0x100000
	v_cmp_ge_u32_e64 s[8:9], v216, s57
	v_cmp_ge_u32_e64 s[12:13], v217, s57
	v_cmp_ge_u32_e64 s[14:15], v218, s57
	v_cmp_ge_u32_e64 s[16:17], v219, s57
	s_bcnt1_i32_b64 s89, s[8:9]
	s_bcnt1_i32_b64 s61, s[12:13]
	s_add_u32 s89, s89, s61
	s_bcnt1_i32_b64 s61, s[14:15]
	s_add_u32 s89, s89, s61
	s_bcnt1_i32_b64 s61, s[16:17]
	s_add_u32 s89, s89, s61
	s_cmp_ge_u32 s89, s91
	s_cselect_b32 s33, s57, s33
	s_cmp_eq_u32 s89, s91
	s_cbranch_scc1 .Lref_e4
	s_or_b32 s57, s33, 0x80000
	v_cmp_ge_u32_e64 s[8:9], v216, s57
	v_cmp_ge_u32_e64 s[12:13], v217, s57
	v_cmp_ge_u32_e64 s[14:15], v218, s57
	v_cmp_ge_u32_e64 s[16:17], v219, s57
	s_bcnt1_i32_b64 s89, s[8:9]
	s_bcnt1_i32_b64 s61, s[12:13]
	s_add_u32 s89, s89, s61
	s_bcnt1_i32_b64 s61, s[14:15]
	s_add_u32 s89, s89, s61
	s_bcnt1_i32_b64 s61, s[16:17]
	s_add_u32 s89, s89, s61
	s_cmp_ge_u32 s89, s91
	s_cselect_b32 s33, s57, s33
	s_cmp_eq_u32 s89, s91
	s_cbranch_scc1 .Lref_e4
	s_or_b32 s57, s33, 0x40000
	v_cmp_ge_u32_e64 s[8:9], v216, s57
	v_cmp_ge_u32_e64 s[12:13], v217, s57
	v_cmp_ge_u32_e64 s[14:15], v218, s57
	v_cmp_ge_u32_e64 s[16:17], v219, s57
	s_bcnt1_i32_b64 s89, s[8:9]
	s_bcnt1_i32_b64 s61, s[12:13]
	s_add_u32 s89, s89, s61
	s_bcnt1_i32_b64 s61, s[14:15]
	s_add_u32 s89, s89, s61
	s_bcnt1_i32_b64 s61, s[16:17]
	s_add_u32 s89, s89, s61
	s_cmp_ge_u32 s89, s91
	s_cselect_b32 s33, s57, s33
	s_cmp_eq_u32 s89, s91
	s_cbranch_scc1 .Lref_e4
	s_or_b32 s57, s33, 0x20000
	v_cmp_ge_u32_e64 s[8:9], v216, s57
	v_cmp_ge_u32_e64 s[12:13], v217, s57
	v_cmp_ge_u32_e64 s[14:15], v218, s57
	v_cmp_ge_u32_e64 s[16:17], v219, s57
	s_bcnt1_i32_b64 s89, s[8:9]
	s_bcnt1_i32_b64 s61, s[12:13]
	s_add_u32 s89, s89, s61
	s_bcnt1_i32_b64 s61, s[14:15]
	s_add_u32 s89, s89, s61
	s_bcnt1_i32_b64 s61, s[16:17]
	s_add_u32 s89, s89, s61
	s_cmp_ge_u32 s89, s91
	s_cselect_b32 s33, s57, s33
	s_cmp_eq_u32 s89, s91
	s_cbranch_scc1 .Lref_e4
	s_or_b32 s57, s33, 0x10000
	v_cmp_ge_u32_e64 s[8:9], v216, s57
	v_cmp_ge_u32_e64 s[12:13], v217, s57
	v_cmp_ge_u32_e64 s[14:15], v218, s57
	v_cmp_ge_u32_e64 s[16:17], v219, s57
	s_bcnt1_i32_b64 s89, s[8:9]
	s_bcnt1_i32_b64 s61, s[12:13]
	s_add_u32 s89, s89, s61
	s_bcnt1_i32_b64 s61, s[14:15]
	s_add_u32 s89, s89, s61
	s_bcnt1_i32_b64 s61, s[16:17]
	s_add_u32 s89, s89, s61
	s_cmp_ge_u32 s89, s91
	s_cselect_b32 s33, s57, s33
	s_cmp_eq_u32 s89, s91
	s_cbranch_scc1 .Lref_e4
	s_or_b32 s57, s33, 0x8000
	v_cmp_ge_u32_e64 s[8:9], v216, s57
	v_cmp_ge_u32_e64 s[12:13], v217, s57
	v_cmp_ge_u32_e64 s[14:15], v218, s57
	v_cmp_ge_u32_e64 s[16:17], v219, s57
	s_bcnt1_i32_b64 s89, s[8:9]
	s_bcnt1_i32_b64 s61, s[12:13]
	s_add_u32 s89, s89, s61
	s_bcnt1_i32_b64 s61, s[14:15]
	s_add_u32 s89, s89, s61
	s_bcnt1_i32_b64 s61, s[16:17]
	s_add_u32 s89, s89, s61
	s_cmp_ge_u32 s89, s91
	s_cselect_b32 s33, s57, s33
	s_cmp_eq_u32 s89, s91
	s_cbranch_scc1 .Lref_e4
	s_or_b32 s57, s33, 0x4000
	v_cmp_ge_u32_e64 s[8:9], v216, s57
	v_cmp_ge_u32_e64 s[12:13], v217, s57
	v_cmp_ge_u32_e64 s[14:15], v218, s57
	v_cmp_ge_u32_e64 s[16:17], v219, s57
	s_bcnt1_i32_b64 s89, s[8:9]
	s_bcnt1_i32_b64 s61, s[12:13]
	s_add_u32 s89, s89, s61
	s_bcnt1_i32_b64 s61, s[14:15]
	s_add_u32 s89, s89, s61
	s_bcnt1_i32_b64 s61, s[16:17]
	s_add_u32 s89, s89, s61
	s_cmp_ge_u32 s89, s91
	s_cselect_b32 s33, s57, s33
	s_cmp_eq_u32 s89, s91
	s_cbranch_scc1 .Lref_e4
	s_or_b32 s57, s33, 0x2000
	v_cmp_ge_u32_e64 s[8:9], v216, s57
	v_cmp_ge_u32_e64 s[12:13], v217, s57
	v_cmp_ge_u32_e64 s[14:15], v218, s57
	v_cmp_ge_u32_e64 s[16:17], v219, s57
	s_bcnt1_i32_b64 s89, s[8:9]
	s_bcnt1_i32_b64 s61, s[12:13]
	s_add_u32 s89, s89, s61
	s_bcnt1_i32_b64 s61, s[14:15]
	s_add_u32 s89, s89, s61
	s_bcnt1_i32_b64 s61, s[16:17]
	s_add_u32 s89, s89, s61
	s_cmp_ge_u32 s89, s91
	s_cselect_b32 s33, s57, s33
	s_cmp_eq_u32 s89, s91
	s_cbranch_scc1 .Lref_e4
	s_or_b32 s57, s33, 0x1000
	v_cmp_ge_u32_e64 s[8:9], v216, s57
	v_cmp_ge_u32_e64 s[12:13], v217, s57
	v_cmp_ge_u32_e64 s[14:15], v218, s57
	v_cmp_ge_u32_e64 s[16:17], v219, s57
	s_bcnt1_i32_b64 s89, s[8:9]
	s_bcnt1_i32_b64 s61, s[12:13]
	s_add_u32 s89, s89, s61
	s_bcnt1_i32_b64 s61, s[14:15]
	s_add_u32 s89, s89, s61
	s_bcnt1_i32_b64 s61, s[16:17]
	s_add_u32 s89, s89, s61
	s_cmp_ge_u32 s89, s91
	s_cselect_b32 s33, s57, s33
	s_cmp_eq_u32 s89, s91
	s_cbranch_scc1 .Lref_e4
	s_or_b32 s57, s33, 0x800
	v_cmp_ge_u32_e64 s[8:9], v216, s57
	v_cmp_ge_u32_e64 s[12:13], v217, s57
	v_cmp_ge_u32_e64 s[14:15], v218, s57
	v_cmp_ge_u32_e64 s[16:17], v219, s57
	s_bcnt1_i32_b64 s89, s[8:9]
	s_bcnt1_i32_b64 s61, s[12:13]
	s_add_u32 s89, s89, s61
	s_bcnt1_i32_b64 s61, s[14:15]
	s_add_u32 s89, s89, s61
	s_bcnt1_i32_b64 s61, s[16:17]
	s_add_u32 s89, s89, s61
	s_cmp_ge_u32 s89, s91
	s_cselect_b32 s33, s57, s33
	s_cmp_eq_u32 s89, s91
	s_cbranch_scc1 .Lref_e4
	s_or_b32 s57, s33, 0x400
	v_cmp_ge_u32_e64 s[8:9], v216, s57
	v_cmp_ge_u32_e64 s[12:13], v217, s57
	v_cmp_ge_u32_e64 s[14:15], v218, s57
	v_cmp_ge_u32_e64 s[16:17], v219, s57
	s_bcnt1_i32_b64 s89, s[8:9]
	s_bcnt1_i32_b64 s61, s[12:13]
	s_add_u32 s89, s89, s61
	s_bcnt1_i32_b64 s61, s[14:15]
	s_add_u32 s89, s89, s61
	s_bcnt1_i32_b64 s61, s[16:17]
	s_add_u32 s89, s89, s61
	s_cmp_ge_u32 s89, s91
	s_cselect_b32 s33, s57, s33
	s_cmp_eq_u32 s89, s91
	s_cbranch_scc1 .Lref_e4
	s_or_b32 s57, s33, 0x200
	v_cmp_ge_u32_e64 s[8:9], v216, s57
	v_cmp_ge_u32_e64 s[12:13], v217, s57
	v_cmp_ge_u32_e64 s[14:15], v218, s57
	v_cmp_ge_u32_e64 s[16:17], v219, s57
	s_bcnt1_i32_b64 s89, s[8:9]
	s_bcnt1_i32_b64 s61, s[12:13]
	s_add_u32 s89, s89, s61
	s_bcnt1_i32_b64 s61, s[14:15]
	s_add_u32 s89, s89, s61
	s_bcnt1_i32_b64 s61, s[16:17]
	s_add_u32 s89, s89, s61
	s_cmp_ge_u32 s89, s91
	s_cselect_b32 s33, s57, s33
	s_cmp_eq_u32 s89, s91
	s_cbranch_scc1 .Lref_e4
	s_or_b32 s57, s33, 0x100
	v_cmp_ge_u32_e64 s[8:9], v216, s57
	v_cmp_ge_u32_e64 s[12:13], v217, s57
	v_cmp_ge_u32_e64 s[14:15], v218, s57
	v_cmp_ge_u32_e64 s[16:17], v219, s57
	s_bcnt1_i32_b64 s89, s[8:9]
	s_bcnt1_i32_b64 s61, s[12:13]
	s_add_u32 s89, s89, s61
	s_bcnt1_i32_b64 s61, s[14:15]
	s_add_u32 s89, s89, s61
	s_bcnt1_i32_b64 s61, s[16:17]
	s_add_u32 s89, s89, s61
	s_cmp_ge_u32 s89, s91
	s_cselect_b32 s33, s57, s33
	s_cmp_eq_u32 s89, s91
	s_cbranch_scc1 .Lref_e4
	s_or_b32 s57, s33, 0x80
	v_cmp_ge_u32_e64 s[8:9], v216, s57
	v_cmp_ge_u32_e64 s[12:13], v217, s57
	v_cmp_ge_u32_e64 s[14:15], v218, s57
	v_cmp_ge_u32_e64 s[16:17], v219, s57
	s_bcnt1_i32_b64 s89, s[8:9]
	s_bcnt1_i32_b64 s61, s[12:13]
	s_add_u32 s89, s89, s61
	s_bcnt1_i32_b64 s61, s[14:15]
	s_add_u32 s89, s89, s61
	s_bcnt1_i32_b64 s61, s[16:17]
	s_add_u32 s89, s89, s61
	s_cmp_ge_u32 s89, s91
	s_cselect_b32 s33, s57, s33
	s_cmp_eq_u32 s89, s91
	s_cbranch_scc1 .Lref_e4
	s_or_b32 s57, s33, 0x40
	v_cmp_ge_u32_e64 s[8:9], v216, s57
	v_cmp_ge_u32_e64 s[12:13], v217, s57
	v_cmp_ge_u32_e64 s[14:15], v218, s57
	v_cmp_ge_u32_e64 s[16:17], v219, s57
	s_bcnt1_i32_b64 s89, s[8:9]
	s_bcnt1_i32_b64 s61, s[12:13]
	s_add_u32 s89, s89, s61
	s_bcnt1_i32_b64 s61, s[14:15]
	s_add_u32 s89, s89, s61
	s_bcnt1_i32_b64 s61, s[16:17]
	s_add_u32 s89, s89, s61
	s_cmp_ge_u32 s89, s91
	s_cselect_b32 s33, s57, s33
	s_cmp_eq_u32 s89, s91
	s_cbranch_scc1 .Lref_e4
	s_or_b32 s57, s33, 0x20
	v_cmp_ge_u32_e64 s[8:9], v216, s57
	v_cmp_ge_u32_e64 s[12:13], v217, s57
	v_cmp_ge_u32_e64 s[14:15], v218, s57
	v_cmp_ge_u32_e64 s[16:17], v219, s57
	s_bcnt1_i32_b64 s89, s[8:9]
	s_bcnt1_i32_b64 s61, s[12:13]
	s_add_u32 s89, s89, s61
	s_bcnt1_i32_b64 s61, s[14:15]
	s_add_u32 s89, s89, s61
	s_bcnt1_i32_b64 s61, s[16:17]
	s_add_u32 s89, s89, s61
	s_cmp_ge_u32 s89, s91
	s_cselect_b32 s33, s57, s33
	s_cmp_eq_u32 s89, s91
	s_cbranch_scc1 .Lref_e4
	s_or_b32 s57, s33, 0x10
	v_cmp_ge_u32_e64 s[8:9], v216, s57
	v_cmp_ge_u32_e64 s[12:13], v217, s57
	v_cmp_ge_u32_e64 s[14:15], v218, s57
	v_cmp_ge_u32_e64 s[16:17], v219, s57
	s_bcnt1_i32_b64 s89, s[8:9]
	s_bcnt1_i32_b64 s61, s[12:13]
	s_add_u32 s89, s89, s61
	s_bcnt1_i32_b64 s61, s[14:15]
	s_add_u32 s89, s89, s61
	s_bcnt1_i32_b64 s61, s[16:17]
	s_add_u32 s89, s89, s61
	s_cmp_ge_u32 s89, s91
	s_cselect_b32 s33, s57, s33
	s_cmp_eq_u32 s89, s91
	s_cbranch_scc1 .Lref_e4
	s_or_b32 s57, s33, 0x8
	v_cmp_ge_u32_e64 s[8:9], v216, s57
	v_cmp_ge_u32_e64 s[12:13], v217, s57
	v_cmp_ge_u32_e64 s[14:15], v218, s57
	v_cmp_ge_u32_e64 s[16:17], v219, s57
	s_bcnt1_i32_b64 s89, s[8:9]
	s_bcnt1_i32_b64 s61, s[12:13]
	s_add_u32 s89, s89, s61
	s_bcnt1_i32_b64 s61, s[14:15]
	s_add_u32 s89, s89, s61
	s_bcnt1_i32_b64 s61, s[16:17]
	s_add_u32 s89, s89, s61
	s_cmp_ge_u32 s89, s91
	s_cselect_b32 s33, s57, s33
	s_cmp_eq_u32 s89, s91
	s_cbranch_scc1 .Lref_e4
	s_or_b32 s57, s33, 0x4
	v_cmp_ge_u32_e64 s[8:9], v216, s57
	v_cmp_ge_u32_e64 s[12:13], v217, s57
	v_cmp_ge_u32_e64 s[14:15], v218, s57
	v_cmp_ge_u32_e64 s[16:17], v219, s57
	s_bcnt1_i32_b64 s89, s[8:9]
	s_bcnt1_i32_b64 s61, s[12:13]
	s_add_u32 s89, s89, s61
	s_bcnt1_i32_b64 s61, s[14:15]
	s_add_u32 s89, s89, s61
	s_bcnt1_i32_b64 s61, s[16:17]
	s_add_u32 s89, s89, s61
	s_cmp_ge_u32 s89, s91
	s_cselect_b32 s33, s57, s33
	s_cmp_eq_u32 s89, s91
	s_cbranch_scc1 .Lref_e4
	s_or_b32 s57, s33, 0x2
	v_cmp_ge_u32_e64 s[8:9], v216, s57
	v_cmp_ge_u32_e64 s[12:13], v217, s57
	v_cmp_ge_u32_e64 s[14:15], v218, s57
	v_cmp_ge_u32_e64 s[16:17], v219, s57
	s_bcnt1_i32_b64 s89, s[8:9]
	s_bcnt1_i32_b64 s61, s[12:13]
	s_add_u32 s89, s89, s61
	s_bcnt1_i32_b64 s61, s[14:15]
	s_add_u32 s89, s89, s61
	s_bcnt1_i32_b64 s61, s[16:17]
	s_add_u32 s89, s89, s61
	s_cmp_ge_u32 s89, s91
	s_cselect_b32 s33, s57, s33
	s_cmp_eq_u32 s89, s91
	s_cbranch_scc1 .Lref_e4
	s_or_b32 s57, s33, 0x1
	v_cmp_ge_u32_e64 s[8:9], v216, s57
	v_cmp_ge_u32_e64 s[12:13], v217, s57
	v_cmp_ge_u32_e64 s[14:15], v218, s57
	v_cmp_ge_u32_e64 s[16:17], v219, s57
	s_bcnt1_i32_b64 s89, s[8:9]
	s_bcnt1_i32_b64 s61, s[12:13]
	s_add_u32 s89, s89, s61
	s_bcnt1_i32_b64 s61, s[14:15]
	s_add_u32 s89, s89, s61
	s_bcnt1_i32_b64 s61, s[16:17]
	s_add_u32 s89, s89, s61
	s_cmp_ge_u32 s89, s91
	s_cselect_b32 s33, s57, s33
	s_cmp_eq_u32 s89, s91
	s_cbranch_scc1 .Lref_e4
	v_cmp_gt_u32_e64 s[8:9], v216, s33
	v_cmp_gt_u32_e64 s[12:13], v217, s33
	v_cmp_gt_u32_e64 s[14:15], v218, s33
	v_cmp_gt_u32_e64 s[16:17], v219, s33
	s_bcnt1_i32_b64 s89, s[8:9]
	s_bcnt1_i32_b64 s61, s[12:13]
	s_add_u32 s89, s89, s61
	s_bcnt1_i32_b64 s61, s[14:15]
	s_add_u32 s89, s89, s61
	s_bcnt1_i32_b64 s61, s[16:17]
	s_add_u32 s89, s89, s61
	s_sub_u32 s91, s91, s89
	v_cmp_eq_u32_e64 s[8:9], v216, s33
	v_cmp_eq_u32_e64 s[12:13], v217, s33
	v_cmp_eq_u32_e64 s[14:15], v218, s33
	v_cmp_eq_u32_e64 s[16:17], v219, s33
	s_bcnt1_i32_b64 s89, s[8:9]
	s_bcnt1_i32_b64 s61, s[12:13]
	s_add_u32 s89, s89, s61
	s_bcnt1_i32_b64 s61, s[14:15]
	s_add_u32 s89, s89, s61
	s_bcnt1_i32_b64 s61, s[16:17]
	s_add_u32 s89, s89, s61
	s_add_u32 s57, s33, 1
	s_cmp_eq_u32 s91, s89
	s_cselect_b32 s57, s33, s57
	s_cselect_b32 s60, 1, 0
	s_branch .Lref_emit4

.Lref_emit4:
	v_cmp_ge_u32_e64 s[8:9], v216, s57
	v_cmp_ge_u32_e64 s[12:13], v217, s57
	v_cmp_ge_u32_e64 s[14:15], v218, s57
	v_cmp_ge_u32_e64 s[16:17], v219, s57
	s_nop 1
	v_mbcnt_lo_u32_b32 v241, s8, 0
	v_mbcnt_hi_u32_b32 v241, s9, v241
	v_add_u32_e32 v241, s90, v241
	v_and_b32_e32 v241, 0xff, v241
	v_lshl_add_u32 v241, v241, 1, v246
	s_mov_b64 exec, s[8:9]
	ds_write_b16 v241, v224
	s_mov_b64 exec, -1
	s_bcnt1_i32_b64 s61, s[8:9]
	s_add_u32 s90, s90, s61
	v_mbcnt_lo_u32_b32 v241, s12, 0
	v_mbcnt_hi_u32_b32 v241, s13, v241
	v_add_u32_e32 v241, s90, v241
	v_and_b32_e32 v241, 0xff, v241
	v_lshl_add_u32 v241, v241, 1, v246
	s_mov_b64 exec, s[12:13]
	ds_write_b16 v241, v225
	s_mov_b64 exec, -1
	s_bcnt1_i32_b64 s61, s[12:13]
	s_add_u32 s90, s90, s61
	v_mbcnt_lo_u32_b32 v241, s14, 0
	v_mbcnt_hi_u32_b32 v241, s15, v241
	v_add_u32_e32 v241, s90, v241
	v_and_b32_e32 v241, 0xff, v241
	v_lshl_add_u32 v241, v241, 1, v246
	s_mov_b64 exec, s[14:15]
	ds_write_b16 v241, v226
	s_mov_b64 exec, -1
	s_bcnt1_i32_b64 s61, s[14:15]
	s_add_u32 s90, s90, s61
	v_mbcnt_lo_u32_b32 v241, s16, 0
	v_mbcnt_hi_u32_b32 v241, s17, v241
	v_add_u32_e32 v241, s90, v241
	v_and_b32_e32 v241, 0xff, v241
	v_lshl_add_u32 v241, v241, 1, v246
	s_mov_b64 exec, s[16:17]
	ds_write_b16 v241, v227
	s_mov_b64 exec, -1
	s_bcnt1_i32_b64 s61, s[16:17]
	s_add_u32 s90, s90, s61
	s_mov_b32 s92, 0
	s_cmp_lg_u32 s60, 0
	s_cbranch_scc1 .Lref_fin
	v_cmp_eq_u32_e64 s[8:9], v216, s33
	v_cmp_eq_u32_e64 s[12:13], v217, s33
	v_cmp_eq_u32_e64 s[14:15], v218, s33
	v_cmp_eq_u32_e64 s[16:17], v219, s33
	s_nop 1
	v_mbcnt_lo_u32_b32 v241, s8, 0
	v_mbcnt_hi_u32_b32 v241, s9, v241
	v_add_u32_e32 v241, s92, v241
	v_lshl_add_u32 v241, v241, 1, v244
	s_mov_b64 exec, s[8:9]
	ds_write_b16 v241, v224
	s_mov_b64 exec, -1
	s_bcnt1_i32_b64 s61, s[8:9]
	s_add_u32 s92, s92, s61
	v_mbcnt_lo_u32_b32 v241, s12, 0
	v_mbcnt_hi_u32_b32 v241, s13, v241
	v_add_u32_e32 v241, s92, v241
	v_lshl_add_u32 v241, v241, 1, v244
	s_mov_b64 exec, s[12:13]
	ds_write_b16 v241, v225
	s_mov_b64 exec, -1
	s_bcnt1_i32_b64 s61, s[12:13]
	s_add_u32 s92, s92, s61
	v_mbcnt_lo_u32_b32 v241, s14, 0
	v_mbcnt_hi_u32_b32 v241, s15, v241
	v_add_u32_e32 v241, s92, v241
	v_lshl_add_u32 v241, v241, 1, v244
	s_mov_b64 exec, s[14:15]
	ds_write_b16 v241, v226
	s_mov_b64 exec, -1
	s_bcnt1_i32_b64 s61, s[14:15]
	s_add_u32 s92, s92, s61
	v_mbcnt_lo_u32_b32 v241, s16, 0
	v_mbcnt_hi_u32_b32 v241, s17, v241
	v_add_u32_e32 v241, s92, v241
	v_lshl_add_u32 v241, v241, 1, v244
	s_mov_b64 exec, s[16:17]
	ds_write_b16 v241, v227
	s_mov_b64 exec, -1
	s_bcnt1_i32_b64 s61, s[16:17]
	s_add_u32 s92, s92, s61
	s_branch .Lref_fin
.Lref_v3:
	ds_read_b32 v216, v238
	ds_read_u16 v224, v245
	ds_read_b32 v217, v238 offset:256
	ds_read_u16 v225, v245 offset:128
	ds_read_b32 v218, v238 offset:512
	ds_read_u16 v226, v245 offset:256
	v_cmp_gt_u32_e64 s[8:9], s93, v145
	v_add_u32_e32 v241, 64, v145
	v_cmp_gt_u32_e64 s[12:13], s93, v241
	v_add_u32_e32 v241, 128, v145
	v_cmp_gt_u32_e64 s[14:15], s93, v241
	s_waitcnt lgkmcnt(0)
	v_cndmask_b32_e64 v216, 0, v216, s[8:9]
	v_cndmask_b32_e64 v217, 0, v217, s[12:13]
	v_cndmask_b32_e64 v218, 0, v218, s[14:15]
	s_or_b32 s57, s33, 0x100000
	v_cmp_ge_u32_e64 s[8:9], v216, s57
	v_cmp_ge_u32_e64 s[12:13], v217, s57
	v_cmp_ge_u32_e64 s[14:15], v218, s57
	s_bcnt1_i32_b64 s89, s[8:9]
	s_bcnt1_i32_b64 s61, s[12:13]
	s_add_u32 s89, s89, s61
	s_bcnt1_i32_b64 s61, s[14:15]
	s_add_u32 s89, s89, s61
	s_cmp_ge_u32 s89, s91
	s_cselect_b32 s33, s57, s33
	s_cmp_eq_u32 s89, s91
	s_cbranch_scc1 .Lref_e3
	s_or_b32 s57, s33, 0x80000
	v_cmp_ge_u32_e64 s[8:9], v216, s57
	v_cmp_ge_u32_e64 s[12:13], v217, s57
	v_cmp_ge_u32_e64 s[14:15], v218, s57
	s_bcnt1_i32_b64 s89, s[8:9]
	s_bcnt1_i32_b64 s61, s[12:13]
	s_add_u32 s89, s89, s61
	s_bcnt1_i32_b64 s61, s[14:15]
	s_add_u32 s89, s89, s61
	s_cmp_ge_u32 s89, s91
	s_cselect_b32 s33, s57, s33
	s_cmp_eq_u32 s89, s91
	s_cbranch_scc1 .Lref_e3
	s_or_b32 s57, s33, 0x40000
	v_cmp_ge_u32_e64 s[8:9], v216, s57
	v_cmp_ge_u32_e64 s[12:13], v217, s57
	v_cmp_ge_u32_e64 s[14:15], v218, s57
	s_bcnt1_i32_b64 s89, s[8:9]
	s_bcnt1_i32_b64 s61, s[12:13]
	s_add_u32 s89, s89, s61
	s_bcnt1_i32_b64 s61, s[14:15]
	s_add_u32 s89, s89, s61
	s_cmp_ge_u32 s89, s91
	s_cselect_b32 s33, s57, s33
	s_cmp_eq_u32 s89, s91
	s_cbranch_scc1 .Lref_e3
	s_or_b32 s57, s33, 0x20000
	v_cmp_ge_u32_e64 s[8:9], v216, s57
	v_cmp_ge_u32_e64 s[12:13], v217, s57
	v_cmp_ge_u32_e64 s[14:15], v218, s57
	s_bcnt1_i32_b64 s89, s[8:9]
	s_bcnt1_i32_b64 s61, s[12:13]
	s_add_u32 s89, s89, s61
	s_bcnt1_i32_b64 s61, s[14:15]
	s_add_u32 s89, s89, s61
	s_cmp_ge_u32 s89, s91
	s_cselect_b32 s33, s57, s33
	s_cmp_eq_u32 s89, s91
	s_cbranch_scc1 .Lref_e3
	s_or_b32 s57, s33, 0x10000
	v_cmp_ge_u32_e64 s[8:9], v216, s57
	v_cmp_ge_u32_e64 s[12:13], v217, s57
	v_cmp_ge_u32_e64 s[14:15], v218, s57
	s_bcnt1_i32_b64 s89, s[8:9]
	s_bcnt1_i32_b64 s61, s[12:13]
	s_add_u32 s89, s89, s61
	s_bcnt1_i32_b64 s61, s[14:15]
	s_add_u32 s89, s89, s61
	s_cmp_ge_u32 s89, s91
	s_cselect_b32 s33, s57, s33
	s_cmp_eq_u32 s89, s91
	s_cbranch_scc1 .Lref_e3
	s_or_b32 s57, s33, 0x8000
	v_cmp_ge_u32_e64 s[8:9], v216, s57
	v_cmp_ge_u32_e64 s[12:13], v217, s57
	v_cmp_ge_u32_e64 s[14:15], v218, s57
	s_bcnt1_i32_b64 s89, s[8:9]
	s_bcnt1_i32_b64 s61, s[12:13]
	s_add_u32 s89, s89, s61
	s_bcnt1_i32_b64 s61, s[14:15]
	s_add_u32 s89, s89, s61
	s_cmp_ge_u32 s89, s91
	s_cselect_b32 s33, s57, s33
	s_cmp_eq_u32 s89, s91
	s_cbranch_scc1 .Lref_e3
	s_or_b32 s57, s33, 0x4000
	v_cmp_ge_u32_e64 s[8:9], v216, s57
	v_cmp_ge_u32_e64 s[12:13], v217, s57
	v_cmp_ge_u32_e64 s[14:15], v218, s57
	s_bcnt1_i32_b64 s89, s[8:9]
	s_bcnt1_i32_b64 s61, s[12:13]
	s_add_u32 s89, s89, s61
	s_bcnt1_i32_b64 s61, s[14:15]
	s_add_u32 s89, s89, s61
	s_cmp_ge_u32 s89, s91
	s_cselect_b32 s33, s57, s33
	s_cmp_eq_u32 s89, s91
	s_cbranch_scc1 .Lref_e3
	s_or_b32 s57, s33, 0x2000
	v_cmp_ge_u32_e64 s[8:9], v216, s57
	v_cmp_ge_u32_e64 s[12:13], v217, s57
	v_cmp_ge_u32_e64 s[14:15], v218, s57
	s_bcnt1_i32_b64 s89, s[8:9]
	s_bcnt1_i32_b64 s61, s[12:13]
	s_add_u32 s89, s89, s61
	s_bcnt1_i32_b64 s61, s[14:15]
	s_add_u32 s89, s89, s61
	s_cmp_ge_u32 s89, s91
	s_cselect_b32 s33, s57, s33
	s_cmp_eq_u32 s89, s91
	s_cbranch_scc1 .Lref_e3
	s_or_b32 s57, s33, 0x1000
	v_cmp_ge_u32_e64 s[8:9], v216, s57
	v_cmp_ge_u32_e64 s[12:13], v217, s57
	v_cmp_ge_u32_e64 s[14:15], v218, s57
	s_bcnt1_i32_b64 s89, s[8:9]
	s_bcnt1_i32_b64 s61, s[12:13]
	s_add_u32 s89, s89, s61
	s_bcnt1_i32_b64 s61, s[14:15]
	s_add_u32 s89, s89, s61
	s_cmp_ge_u32 s89, s91
	s_cselect_b32 s33, s57, s33
	s_cmp_eq_u32 s89, s91
	s_cbranch_scc1 .Lref_e3
	s_or_b32 s57, s33, 0x800
	v_cmp_ge_u32_e64 s[8:9], v216, s57
	v_cmp_ge_u32_e64 s[12:13], v217, s57
	v_cmp_ge_u32_e64 s[14:15], v218, s57
	s_bcnt1_i32_b64 s89, s[8:9]
	s_bcnt1_i32_b64 s61, s[12:13]
	s_add_u32 s89, s89, s61
	s_bcnt1_i32_b64 s61, s[14:15]
	s_add_u32 s89, s89, s61
	s_cmp_ge_u32 s89, s91
	s_cselect_b32 s33, s57, s33
	s_cmp_eq_u32 s89, s91
	s_cbranch_scc1 .Lref_e3
	s_or_b32 s57, s33, 0x400
	v_cmp_ge_u32_e64 s[8:9], v216, s57
	v_cmp_ge_u32_e64 s[12:13], v217, s57
	v_cmp_ge_u32_e64 s[14:15], v218, s57
	s_bcnt1_i32_b64 s89, s[8:9]
	s_bcnt1_i32_b64 s61, s[12:13]
	s_add_u32 s89, s89, s61
	s_bcnt1_i32_b64 s61, s[14:15]
	s_add_u32 s89, s89, s61
	s_cmp_ge_u32 s89, s91
	s_cselect_b32 s33, s57, s33
	s_cmp_eq_u32 s89, s91
	s_cbranch_scc1 .Lref_e3
	s_or_b32 s57, s33, 0x200
	v_cmp_ge_u32_e64 s[8:9], v216, s57
	v_cmp_ge_u32_e64 s[12:13], v217, s57
	v_cmp_ge_u32_e64 s[14:15], v218, s57
	s_bcnt1_i32_b64 s89, s[8:9]
	s_bcnt1_i32_b64 s61, s[12:13]
	s_add_u32 s89, s89, s61
	s_bcnt1_i32_b64 s61, s[14:15]
	s_add_u32 s89, s89, s61
	s_cmp_ge_u32 s89, s91
	s_cselect_b32 s33, s57, s33
	s_cmp_eq_u32 s89, s91
	s_cbranch_scc1 .Lref_e3
	s_or_b32 s57, s33, 0x100
	v_cmp_ge_u32_e64 s[8:9], v216, s57
	v_cmp_ge_u32_e64 s[12:13], v217, s57
	v_cmp_ge_u32_e64 s[14:15], v218, s57
	s_bcnt1_i32_b64 s89, s[8:9]
	s_bcnt1_i32_b64 s61, s[12:13]
	s_add_u32 s89, s89, s61
	s_bcnt1_i32_b64 s61, s[14:15]
	s_add_u32 s89, s89, s61
	s_cmp_ge_u32 s89, s91
	s_cselect_b32 s33, s57, s33
	s_cmp_eq_u32 s89, s91
	s_cbranch_scc1 .Lref_e3
	s_or_b32 s57, s33, 0x80
	v_cmp_ge_u32_e64 s[8:9], v216, s57
	v_cmp_ge_u32_e64 s[12:13], v217, s57
	v_cmp_ge_u32_e64 s[14:15], v218, s57
	s_bcnt1_i32_b64 s89, s[8:9]
	s_bcnt1_i32_b64 s61, s[12:13]
	s_add_u32 s89, s89, s61
	s_bcnt1_i32_b64 s61, s[14:15]
	s_add_u32 s89, s89, s61
	s_cmp_ge_u32 s89, s91
	s_cselect_b32 s33, s57, s33
	s_cmp_eq_u32 s89, s91
	s_cbranch_scc1 .Lref_e3
	s_or_b32 s57, s33, 0x40
	v_cmp_ge_u32_e64 s[8:9], v216, s57
	v_cmp_ge_u32_e64 s[12:13], v217, s57
	v_cmp_ge_u32_e64 s[14:15], v218, s57
	s_bcnt1_i32_b64 s89, s[8:9]
	s_bcnt1_i32_b64 s61, s[12:13]
	s_add_u32 s89, s89, s61
	s_bcnt1_i32_b64 s61, s[14:15]
	s_add_u32 s89, s89, s61
	s_cmp_ge_u32 s89, s91
	s_cselect_b32 s33, s57, s33
	s_cmp_eq_u32 s89, s91
	s_cbranch_scc1 .Lref_e3
	s_or_b32 s57, s33, 0x20
	v_cmp_ge_u32_e64 s[8:9], v216, s57
	v_cmp_ge_u32_e64 s[12:13], v217, s57
	v_cmp_ge_u32_e64 s[14:15], v218, s57
	s_bcnt1_i32_b64 s89, s[8:9]
	s_bcnt1_i32_b64 s61, s[12:13]
	s_add_u32 s89, s89, s61
	s_bcnt1_i32_b64 s61, s[14:15]
	s_add_u32 s89, s89, s61
	s_cmp_ge_u32 s89, s91
	s_cselect_b32 s33, s57, s33
	s_cmp_eq_u32 s89, s91
	s_cbranch_scc1 .Lref_e3
	s_or_b32 s57, s33, 0x10
	v_cmp_ge_u32_e64 s[8:9], v216, s57
	v_cmp_ge_u32_e64 s[12:13], v217, s57
	v_cmp_ge_u32_e64 s[14:15], v218, s57
	s_bcnt1_i32_b64 s89, s[8:9]
	s_bcnt1_i32_b64 s61, s[12:13]
	s_add_u32 s89, s89, s61
	s_bcnt1_i32_b64 s61, s[14:15]
	s_add_u32 s89, s89, s61
	s_cmp_ge_u32 s89, s91
	s_cselect_b32 s33, s57, s33
	s_cmp_eq_u32 s89, s91
	s_cbranch_scc1 .Lref_e3
	s_or_b32 s57, s33, 0x8
	v_cmp_ge_u32_e64 s[8:9], v216, s57
	v_cmp_ge_u32_e64 s[12:13], v217, s57
	v_cmp_ge_u32_e64 s[14:15], v218, s57
	s_bcnt1_i32_b64 s89, s[8:9]
	s_bcnt1_i32_b64 s61, s[12:13]
	s_add_u32 s89, s89, s61
	s_bcnt1_i32_b64 s61, s[14:15]
	s_add_u32 s89, s89, s61
	s_cmp_ge_u32 s89, s91
	s_cselect_b32 s33, s57, s33
	s_cmp_eq_u32 s89, s91
	s_cbranch_scc1 .Lref_e3
	s_or_b32 s57, s33, 0x4
	v_cmp_ge_u32_e64 s[8:9], v216, s57
	v_cmp_ge_u32_e64 s[12:13], v217, s57
	v_cmp_ge_u32_e64 s[14:15], v218, s57
	s_bcnt1_i32_b64 s89, s[8:9]
	s_bcnt1_i32_b64 s61, s[12:13]
	s_add_u32 s89, s89, s61
	s_bcnt1_i32_b64 s61, s[14:15]
	s_add_u32 s89, s89, s61
	s_cmp_ge_u32 s89, s91
	s_cselect_b32 s33, s57, s33
	s_cmp_eq_u32 s89, s91
	s_cbranch_scc1 .Lref_e3
	s_or_b32 s57, s33, 0x2
	v_cmp_ge_u32_e64 s[8:9], v216, s57
	v_cmp_ge_u32_e64 s[12:13], v217, s57
	v_cmp_ge_u32_e64 s[14:15], v218, s57
	s_bcnt1_i32_b64 s89, s[8:9]
	s_bcnt1_i32_b64 s61, s[12:13]
	s_add_u32 s89, s89, s61
	s_bcnt1_i32_b64 s61, s[14:15]
	s_add_u32 s89, s89, s61
	s_cmp_ge_u32 s89, s91
	s_cselect_b32 s33, s57, s33
	s_cmp_eq_u32 s89, s91
	s_cbranch_scc1 .Lref_e3
	s_or_b32 s57, s33, 0x1
	v_cmp_ge_u32_e64 s[8:9], v216, s57
	v_cmp_ge_u32_e64 s[12:13], v217, s57
	v_cmp_ge_u32_e64 s[14:15], v218, s57
	s_bcnt1_i32_b64 s89, s[8:9]
	s_bcnt1_i32_b64 s61, s[12:13]
	s_add_u32 s89, s89, s61
	s_bcnt1_i32_b64 s61, s[14:15]
	s_add_u32 s89, s89, s61
	s_cmp_ge_u32 s89, s91
	s_cselect_b32 s33, s57, s33
	s_cmp_eq_u32 s89, s91
	s_cbranch_scc1 .Lref_e3
	v_cmp_gt_u32_e64 s[8:9], v216, s33
	v_cmp_gt_u32_e64 s[12:13], v217, s33
	v_cmp_gt_u32_e64 s[14:15], v218, s33
	s_bcnt1_i32_b64 s89, s[8:9]
	s_bcnt1_i32_b64 s61, s[12:13]
	s_add_u32 s89, s89, s61
	s_bcnt1_i32_b64 s61, s[14:15]
	s_add_u32 s89, s89, s61
	s_sub_u32 s91, s91, s89
	v_cmp_eq_u32_e64 s[8:9], v216, s33
	v_cmp_eq_u32_e64 s[12:13], v217, s33
	v_cmp_eq_u32_e64 s[14:15], v218, s33
	s_bcnt1_i32_b64 s89, s[8:9]
	s_bcnt1_i32_b64 s61, s[12:13]
	s_add_u32 s89, s89, s61
	s_bcnt1_i32_b64 s61, s[14:15]
	s_add_u32 s89, s89, s61
	s_add_u32 s57, s33, 1
	s_cmp_eq_u32 s91, s89
	s_cselect_b32 s57, s33, s57
	s_cselect_b32 s60, 1, 0
	s_branch .Lref_emit3

.Lref_emit3:
	v_cmp_ge_u32_e64 s[8:9], v216, s57
	v_cmp_ge_u32_e64 s[12:13], v217, s57
	v_cmp_ge_u32_e64 s[14:15], v218, s57
	s_nop 1
	v_mbcnt_lo_u32_b32 v241, s8, 0
	v_mbcnt_hi_u32_b32 v241, s9, v241
	v_add_u32_e32 v241, s90, v241
	v_and_b32_e32 v241, 0xff, v241
	v_lshl_add_u32 v241, v241, 1, v246
	s_mov_b64 exec, s[8:9]
	ds_write_b16 v241, v224
	s_mov_b64 exec, -1
	s_bcnt1_i32_b64 s61, s[8:9]
	s_add_u32 s90, s90, s61
	v_mbcnt_lo_u32_b32 v241, s12, 0
	v_mbcnt_hi_u32_b32 v241, s13, v241
	v_add_u32_e32 v241, s90, v241
	v_and_b32_e32 v241, 0xff, v241
	v_lshl_add_u32 v241, v241, 1, v246
	s_mov_b64 exec, s[12:13]
	ds_write_b16 v241, v225
	s_mov_b64 exec, -1
	s_bcnt1_i32_b64 s61, s[12:13]
	s_add_u32 s90, s90, s61
	v_mbcnt_lo_u32_b32 v241, s14, 0
	v_mbcnt_hi_u32_b32 v241, s15, v241
	v_add_u32_e32 v241, s90, v241
	v_and_b32_e32 v241, 0xff, v241
	v_lshl_add_u32 v241, v241, 1, v246
	s_mov_b64 exec, s[14:15]
	ds_write_b16 v241, v226
	s_mov_b64 exec, -1
	s_bcnt1_i32_b64 s61, s[14:15]
	s_add_u32 s90, s90, s61
	s_mov_b32 s92, 0
	s_cmp_lg_u32 s60, 0
	s_cbranch_scc1 .Lref_fin
	v_cmp_eq_u32_e64 s[8:9], v216, s33
	v_cmp_eq_u32_e64 s[12:13], v217, s33
	v_cmp_eq_u32_e64 s[14:15], v218, s33
	s_nop 1
	v_mbcnt_lo_u32_b32 v241, s8, 0
	v_mbcnt_hi_u32_b32 v241, s9, v241
	v_add_u32_e32 v241, s92, v241
	v_lshl_add_u32 v241, v241, 1, v244
	s_mov_b64 exec, s[8:9]
	ds_write_b16 v241, v224
	s_mov_b64 exec, -1
	s_bcnt1_i32_b64 s61, s[8:9]
	s_add_u32 s92, s92, s61
	v_mbcnt_lo_u32_b32 v241, s12, 0
	v_mbcnt_hi_u32_b32 v241, s13, v241
	v_add_u32_e32 v241, s92, v241
	v_lshl_add_u32 v241, v241, 1, v244
	s_mov_b64 exec, s[12:13]
	ds_write_b16 v241, v225
	s_mov_b64 exec, -1
	s_bcnt1_i32_b64 s61, s[12:13]
	s_add_u32 s92, s92, s61
	v_mbcnt_lo_u32_b32 v241, s14, 0
	v_mbcnt_hi_u32_b32 v241, s15, v241
	v_add_u32_e32 v241, s92, v241
	v_lshl_add_u32 v241, v241, 1, v244
	s_mov_b64 exec, s[14:15]
	ds_write_b16 v241, v226
	s_mov_b64 exec, -1
	s_bcnt1_i32_b64 s61, s[14:15]
	s_add_u32 s92, s92, s61
	s_branch .Lref_fin
.Lref_v2:
	ds_read_b32 v216, v238
	ds_read_u16 v224, v245
	ds_read_b32 v217, v238 offset:256
	ds_read_u16 v225, v245 offset:128
	v_cmp_gt_u32_e64 s[8:9], s93, v145
	v_add_u32_e32 v241, 64, v145
	v_cmp_gt_u32_e64 s[12:13], s93, v241
	s_waitcnt lgkmcnt(0)
	v_cndmask_b32_e64 v216, 0, v216, s[8:9]
	v_cndmask_b32_e64 v217, 0, v217, s[12:13]
	s_or_b32 s57, s33, 0x100000
	v_cmp_ge_u32_e64 s[8:9], v216, s57
	v_cmp_ge_u32_e64 s[12:13], v217, s57
	s_bcnt1_i32_b64 s89, s[8:9]
	s_bcnt1_i32_b64 s61, s[12:13]
	s_add_u32 s89, s89, s61
	s_cmp_ge_u32 s89, s91
	s_cselect_b32 s33, s57, s33
	s_cmp_eq_u32 s89, s91
	s_cbranch_scc1 .Lref_e2
	s_or_b32 s57, s33, 0x80000
	v_cmp_ge_u32_e64 s[8:9], v216, s57
	v_cmp_ge_u32_e64 s[12:13], v217, s57
	s_bcnt1_i32_b64 s89, s[8:9]
	s_bcnt1_i32_b64 s61, s[12:13]
	s_add_u32 s89, s89, s61
	s_cmp_ge_u32 s89, s91
	s_cselect_b32 s33, s57, s33
	s_cmp_eq_u32 s89, s91
	s_cbranch_scc1 .Lref_e2
	s_or_b32 s57, s33, 0x40000
	v_cmp_ge_u32_e64 s[8:9], v216, s57
	v_cmp_ge_u32_e64 s[12:13], v217, s57
	s_bcnt1_i32_b64 s89, s[8:9]
	s_bcnt1_i32_b64 s61, s[12:13]
	s_add_u32 s89, s89, s61
	s_cmp_ge_u32 s89, s91
	s_cselect_b32 s33, s57, s33
	s_cmp_eq_u32 s89, s91
	s_cbranch_scc1 .Lref_e2
	s_or_b32 s57, s33, 0x20000
	v_cmp_ge_u32_e64 s[8:9], v216, s57
	v_cmp_ge_u32_e64 s[12:13], v217, s57
	s_bcnt1_i32_b64 s89, s[8:9]
	s_bcnt1_i32_b64 s61, s[12:13]
	s_add_u32 s89, s89, s61
	s_cmp_ge_u32 s89, s91
	s_cselect_b32 s33, s57, s33
	s_cmp_eq_u32 s89, s91
	s_cbranch_scc1 .Lref_e2
	s_or_b32 s57, s33, 0x10000
	v_cmp_ge_u32_e64 s[8:9], v216, s57
	v_cmp_ge_u32_e64 s[12:13], v217, s57
	s_bcnt1_i32_b64 s89, s[8:9]
	s_bcnt1_i32_b64 s61, s[12:13]
	s_add_u32 s89, s89, s61
	s_cmp_ge_u32 s89, s91
	s_cselect_b32 s33, s57, s33
	s_cmp_eq_u32 s89, s91
	s_cbranch_scc1 .Lref_e2
	s_or_b32 s57, s33, 0x8000
	v_cmp_ge_u32_e64 s[8:9], v216, s57
	v_cmp_ge_u32_e64 s[12:13], v217, s57
	s_bcnt1_i32_b64 s89, s[8:9]
	s_bcnt1_i32_b64 s61, s[12:13]
	s_add_u32 s89, s89, s61
	s_cmp_ge_u32 s89, s91
	s_cselect_b32 s33, s57, s33
	s_cmp_eq_u32 s89, s91
	s_cbranch_scc1 .Lref_e2
	s_or_b32 s57, s33, 0x4000
	v_cmp_ge_u32_e64 s[8:9], v216, s57
	v_cmp_ge_u32_e64 s[12:13], v217, s57
	s_bcnt1_i32_b64 s89, s[8:9]
	s_bcnt1_i32_b64 s61, s[12:13]
	s_add_u32 s89, s89, s61
	s_cmp_ge_u32 s89, s91
	s_cselect_b32 s33, s57, s33
	s_cmp_eq_u32 s89, s91
	s_cbranch_scc1 .Lref_e2
	s_or_b32 s57, s33, 0x2000
	v_cmp_ge_u32_e64 s[8:9], v216, s57
	v_cmp_ge_u32_e64 s[12:13], v217, s57
	s_bcnt1_i32_b64 s89, s[8:9]
	s_bcnt1_i32_b64 s61, s[12:13]
	s_add_u32 s89, s89, s61
	s_cmp_ge_u32 s89, s91
	s_cselect_b32 s33, s57, s33
	s_cmp_eq_u32 s89, s91
	s_cbranch_scc1 .Lref_e2
	s_or_b32 s57, s33, 0x1000
	v_cmp_ge_u32_e64 s[8:9], v216, s57
	v_cmp_ge_u32_e64 s[12:13], v217, s57
	s_bcnt1_i32_b64 s89, s[8:9]
	s_bcnt1_i32_b64 s61, s[12:13]
	s_add_u32 s89, s89, s61
	s_cmp_ge_u32 s89, s91
	s_cselect_b32 s33, s57, s33
	s_cmp_eq_u32 s89, s91
	s_cbranch_scc1 .Lref_e2
	s_or_b32 s57, s33, 0x800
	v_cmp_ge_u32_e64 s[8:9], v216, s57
	v_cmp_ge_u32_e64 s[12:13], v217, s57
	s_bcnt1_i32_b64 s89, s[8:9]
	s_bcnt1_i32_b64 s61, s[12:13]
	s_add_u32 s89, s89, s61
	s_cmp_ge_u32 s89, s91
	s_cselect_b32 s33, s57, s33
	s_cmp_eq_u32 s89, s91
	s_cbranch_scc1 .Lref_e2
	s_or_b32 s57, s33, 0x400
	v_cmp_ge_u32_e64 s[8:9], v216, s57
	v_cmp_ge_u32_e64 s[12:13], v217, s57
	s_bcnt1_i32_b64 s89, s[8:9]
	s_bcnt1_i32_b64 s61, s[12:13]
	s_add_u32 s89, s89, s61
	s_cmp_ge_u32 s89, s91
	s_cselect_b32 s33, s57, s33
	s_cmp_eq_u32 s89, s91
	s_cbranch_scc1 .Lref_e2
	s_or_b32 s57, s33, 0x200
	v_cmp_ge_u32_e64 s[8:9], v216, s57
	v_cmp_ge_u32_e64 s[12:13], v217, s57
	s_bcnt1_i32_b64 s89, s[8:9]
	s_bcnt1_i32_b64 s61, s[12:13]
	s_add_u32 s89, s89, s61
	s_cmp_ge_u32 s89, s91
	s_cselect_b32 s33, s57, s33
	s_cmp_eq_u32 s89, s91
	s_cbranch_scc1 .Lref_e2
	s_or_b32 s57, s33, 0x100
	v_cmp_ge_u32_e64 s[8:9], v216, s57
	v_cmp_ge_u32_e64 s[12:13], v217, s57
	s_bcnt1_i32_b64 s89, s[8:9]
	s_bcnt1_i32_b64 s61, s[12:13]
	s_add_u32 s89, s89, s61
	s_cmp_ge_u32 s89, s91
	s_cselect_b32 s33, s57, s33
	s_cmp_eq_u32 s89, s91
	s_cbranch_scc1 .Lref_e2
	s_or_b32 s57, s33, 0x80
	v_cmp_ge_u32_e64 s[8:9], v216, s57
	v_cmp_ge_u32_e64 s[12:13], v217, s57
	s_bcnt1_i32_b64 s89, s[8:9]
	s_bcnt1_i32_b64 s61, s[12:13]
	s_add_u32 s89, s89, s61
	s_cmp_ge_u32 s89, s91
	s_cselect_b32 s33, s57, s33
	s_cmp_eq_u32 s89, s91
	s_cbranch_scc1 .Lref_e2
	s_or_b32 s57, s33, 0x40
	v_cmp_ge_u32_e64 s[8:9], v216, s57
	v_cmp_ge_u32_e64 s[12:13], v217, s57
	s_bcnt1_i32_b64 s89, s[8:9]
	s_bcnt1_i32_b64 s61, s[12:13]
	s_add_u32 s89, s89, s61
	s_cmp_ge_u32 s89, s91
	s_cselect_b32 s33, s57, s33
	s_cmp_eq_u32 s89, s91
	s_cbranch_scc1 .Lref_e2
	s_or_b32 s57, s33, 0x20
	v_cmp_ge_u32_e64 s[8:9], v216, s57
	v_cmp_ge_u32_e64 s[12:13], v217, s57
	s_bcnt1_i32_b64 s89, s[8:9]
	s_bcnt1_i32_b64 s61, s[12:13]
	s_add_u32 s89, s89, s61
	s_cmp_ge_u32 s89, s91
	s_cselect_b32 s33, s57, s33
	s_cmp_eq_u32 s89, s91
	s_cbranch_scc1 .Lref_e2
	s_or_b32 s57, s33, 0x10
	v_cmp_ge_u32_e64 s[8:9], v216, s57
	v_cmp_ge_u32_e64 s[12:13], v217, s57
	s_bcnt1_i32_b64 s89, s[8:9]
	s_bcnt1_i32_b64 s61, s[12:13]
	s_add_u32 s89, s89, s61
	s_cmp_ge_u32 s89, s91
	s_cselect_b32 s33, s57, s33
	s_cmp_eq_u32 s89, s91
	s_cbranch_scc1 .Lref_e2
	s_or_b32 s57, s33, 0x8
	v_cmp_ge_u32_e64 s[8:9], v216, s57
	v_cmp_ge_u32_e64 s[12:13], v217, s57
	s_bcnt1_i32_b64 s89, s[8:9]
	s_bcnt1_i32_b64 s61, s[12:13]
	s_add_u32 s89, s89, s61
	s_cmp_ge_u32 s89, s91
	s_cselect_b32 s33, s57, s33
	s_cmp_eq_u32 s89, s91
	s_cbranch_scc1 .Lref_e2
	s_or_b32 s57, s33, 0x4
	v_cmp_ge_u32_e64 s[8:9], v216, s57
	v_cmp_ge_u32_e64 s[12:13], v217, s57
	s_bcnt1_i32_b64 s89, s[8:9]
	s_bcnt1_i32_b64 s61, s[12:13]
	s_add_u32 s89, s89, s61
	s_cmp_ge_u32 s89, s91
	s_cselect_b32 s33, s57, s33
	s_cmp_eq_u32 s89, s91
	s_cbranch_scc1 .Lref_e2
	s_or_b32 s57, s33, 0x2
	v_cmp_ge_u32_e64 s[8:9], v216, s57
	v_cmp_ge_u32_e64 s[12:13], v217, s57
	s_bcnt1_i32_b64 s89, s[8:9]
	s_bcnt1_i32_b64 s61, s[12:13]
	s_add_u32 s89, s89, s61
	s_cmp_ge_u32 s89, s91
	s_cselect_b32 s33, s57, s33
	s_cmp_eq_u32 s89, s91
	s_cbranch_scc1 .Lref_e2
	s_or_b32 s57, s33, 0x1
	v_cmp_ge_u32_e64 s[8:9], v216, s57
	v_cmp_ge_u32_e64 s[12:13], v217, s57
	s_bcnt1_i32_b64 s89, s[8:9]
	s_bcnt1_i32_b64 s61, s[12:13]
	s_add_u32 s89, s89, s61
	s_cmp_ge_u32 s89, s91
	s_cselect_b32 s33, s57, s33
	s_cmp_eq_u32 s89, s91
	s_cbranch_scc1 .Lref_e2
	v_cmp_gt_u32_e64 s[8:9], v216, s33
	v_cmp_gt_u32_e64 s[12:13], v217, s33
	s_bcnt1_i32_b64 s89, s[8:9]
	s_bcnt1_i32_b64 s61, s[12:13]
	s_add_u32 s89, s89, s61
	s_sub_u32 s91, s91, s89
	v_cmp_eq_u32_e64 s[8:9], v216, s33
	v_cmp_eq_u32_e64 s[12:13], v217, s33
	s_bcnt1_i32_b64 s89, s[8:9]
	s_bcnt1_i32_b64 s61, s[12:13]
	s_add_u32 s89, s89, s61
	s_add_u32 s57, s33, 1
	s_cmp_eq_u32 s91, s89
	s_cselect_b32 s57, s33, s57
	s_cselect_b32 s60, 1, 0
	s_branch .Lref_emit2

.Lref_emit2:
	v_cmp_ge_u32_e64 s[8:9], v216, s57
	v_cmp_ge_u32_e64 s[12:13], v217, s57
	s_nop 1
	v_mbcnt_lo_u32_b32 v241, s8, 0
	v_mbcnt_hi_u32_b32 v241, s9, v241
	v_add_u32_e32 v241, s90, v241
	v_and_b32_e32 v241, 0xff, v241
	v_lshl_add_u32 v241, v241, 1, v246
	s_mov_b64 exec, s[8:9]
	ds_write_b16 v241, v224
	s_mov_b64 exec, -1
	s_bcnt1_i32_b64 s61, s[8:9]
	s_add_u32 s90, s90, s61
	v_mbcnt_lo_u32_b32 v241, s12, 0
	v_mbcnt_hi_u32_b32 v241, s13, v241
	v_add_u32_e32 v241, s90, v241
	v_and_b32_e32 v241, 0xff, v241
	v_lshl_add_u32 v241, v241, 1, v246
	s_mov_b64 exec, s[12:13]
	ds_write_b16 v241, v225
	s_mov_b64 exec, -1
	s_bcnt1_i32_b64 s61, s[12:13]
	s_add_u32 s90, s90, s61
	s_mov_b32 s92, 0
	s_cmp_lg_u32 s60, 0
	s_cbranch_scc1 .Lref_fin
	v_cmp_eq_u32_e64 s[8:9], v216, s33
	v_cmp_eq_u32_e64 s[12:13], v217, s33
	s_nop 1
	v_mbcnt_lo_u32_b32 v241, s8, 0
	v_mbcnt_hi_u32_b32 v241, s9, v241
	v_add_u32_e32 v241, s92, v241
	v_lshl_add_u32 v241, v241, 1, v244
	s_mov_b64 exec, s[8:9]
	ds_write_b16 v241, v224
	s_mov_b64 exec, -1
	s_bcnt1_i32_b64 s61, s[8:9]
	s_add_u32 s92, s92, s61
	v_mbcnt_lo_u32_b32 v241, s12, 0
	v_mbcnt_hi_u32_b32 v241, s13, v241
	v_add_u32_e32 v241, s92, v241
	v_lshl_add_u32 v241, v241, 1, v244
	s_mov_b64 exec, s[12:13]
	ds_write_b16 v241, v225
	s_mov_b64 exec, -1
	s_bcnt1_i32_b64 s61, s[12:13]
	s_add_u32 s92, s92, s61
	s_branch .Lref_fin
.Lref_v1:
	ds_read_b32 v216, v238
	ds_read_u16 v224, v245
	v_cmp_gt_u32_e64 s[8:9], s93, v145
	s_waitcnt lgkmcnt(0)
	v_cndmask_b32_e64 v216, 0, v216, s[8:9]
	s_or_b32 s57, s33, 0x100000
	v_cmp_ge_u32_e64 s[8:9], v216, s57
	s_bcnt1_i32_b64 s89, s[8:9]
	s_cmp_ge_u32 s89, s91
	s_cselect_b32 s33, s57, s33
	s_cmp_eq_u32 s89, s91
	s_cbranch_scc1 .Lref_e1
	s_or_b32 s57, s33, 0x80000
	v_cmp_ge_u32_e64 s[8:9], v216, s57
	s_bcnt1_i32_b64 s89, s[8:9]
	s_cmp_ge_u32 s89, s91
	s_cselect_b32 s33, s57, s33
	s_cmp_eq_u32 s89, s91
	s_cbranch_scc1 .Lref_e1
	s_or_b32 s57, s33, 0x40000
	v_cmp_ge_u32_e64 s[8:9], v216, s57
	s_bcnt1_i32_b64 s89, s[8:9]
	s_cmp_ge_u32 s89, s91
	s_cselect_b32 s33, s57, s33
	s_cmp_eq_u32 s89, s91
	s_cbranch_scc1 .Lref_e1
	s_or_b32 s57, s33, 0x20000
	v_cmp_ge_u32_e64 s[8:9], v216, s57
	s_bcnt1_i32_b64 s89, s[8:9]
	s_cmp_ge_u32 s89, s91
	s_cselect_b32 s33, s57, s33
	s_cmp_eq_u32 s89, s91
	s_cbranch_scc1 .Lref_e1
	s_or_b32 s57, s33, 0x10000
	v_cmp_ge_u32_e64 s[8:9], v216, s57
	s_bcnt1_i32_b64 s89, s[8:9]
	s_cmp_ge_u32 s89, s91
	s_cselect_b32 s33, s57, s33
	s_cmp_eq_u32 s89, s91
	s_cbranch_scc1 .Lref_e1
	s_or_b32 s57, s33, 0x8000
	v_cmp_ge_u32_e64 s[8:9], v216, s57
	s_bcnt1_i32_b64 s89, s[8:9]
	s_cmp_ge_u32 s89, s91
	s_cselect_b32 s33, s57, s33
	s_cmp_eq_u32 s89, s91
	s_cbranch_scc1 .Lref_e1
	s_or_b32 s57, s33, 0x4000
	v_cmp_ge_u32_e64 s[8:9], v216, s57
	s_bcnt1_i32_b64 s89, s[8:9]
	s_cmp_ge_u32 s89, s91
	s_cselect_b32 s33, s57, s33
	s_cmp_eq_u32 s89, s91
	s_cbranch_scc1 .Lref_e1
	s_or_b32 s57, s33, 0x2000
	v_cmp_ge_u32_e64 s[8:9], v216, s57
	s_bcnt1_i32_b64 s89, s[8:9]
	s_cmp_ge_u32 s89, s91
	s_cselect_b32 s33, s57, s33
	s_cmp_eq_u32 s89, s91
	s_cbranch_scc1 .Lref_e1
	s_or_b32 s57, s33, 0x1000
	v_cmp_ge_u32_e64 s[8:9], v216, s57
	s_bcnt1_i32_b64 s89, s[8:9]
	s_cmp_ge_u32 s89, s91
	s_cselect_b32 s33, s57, s33
	s_cmp_eq_u32 s89, s91
	s_cbranch_scc1 .Lref_e1
	s_or_b32 s57, s33, 0x800
	v_cmp_ge_u32_e64 s[8:9], v216, s57
	s_bcnt1_i32_b64 s89, s[8:9]
	s_cmp_ge_u32 s89, s91
	s_cselect_b32 s33, s57, s33
	s_cmp_eq_u32 s89, s91
	s_cbranch_scc1 .Lref_e1
	s_or_b32 s57, s33, 0x400
	v_cmp_ge_u32_e64 s[8:9], v216, s57
	s_bcnt1_i32_b64 s89, s[8:9]
	s_cmp_ge_u32 s89, s91
	s_cselect_b32 s33, s57, s33
	s_cmp_eq_u32 s89, s91
	s_cbranch_scc1 .Lref_e1
	s_or_b32 s57, s33, 0x200
	v_cmp_ge_u32_e64 s[8:9], v216, s57
	s_bcnt1_i32_b64 s89, s[8:9]
	s_cmp_ge_u32 s89, s91
	s_cselect_b32 s33, s57, s33
	s_cmp_eq_u32 s89, s91
	s_cbranch_scc1 .Lref_e1
	s_or_b32 s57, s33, 0x100
	v_cmp_ge_u32_e64 s[8:9], v216, s57
	s_bcnt1_i32_b64 s89, s[8:9]
	s_cmp_ge_u32 s89, s91
	s_cselect_b32 s33, s57, s33
	s_cmp_eq_u32 s89, s91
	s_cbranch_scc1 .Lref_e1
	s_or_b32 s57, s33, 0x80
	v_cmp_ge_u32_e64 s[8:9], v216, s57
	s_bcnt1_i32_b64 s89, s[8:9]
	s_cmp_ge_u32 s89, s91
	s_cselect_b32 s33, s57, s33
	s_cmp_eq_u32 s89, s91
	s_cbranch_scc1 .Lref_e1
	s_or_b32 s57, s33, 0x40
	v_cmp_ge_u32_e64 s[8:9], v216, s57
	s_bcnt1_i32_b64 s89, s[8:9]
	s_cmp_ge_u32 s89, s91
	s_cselect_b32 s33, s57, s33
	s_cmp_eq_u32 s89, s91
	s_cbranch_scc1 .Lref_e1
	s_or_b32 s57, s33, 0x20
	v_cmp_ge_u32_e64 s[8:9], v216, s57
	s_bcnt1_i32_b64 s89, s[8:9]
	s_cmp_ge_u32 s89, s91
	s_cselect_b32 s33, s57, s33
	s_cmp_eq_u32 s89, s91
	s_cbranch_scc1 .Lref_e1
	s_or_b32 s57, s33, 0x10
	v_cmp_ge_u32_e64 s[8:9], v216, s57
	s_bcnt1_i32_b64 s89, s[8:9]
	s_cmp_ge_u32 s89, s91
	s_cselect_b32 s33, s57, s33
	s_cmp_eq_u32 s89, s91
	s_cbranch_scc1 .Lref_e1
	s_or_b32 s57, s33, 0x8
	v_cmp_ge_u32_e64 s[8:9], v216, s57
	s_bcnt1_i32_b64 s89, s[8:9]
	s_cmp_ge_u32 s89, s91
	s_cselect_b32 s33, s57, s33
	s_cmp_eq_u32 s89, s91
	s_cbranch_scc1 .Lref_e1
	s_or_b32 s57, s33, 0x4
	v_cmp_ge_u32_e64 s[8:9], v216, s57
	s_bcnt1_i32_b64 s89, s[8:9]
	s_cmp_ge_u32 s89, s91
	s_cselect_b32 s33, s57, s33
	s_cmp_eq_u32 s89, s91
	s_cbranch_scc1 .Lref_e1
	s_or_b32 s57, s33, 0x2
	v_cmp_ge_u32_e64 s[8:9], v216, s57
	s_bcnt1_i32_b64 s89, s[8:9]
	s_cmp_ge_u32 s89, s91
	s_cselect_b32 s33, s57, s33
	s_cmp_eq_u32 s89, s91
	s_cbranch_scc1 .Lref_e1
	s_or_b32 s57, s33, 0x1
	v_cmp_ge_u32_e64 s[8:9], v216, s57
	s_bcnt1_i32_b64 s89, s[8:9]
	s_cmp_ge_u32 s89, s91
	s_cselect_b32 s33, s57, s33
	s_cmp_eq_u32 s89, s91
	s_cbranch_scc1 .Lref_e1
	v_cmp_gt_u32_e64 s[8:9], v216, s33
	s_bcnt1_i32_b64 s89, s[8:9]
	s_sub_u32 s91, s91, s89
	v_cmp_eq_u32_e64 s[8:9], v216, s33
	s_bcnt1_i32_b64 s89, s[8:9]
	s_add_u32 s57, s33, 1
	s_cmp_eq_u32 s91, s89
	s_cselect_b32 s57, s33, s57
	s_cselect_b32 s60, 1, 0
	s_branch .Lref_emit1

.Lref_emit1:
	v_cmp_ge_u32_e64 s[8:9], v216, s57
	s_nop 1
	v_mbcnt_lo_u32_b32 v241, s8, 0
	v_mbcnt_hi_u32_b32 v241, s9, v241
	v_add_u32_e32 v241, s90, v241
	v_and_b32_e32 v241, 0xff, v241
	v_lshl_add_u32 v241, v241, 1, v246
	s_mov_b64 exec, s[8:9]
	ds_write_b16 v241, v224
	s_mov_b64 exec, -1
	s_bcnt1_i32_b64 s61, s[8:9]
	s_add_u32 s90, s90, s61
	s_mov_b32 s92, 0
	s_cmp_lg_u32 s60, 0
	s_cbranch_scc1 .Lref_fin
	v_cmp_eq_u32_e64 s[8:9], v216, s33
	s_nop 1
	v_mbcnt_lo_u32_b32 v241, s8, 0
	v_mbcnt_hi_u32_b32 v241, s9, v241
	v_add_u32_e32 v241, s92, v241
	v_lshl_add_u32 v241, v241, 1, v244
	s_mov_b64 exec, s[8:9]
	ds_write_b16 v241, v224
	s_mov_b64 exec, -1
	s_bcnt1_i32_b64 s61, s[8:9]
	s_add_u32 s92, s92, s61

.LBB0_975:
	s_or_b64 exec, exec, s[4:5]
	v_mov_b32_e32 v15, v202
	s_add_u32 s62, s28, 0x14000000
	s_waitcnt lgkmcnt(0)
	s_barrier
	s_nop 0
	s_nop 0
	s_nop 0
	s_nop 0
	s_nop 0
	s_nop 0
	s_nop 0
	s_nop 0
	s_nop 0
	s_nop 0
	s_nop 0
	s_nop 0
	s_nop 0
	s_nop 0
	s_nop 0
	s_nop 0
	s_nop 0
	s_nop 0
	s_nop 0
	s_nop 0
	s_nop 0
	s_nop 0
	s_addc_u32 s63, s29, 0
	v_readfirstlane_b32 s4, v15
	s_ashr_i32 s4, s4, 6
	s_and_b64 s[6:7], s[46:47], exec
	s_cselect_b32 s5, 8, 1
	v_cvt_f32_ubyte0_e32 v1, s5
	v_rcp_iflag_f32_e32 v1, v1
	s_add_i32 s8, s5, -1
	s_and_b64 s[6:7], s[46:47], exec
	s_cselect_b32 s24, 3, 0
	v_mul_f32_e32 v1, 0x4f7ffffe, v1
	v_cvt_u32_f32_e32 v1, v1
	s_sub_i32 s9, 0, s5
	s_abs_i32 s7, s30
	s_lshr_b32 s6, s2, s24
	v_readfirstlane_b32 s10, v1
	s_mul_i32 s9, s9, s10
	s_mul_hi_u32 s9, s10, s9
	s_add_i32 s10, s10, s9
	s_mul_hi_u32 s9, s7, s10
	s_mul_i32 s10, s9, s5
	s_sub_i32 s7, s7, s10
	s_lshl_b32 s6, s6, 3
	s_ashr_i32 s68, s30, 31
	s_add_i32 s10, s9, 1
	s_sub_i32 s11, s7, s5
	s_cmp_ge_u32 s7, s5
	s_cselect_b32 s9, s10, s9
	s_cselect_b32 s7, s11, s7
	s_add_i32 s10, s9, 1
	s_cmp_ge_u32 s7, s5
	s_cselect_b32 s7, s10, s9
	s_xor_b32 s7, s7, s68
	s_sub_i32 s7, s7, s68
	s_lshl_b32 s25, s7, 3
	s_abs_i32 s7, s25
	v_cvt_f32_u32_e32 v1, s7
	s_add_i32 s40, s4, s6
	s_sub_i32 s6, s25, s40
	s_and_b32 s41, s8, s2
	v_rcp_iflag_f32_e32 v1, v1
	s_add_i32 s8, s6, 0x1fff
	s_sub_i32 s6, 0xffffe001, s6
	s_xor_b32 s9, s8, s25
	v_mul_f32_e32 v1, 0x4f7ffffe, v1
	v_cvt_u32_f32_e32 v1, v1
	s_max_i32 s6, s8, s6
	s_sub_i32 s8, 0, s7
	s_ashr_i32 s9, s9, 31
	v_readfirstlane_b32 s10, v1
	s_mul_i32 s8, s8, s10
	s_mul_hi_u32 s8, s10, s8
	s_add_i32 s10, s10, s8
	s_mul_hi_u32 s8, s6, s10
	s_mul_i32 s10, s8, s7
	s_sub_i32 s6, s6, s10
	s_add_i32 s10, s8, 1
	s_sub_i32 s11, s6, s7
	s_cmp_ge_u32 s6, s7
	s_cselect_b32 s8, s10, s8
	s_cselect_b32 s6, s11, s6
	s_add_i32 s10, s8, 1
	s_cmp_ge_u32 s6, s7
	s_cselect_b32 s6, s10, s8
	s_sub_i32 s5, s5, s41
	s_xor_b32 s6, s6, s9
	s_add_i32 s5, s5, 15
	s_sub_i32 s42, s6, s9
	s_lshr_b32 s5, s5, s24
	s_mul_i32 s43, s42, s5
	s_cmp_lt_i32 s43, 1
	s_mov_b32 s9, 0
	s_cbranch_scc1 .LBB0_980
	s_lshl_b32 s5, s4, 14
	s_lshl_b32 s4, s4, 10
	s_add_i32 s47, s4, 0
	s_lshr_b32 s8, s41, 2
	s_add_i32 s46, s5, 0
	s_add_i32 s47, s47, 0x20000
	s_and_b32 s10, s41, 3
	s_lshl_b64 s[4:5], s[8:9], 13
	s_ashr_i32 s6, s40, 31
	s_add_u32 s4, s4, s40
	s_addc_u32 s5, s5, s6
	s_lshl_b64 s[6:7], s[4:5], 9
	v_and_b32_e32 v14, 63, v15
	s_add_u32 s6, s44, s6
	s_addc_u32 s7, s45, s7
	v_lshlrev_b32_e32 v42, 3, v14
	global_load_dwordx2 v[2:3], v42, s[6:7]
	v_and_b32_e32 v17, 15, v15
	v_bfe_u32 v4, v15, 4, 2
	v_bfe_u32 v6, v15, 2, 2
	v_and_b32_e32 v1, 7, v15
	v_lshlrev_b32_e32 v34, 3, v15
	v_mov_b32_e32 v7, 0x1000
	v_lshrrev_b32_e32 v9, 3, v15
	v_or_b32_e32 v12, 16, v17
	v_lshl_or_b32 v6, v4, 2, v6
	v_bfe_u32 v5, v15, 3, 1
	v_and_b32_e32 v10, 1, v15
	v_bitop3_b32 v13, v4, v1, 4 bitop3:0x36
	v_bitop3_b32 v16, v4, v15, 7 bitop3:0x78
	v_and_or_b32 v7, v34, 24, v7
	v_xor_b32_e32 v9, v9, v15
	v_mul_u32_u24_e32 v21, 0x40004, v14
	v_lshrrev_b32_e32 v22, 3, v12
	v_lshlrev_b32_e32 v24, 4, v6
	v_lshlrev_b32_e32 v6, 7, v6
	s_cmpk_gt_i32 s40, 0xff
	s_movk_i32 s6, 0x60
	v_lshlrev_b32_e32 v12, 7, v12
	v_xor_b32_e32 v23, v13, v5
	v_xor_b32_e32 v5, v16, v5
	v_and_or_b32 v9, v9, 6, v10
	v_or_b32_e32 v60, 0x10000, v21
	v_or_b32_e32 v61, 0x30002, v21
	v_xor_b32_e32 v10, v13, v22
	v_xor_b32_e32 v13, v16, v22
	v_or_b32_e32 v16, 0x800, v6
	v_or_b32_e32 v6, v6, v7
	s_cselect_b64 vcc, -1, 0
	v_lshlrev_b32_e32 v11, 6, v15
	s_waitcnt vmcnt(2)
	v_lshlrev_b32_e32 v52, 4, v9
	v_add_u32_e32 v9, s47, v42
	v_lshl_or_b32 v37, v10, 4, v12
	v_bitop3_b32 v10, v24, v16, s6 bitop3:0xce
	v_bitop3_b32 v39, v24, v6, s6 bitop3:0xce
	s_mul_hi_u32 s6, s4, 0x1200
	s_mulk_i32 s5, 0x1200
	s_mulk_i32 s4, 0x1200
	s_add_i32 s6, s6, s5
	v_mov_b32_e32 v43, 0
	s_add_u32 s4, s38, s4
	v_mov_b32_e32 v8, 0x60
	v_lshlrev_b32_e32 v19, 7, v17
	s_addc_u32 s5, s39, s6
	v_lshl_or_b32 v35, v23, 4, v19
	v_lshl_or_b32 v36, v5, 4, v19
	v_and_b32_e32 v5, 0x60, v24
	v_bitop3_b32 v19, v24, 64, v8 bitop3:0x6c
	v_bitop3_b32 v8, v24, 32, v8 bitop3:0x6c
	v_bfe_u32 v18, v15, 3, 3
	v_lshl_or_b32 v38, v13, 4, v12
	v_or_b32_e32 v12, v19, v16
	v_or_b32_e32 v13, v8, v16
	v_or_b32_e32 v41, v8, v6
	v_or_b32_e32 v8, v5, v16
	s_waitcnt vmcnt(1)
	v_or_b32_e32 v56, v6, v5
	v_lshlrev_b32_e32 v16, 3, v4
	v_and_b32_e32 v4, 48, v15
	v_mov_b32_e32 v5, v43
	v_lshlrev_b32_e32 v63, 6, v18
	v_bitop3_b32 v20, v18, v15, 7 bitop3:0x78
	v_or_b32_e32 v40, v19, v6
	v_add_u32_e32 v57, v10, v7
	v_add_u32_e32 v58, v12, v7
	v_add_u32_e32 v59, v13, v7
	v_add_u32_e32 v90, v8, v7
	v_add_u32_e32 v18, s47, v63
	v_mov_b32_e32 v19, v43
	v_lshlrev_b32_e32 v44, 4, v20
	v_mov_b32_e32 v45, v43
	s_mov_b32 m0, s46
	v_mov_b32_e32 v53, v43
	v_mov_b32_e32 v64, 9
	v_xor_b32_e32 v50, 16, v44
	v_mov_b32_e32 v51, v43
	v_xor_b32_e32 v48, 32, v44
	s_waitcnt vmcnt(0)
	v_cndmask_b32_e32 v2, v60, v2, vcc
	v_cndmask_b32_e32 v3, v61, v3, vcc
	ds_write_b64 v9, v[2:3]
	v_and_b32_e32 v2, 0xc0, v11
	v_lshlrev_b32_e32 v62, 1, v2
	v_lshl_or_b32 v2, s10, 9, v62
	v_mov_b32_e32 v3, v43
	v_lshl_add_u64 v[2:3], s[4:5], 0, v[2:3]
	s_lshl_b64 s[4:5], s[8:9], 22
	s_add_u32 s6, s80, s4
	v_lshl_add_u64 v[2:3], v[2:3], 0, v[4:5]
	s_addc_u32 s7, s81, s5
	global_load_dwordx4 v[10:13], v[2:3], off
	global_load_dwordx4 v[6:9], v[2:3], off offset:64
	s_waitcnt lgkmcnt(0)
	s_add_u32 s4, s37, s4
	ds_read_b128 v[30:33], v18
	ds_read_b128 v[22:25], v18 offset:16
	ds_read_b128 v[2:5], v18 offset:32
	ds_read_b128 v[26:29], v18 offset:48
	s_addc_u32 s5, s79, s5
	s_lshl_b32 s8, s10, 7
	s_add_u32 s4, s4, s8
	s_addc_u32 s5, s5, 0
	s_waitcnt lgkmcnt(3)
	v_lshlrev_b32_e32 v18, 9, v30
	s_add_u32 s6, s6, s8
	v_and_b32_e32 v18, 0x1fffe00, v18
	s_addc_u32 s7, s7, 0
	v_lshl_add_u64 v[20:21], s[4:5], 0, v[18:19]
	s_add_i32 s48, s46, 0x1000
	v_lshl_add_u64 v[20:21], v[20:21], 0, v[44:45]
	v_lshl_add_u64 v[18:19], s[6:7], 0, v[18:19]
	global_load_lds_dwordx4 v[20:21], off
	v_lshl_add_u64 v[18:19], v[18:19], 0, v[52:53]
	s_mov_b32 m0, s48
	s_add_i32 s49, s46, 0x400
	global_load_lds_dwordx4 v[18:19], off
	v_lshlrev_b32_sdwa v18, v64, v30 dst_sel:DWORD dst_unused:UNUSED_PAD src0_sel:DWORD src1_sel:WORD_1
	v_mov_b32_e32 v19, v43
	v_lshl_add_u64 v[20:21], s[4:5], 0, v[18:19]
	v_lshl_add_u64 v[20:21], v[20:21], 0, v[50:51]
	s_mov_b32 m0, s49
	v_lshl_add_u64 v[18:19], s[6:7], 0, v[18:19]
	s_add_i32 s50, s46, 0x1400
	global_load_lds_dwordx4 v[20:21], off
	v_lshl_add_u64 v[18:19], v[18:19], 0, v[52:53]
	s_mov_b32 m0, s50
	v_mov_b32_e32 v49, v43
	global_load_lds_dwordx4 v[18:19], off
	v_lshlrev_b32_e32 v18, 9, v31
	v_and_b32_e32 v18, 0x1fffe00, v18
	v_mov_b32_e32 v19, v43
	v_lshl_add_u64 v[20:21], s[4:5], 0, v[18:19]
	s_add_i32 s51, s46, 0x800
	v_lshl_add_u64 v[20:21], v[20:21], 0, v[48:49]
	s_mov_b32 m0, s51
	v_lshl_add_u64 v[18:19], s[6:7], 0, v[18:19]
	s_add_i32 s52, s46, 0x1800
	global_load_lds_dwordx4 v[20:21], off
	v_lshl_add_u64 v[18:19], v[18:19], 0, v[52:53]
	s_mov_b32 m0, s52
	v_xor_b32_e32 v46, 48, v44
	global_load_lds_dwordx4 v[18:19], off
	v_lshlrev_b32_sdwa v18, v64, v31 dst_sel:DWORD dst_unused:UNUSED_PAD src0_sel:DWORD src1_sel:WORD_1
	v_mov_b32_e32 v19, v43
	v_lshl_add_u64 v[20:21], s[4:5], 0, v[18:19]
	v_mov_b32_e32 v47, v43
	s_add_i32 s53, s46, 0xc00
	v_lshl_add_u64 v[20:21], v[20:21], 0, v[46:47]
	s_mov_b32 m0, s53
	v_lshl_add_u64 v[18:19], s[6:7], 0, v[18:19]
	s_add_i32 s54, s46, 0x1c00
	global_load_lds_dwordx4 v[20:21], off
	v_lshl_add_u64 v[18:19], v[18:19], 0, v[52:53]
	s_mov_b32 m0, s54
	v_cmp_gt_u32_e64 s[4:5], 4, v17
	global_load_lds_dwordx4 v[18:19], off
	v_and_b32_e32 v17, 0x80, v34
	v_bfe_u32 v15, v15, 5, 1
	v_or_b32_e32 v19, 32, v17
	v_or_b32_e32 v20, 64, v17
	v_or_b32_e32 v21, 0x60, v17
	v_or_b32_e32 v30, 6, v15
	v_or_b32_e32 v82, v17, v30
	v_or_b32_e32 v84, v19, v30
	v_or_b32_e32 v86, v20, v30
	v_or_b32_e32 v88, v21, v30
	v_or_b32_e32 v30, 10, v15
	v_or_b32_e32 v18, 2, v15
	v_or_b32_e32 v98, v17, v30
	v_or_b32_e32 v100, v19, v30
	v_or_b32_e32 v102, v20, v30
	v_or_b32_e32 v104, v21, v30
	v_or_b32_e32 v30, 14, v15
	v_or_b32_e32 v66, v17, v18
	v_or_b32_e32 v68, v19, v18
	v_or_b32_e32 v70, v20, v18
	v_or_b32_e32 v72, v21, v18
	v_or_b32_e32 v18, 4, v15
	v_or_b32_e32 v106, v17, v30
	v_or_b32_e32 v108, v19, v30
	v_or_b32_e32 v110, v20, v30
	v_or_b32_e32 v112, v21, v30
	v_or_b32_e32 v30, 18, v15
	v_or_b32_e32 v81, v17, v18
	v_or_b32_e32 v83, v19, v18
	v_or_b32_e32 v85, v20, v18
	v_or_b32_e32 v87, v21, v18
	v_or_b32_e32 v18, 8, v15
	v_or_b32_e32 v114, v17, v30
	v_or_b32_e32 v116, v19, v30
	v_or_b32_e32 v118, v20, v30
	v_or_b32_e32 v120, v21, v30
	v_or_b32_e32 v30, 22, v15
	v_lshl_add_u64 v[54:55], s[44:45], 0, v[42:43]
	v_or_b32_e32 v97, v17, v18
	v_or_b32_e32 v99, v19, v18
	v_or_b32_e32 v101, v20, v18
	v_or_b32_e32 v103, v21, v18
	v_or_b32_e32 v18, 12, v15
	v_or_b32_e32 v122, v17, v30
	v_or_b32_e32 v124, v19, v30
	v_or_b32_e32 v126, v20, v30
	v_or_b32_e32 v128, v21, v30
	v_or_b32_e32 v30, 26, v15
	s_abs_i32 s45, s42
	v_or_b32_e32 v105, v17, v18
	v_or_b32_e32 v107, v19, v18
	v_or_b32_e32 v109, v20, v18
	v_or_b32_e32 v111, v21, v18
	v_or_b32_e32 v18, 16, v15
	v_or_b32_e32 v130, v17, v30
	v_or_b32_e32 v132, v19, v30
	v_or_b32_e32 v134, v20, v30
	v_or_b32_e32 v136, v21, v30
	v_cvt_f32_u32_e32 v30, s45
	v_or_b32_e32 v113, v17, v18
	v_or_b32_e32 v115, v19, v18
	v_or_b32_e32 v117, v20, v18
	v_or_b32_e32 v119, v21, v18
	v_or_b32_e32 v18, 20, v15
	v_or_b32_e32 v121, v17, v18
	v_or_b32_e32 v123, v19, v18
	v_or_b32_e32 v125, v20, v18
	v_or_b32_e32 v127, v21, v18
	v_or_b32_e32 v18, 24, v15
	v_or_b32_e32 v65, v17, v15
	v_or_b32_e32 v67, v19, v15
	v_or_b32_e32 v69, v20, v15
	v_or_b32_e32 v71, v21, v15
	v_or_b32_e32 v129, v17, v18
	v_or_b32_e32 v131, v19, v18
	v_or_b32_e32 v133, v20, v18
	v_or_b32_e32 v135, v21, v18
	v_or_b32_e32 v18, 28, v15
	v_or_b32_e32 v15, 30, v15
	v_or_b32_e32 v137, v17, v18
	v_or_b32_e32 v138, v17, v15
	v_rcp_iflag_f32_e32 v17, v30
	s_sub_i32 s8, 0, s45
	s_add_i32 s44, s46, 0x2000
	v_lshlrev_b32_e32 v1, 2, v14
	v_mul_f32_e32 v17, 0x4f7ffffe, v17
	v_cvt_u32_f32_e32 v17, v17
	s_waitcnt vmcnt(0)
	v_cndmask_b32_e64 v9, 0, v9, s[4:5]
	v_cndmask_b32_e64 v8, 0, v8, s[4:5]
	v_cndmask_b32_e64 v7, 0, v7, s[4:5]
	v_readfirstlane_b32 s10, v17
	s_mul_i32 s8, s8, s10
	s_mul_hi_u32 s8, s10, s8
	v_cndmask_b32_e64 v6, 0, v6, s[4:5]
	v_cndmask_b32_e64 v13, 0, v13, s[4:5]
	v_cndmask_b32_e64 v12, 0, v12, s[4:5]
	v_cndmask_b32_e64 v11, 0, v11, s[4:5]
	v_cndmask_b32_e64 v10, 0, v10, s[4:5]
	v_cmp_gt_u32_e64 s[6:7], 16, v14
	v_add_u32_e32 v73, s46, v56
	v_add_u32_e32 v74, s46, v90
	v_add_u32_e32 v75, s46, v41
	v_add_u32_e32 v76, s46, v59
	v_add_u32_e32 v77, s46, v40
	v_add_u32_e32 v78, s46, v58
	v_add_u32_e32 v79, s46, v39
	v_add_u32_e32 v80, s46, v57
	v_add_u32_e32 v89, s44, v56
	v_add_u32_e32 v90, s44, v90
	v_add_u32_e32 v91, s44, v41
	v_add_u32_e32 v92, s44, v59
	v_add_u32_e32 v93, s44, v40
	v_add_u32_e32 v94, s44, v58
	v_add_u32_e32 v95, s44, v39
	v_add_u32_e32 v96, s44, v57
	v_or_b32_e32 v139, v19, v18
	v_or_b32_e32 v140, v19, v15
	v_or_b32_e32 v141, v20, v18
	v_or_b32_e32 v142, v20, v15
	v_or_b32_e32 v143, v21, v18
	v_or_b32_e32 v144, v21, v15
	s_ashr_i32 s55, s42, 31
	s_add_i32 s56, s10, s8
	s_sub_i32 s57, 0, s42
	v_lshlrev_b32_e32 v56, 1, v16
	s_add_i32 s58, s46, 0x3000
	s_add_i32 s59, s46, 0x2400
	s_add_i32 s60, s46, 0x3400
	s_add_i32 s61, s46, 0x2800
	s_add_i32 s64, s46, 0x3800
	s_add_i32 s65, s46, 0x2c00
	s_add_i32 s66, s46, 0x3c00
	v_add_u32_e32 v145, s46, v36
	v_add_u32_e32 v149, s46, v35
	v_add_u32_e32 v151, s46, v38
	v_add_u32_e32 v153, s46, v37
	v_lshlrev_b32_e32 v58, 1, v14
	s_movk_i32 s67, 0x7fff
	s_mov_b32 s69, 0
	s_mov_b32 s70, 0
	s_branch .LBB0_978
